# LN epilogue: batched stat-slot loads + FFN-down residual prefetch; ConvGlu taps prefetched before K-loop, drain removed
# baseline (speedup 1.0000x reference)
; #define PG8_STAGE(bufoff, gbase, voff) do { _Pragma("unroll") for (int _i = 0; _i < 2; ++_i) \
;         __builtin_amdgcn_global_load_lds((const unsigned*)((const char*)(gbase) + (voff)[_i]), (LAS unsigned*)(lds + (bufoff) + ldsw + _i * 8192), 16, 0, 0); } while (0)
; #define PG8_LDA(dst, b, h) do { _Pragma("unroll") for (int m = 0; m < 4; ++m) _Pragma("unroll") for (int k = 0; k < 2; ++k) dst[m][k] = *(const LAS bf16x8*)(lds + PG8_SA(b, h) + aoff + m * 2048 + k * 1024); } while (0)
; #define PG8_LDB(dst, b, h) do { _Pragma("unroll") for (int n = 0; n < 2; ++n) _Pragma("unroll") for (int k = 0; k < 2; ++k) dst[n][k] = *(const LAS bf16x8*)(lds + PG8_SB(b, h) + boff + n * 2048 + k * 1024); } while (0)
; #define PG8_WAIT_V(n) asm volatile("s_waitcnt vmcnt(" #n ")" ::: "memory")
; #define PG8_BAR __builtin_amdgcn_s_barrier()
; template <class Epi, class Sched, bool ALIGN_EPI = true>
; __device__ __forceinline__ void gemm_phase(LAS unsigned char* lds, const Gemm g, const Sched& S, const Epi& E) {
;     ...
;         for (int t = 0; t < nt; t += 2) {
;             const bool last = (t == nt - 2);
;             const char* a1 = cA + (size_t)(t + 1) * kstep;
;             const char* a2 = last ? nA : cA + (size_t)(t + 2) * kstep; const char* b2 = last ? nB : cB + (size_t)(t + 2) * kstep;
;             const char* a3 = a2 + kstep; const char* b3 = b2 + kstep;
;             PG8_LDB(B0, 0, 0); PG8_LDB(B1, 0, 1); PG8_SCHED; PG8_LDA(At, 0, 0); PG8_STAGE(PG8_SA(1, 1), a1 + hA, voffA);
;             PG8_WAIT_V(8); PG8_WAIT_L(0); PG8_BAR; PG8_MMA(0, 0, At, B0); PG8_MMA(0, 1, At, B1); PG8_BAR; PG8_SCHED;
;             PG8_LDA(At, 0, 1); PG8_STAGE(PG8_SB(0, 0), b2, voffB); PG8_STAGE(PG8_SB(0, 1), b2 + hB, voffB); PG8_STAGE(PG8_SA(0, 0), a2, voffA);
;             PG8_WAIT_V(8); PG8_WAIT_L(0); PG8_BAR; PG8_MMA(1, 0, At, B0); PG8_MMA(1, 1, At, B1); PG8_BAR; PG8_SCHED;
;             PG8_LDB(B0, 1, 0); PG8_LDB(B1, 1, 1); PG8_SCHED; PG8_LDA(At, 1, 0); PG8_STAGE(PG8_SA(0, 1), a2 + hA, voffA);
;             PG8_WAIT_V(8); PG8_WAIT_L(0); PG8_BAR; PG8_MMA(0, 0, At, B0); PG8_MMA(0, 1, At, B1); PG8_BAR; PG8_SCHED;
;             PG8_LDA(At, 1, 1); PG8_STAGE(PG8_SB(1, 0), b3, voffB); PG8_STAGE(PG8_SB(1, 1), b3 + hB, voffB); PG8_STAGE(PG8_SA(1, 0), a3, voffA);
;             PG8_WAIT_V(8); PG8_WAIT_L(0); PG8_BAR; PG8_MMA(1, 0, At, B0); PG8_MMA(1, 1, At, B1); PG8_BAR; PG8_SCHED;
.LBB0_77:
	s_add_u32 s26, s6, 0xfff80080
	s_addc_u32 s27, s7, -1
	s_add_i32 s30, 0, 0x10000
	s_cmp_eq_u32 s25, 28
	s_cselect_b32 s45, s15, s27
	s_cselect_b32 s44, s17, s26
	s_cselect_b32 s43, s13, s24
	s_cselect_b32 s42, s18, s19
	s_add_i32 s31, 0, 0x14000
	v_add_u32_e32 v144, s30, v166
	v_add_u32_e32 v156, s31, v166
	ds_read_b128 v[132:135], v144
	ds_read_b128 v[136:139], v144 offset:1024
	ds_read_b128 v[140:143], v144 offset:2048
	ds_read_b128 v[144:147], v144 offset:3072
	ds_read_b128 v[170:173], v156
	ds_read_b128 v[174:177], v156 offset:1024
	ds_read_b128 v[178:181], v156 offset:2048
	ds_read_b128 v[182:185], v156 offset:3072
	v_lshl_add_u64 v[156:157], s[6:7], 0, v[152:153]
	s_add_i32 m0, s60, 0xc000
	ds_read_b128 v[186:189], v168
	ds_read_b128 v[190:193], v168 offset:1024
	ds_read_b128 v[194:197], v168 offset:2048
	ds_read_b128 v[204:207], v168 offset:3072
	ds_read_b128 v[208:211], v168 offset:4096
	ds_read_b128 v[212:215], v168 offset:5120
	ds_read_b128 v[216:219], v168 offset:6144
	ds_read_b128 v[220:223], v168 offset:7168
	global_load_lds_dwordx4 v[156:157], off
	v_lshl_add_u64 v[156:157], s[6:7], 0, v[154:155]
	s_add_i32 m0, s60, 0xe000
	s_nop 0
	global_load_lds_dwordx4 v[156:157], off
	s_waitcnt vmcnt(8)
	s_waitcnt lgkmcnt(0)
	s_barrier
	s_setprio 1
	s_waitcnt lgkmcnt(0)
	v_mfma_f32_16x16x32_bf16 v[128:131], v[132:135], v[186:189], v[128:131]
	v_mfma_f32_16x16x32_bf16 v[124:127], v[140:143], v[186:189], v[124:127]
	v_mfma_f32_16x16x32_bf16 v[116:119], v[132:135], v[194:197], v[116:119]
	v_mfma_f32_16x16x32_bf16 v[112:115], v[140:143], v[194:197], v[112:115]
	v_mfma_f32_16x16x32_bf16 v[104:107], v[132:135], v[208:211], v[104:107]
	v_mfma_f32_16x16x32_bf16 v[96:99], v[140:143], v[208:211], v[96:99]
	v_mfma_f32_16x16x32_bf16 v[88:91], v[132:135], v[216:219], v[88:91]
	v_mfma_f32_16x16x32_bf16 v[80:83], v[140:143], v[216:219], v[80:83]
	v_mfma_f32_16x16x32_bf16 v[128:131], v[136:139], v[190:193], v[128:131]
	v_mfma_f32_16x16x32_bf16 v[124:127], v[144:147], v[190:193], v[124:127]
	v_mfma_f32_16x16x32_bf16 v[116:119], v[136:139], v[204:207], v[116:119]
	v_mfma_f32_16x16x32_bf16 v[112:115], v[144:147], v[204:207], v[112:115]
	v_mfma_f32_16x16x32_bf16 v[104:107], v[136:139], v[212:215], v[104:107]
	v_mfma_f32_16x16x32_bf16 v[96:99], v[144:147], v[212:215], v[96:99]
	v_mfma_f32_16x16x32_bf16 v[88:91], v[136:139], v[220:223], v[88:91]
	v_mfma_f32_16x16x32_bf16 v[80:83], v[144:147], v[220:223], v[80:83]
	s_setprio 0
	s_setprio 1
	v_mfma_f32_16x16x32_bf16 v[120:123], v[170:173], v[186:189], v[120:123]
	v_mfma_f32_16x16x32_bf16 v[108:111], v[178:181], v[186:189], v[108:111]
	v_mfma_f32_16x16x32_bf16 v[100:103], v[170:173], v[194:197], v[100:103]
	v_mfma_f32_16x16x32_bf16 v[92:95], v[178:181], v[194:197], v[92:95]
	v_mfma_f32_16x16x32_bf16 v[84:87], v[170:173], v[208:211], v[84:87]
	v_mfma_f32_16x16x32_bf16 v[76:79], v[178:181], v[208:211], v[76:79]
	v_mfma_f32_16x16x32_bf16 v[72:75], v[170:173], v[216:219], v[72:75]
	v_mfma_f32_16x16x32_bf16 v[68:71], v[178:181], v[216:219], v[68:71]
	v_mfma_f32_16x16x32_bf16 v[120:123], v[174:177], v[190:193], v[120:123]
	v_mfma_f32_16x16x32_bf16 v[108:111], v[182:185], v[190:193], v[108:111]
	v_mfma_f32_16x16x32_bf16 v[100:103], v[174:177], v[204:207], v[100:103]
	v_mfma_f32_16x16x32_bf16 v[92:95], v[182:185], v[204:207], v[92:95]
	v_mfma_f32_16x16x32_bf16 v[84:87], v[174:177], v[212:215], v[84:87]
	v_mfma_f32_16x16x32_bf16 v[76:79], v[182:185], v[212:215], v[76:79]
	v_mfma_f32_16x16x32_bf16 v[72:75], v[174:177], v[220:223], v[72:75]
	v_mfma_f32_16x16x32_bf16 v[68:71], v[182:185], v[220:223], v[68:71]
	s_setprio 0
	s_barrier
	s_add_i32 s26, s30, s59
	v_lshl_add_u64 v[156:157], s[42:43], 0, v[2:3]
	s_mov_b32 m0, s26
	ds_read_b128 v[186:189], v168 offset:16384
	ds_read_b128 v[190:193], v168 offset:17408
	ds_read_b128 v[194:197], v168 offset:18432
	ds_read_b128 v[204:207], v168 offset:19456
	ds_read_b128 v[208:211], v168 offset:20480
	ds_read_b128 v[212:215], v168 offset:21504
	ds_read_b128 v[216:219], v168 offset:22528
	ds_read_b128 v[220:223], v168 offset:23552
	global_load_lds_dwordx4 v[156:157], off
	s_add_i32 m0, s26, 0x2000
	s_add_u32 s26, s42, 0x80000
	v_lshl_add_u64 v[164:165], s[42:43], 0, v[0:1]
	s_addc_u32 s27, s43, 0
	s_add_i32 s30, s31, s59
	global_load_lds_dwordx4 v[164:165], off
	v_lshl_add_u64 v[224:225], s[26:27], 0, v[2:3]
	s_mov_b32 m0, s30
	v_lshl_add_u64 v[226:227], s[44:45], 0, v[148:149]
	global_load_lds_dwordx4 v[224:225], off
	v_lshl_add_u64 v[224:225], s[26:27], 0, v[0:1]
	s_add_i32 m0, s30, 0x2000
	s_nop 0
	global_load_lds_dwordx4 v[224:225], off
	v_lshl_add_u64 v[224:225], s[44:45], 0, v[150:151]
	s_mov_b32 m0, s60
	s_nop 0
	global_load_lds_dwordx4 v[224:225], off
	s_mov_b32 m0, s61
	s_nop 0
	global_load_lds_dwordx4 v[226:227], off
	s_waitcnt vmcnt(8)
	s_waitcnt lgkmcnt(0)
	s_barrier
; #define PG8_STAGE(bufoff, gbase, voff) do { _Pragma("unroll") for (int _i = 0; _i < 2; ++_i) \
;         __builtin_amdgcn_global_load_lds((const unsigned*)((const char*)(gbase) + (voff)[_i]), (LAS unsigned*)(lds + (bufoff) + ldsw + _i * 8192), 16, 0, 0); } while (0)
; #define PG8_LDA(dst, b, h) do { _Pragma("unroll") for (int m = 0; m < 4; ++m) _Pragma("unroll") for (int k = 0; k < 2; ++k) dst[m][k] = *(const LAS bf16x8*)(lds + PG8_SA(b, h) + aoff + m * 2048 + k * 1024); } while (0)
; #define PG8_LDB(dst, b, h) do { _Pragma("unroll") for (int n = 0; n < 2; ++n) _Pragma("unroll") for (int k = 0; k < 2; ++k) dst[n][k] = *(const LAS bf16x8*)(lds + PG8_SB(b, h) + boff + n * 2048 + k * 1024); } while (0)
; #define PG8_MMA(ai, bj, At, Bt) do { __builtin_amdgcn_s_setprio(1); _Pragma("unroll") for (int m = 0; m < 4; ++m) _Pragma("unroll") for (int n = 0; n < 2; ++n) _Pragma("unroll") for (int k = 0; k < 2; ++k) \
;         acc[ai][bj][m][n] = __builtin_amdgcn_mfma_f32_16x16x32_bf16(Bt[n][k], At[m][k], acc[ai][bj][m][n], 0, 0, 0); __builtin_amdgcn_s_setprio(0); } while (0)
; #define PG8_WAIT_V(n) asm volatile("s_waitcnt vmcnt(" #n ")" ::: "memory")
; #define PG8_WAIT_L(n) asm volatile("s_waitcnt lgkmcnt(" #n ")" ::: "memory")
; #define PG8_BAR __builtin_amdgcn_s_barrier()
; #define PG8_SCHED __builtin_amdgcn_sched_barrier(0)
; template <class Epi, class Sched, bool ALIGN_EPI = true>
; __device__ __forceinline__ void gemm_phase(LAS unsigned char* lds, const Gemm g, const Sched& S, const Epi& E) {
;     ...
;             PG8_LDB(B0, 0, 0); PG8_LDB(B1, 0, 1); PG8_SCHED; PG8_LDA(At, 0, 0); PG8_STAGE(PG8_SA(1, 1), a1 + hA, voffA);
;             PG8_WAIT_V(8); PG8_WAIT_L(0); PG8_BAR; PG8_MMA(0, 0, At, B0); PG8_MMA(0, 1, At, B1); PG8_BAR; PG8_SCHED;
;             PG8_LDA(At, 0, 1); PG8_STAGE(PG8_SB(0, 0), b2, voffB); PG8_STAGE(PG8_SB(0, 1), b2 + hB, voffB); PG8_STAGE(PG8_SA(0, 0), a2, voffA);
;             PG8_WAIT_V(8); PG8_WAIT_L(0); PG8_BAR; PG8_MMA(1, 0, At, B0); PG8_MMA(1, 1, At, B1); PG8_BAR; PG8_SCHED;
;             PG8_LDB(B0, 1, 0); PG8_LDB(B1, 1, 1); PG8_SCHED; PG8_LDA(At, 1, 0); PG8_STAGE(PG8_SA(0, 1), a2 + hA, voffA);
;             PG8_WAIT_V(8); PG8_WAIT_L(0); PG8_BAR; PG8_MMA(0, 0, At, B0); PG8_MMA(0, 1, At, B1); PG8_BAR; PG8_SCHED;
	s_setprio 1
	s_waitcnt lgkmcnt(0)
	v_mfma_f32_16x16x32_bf16 v[64:67], v[132:135], v[186:189], v[64:67]
	v_mfma_f32_16x16x32_bf16 v[60:63], v[140:143], v[186:189], v[60:63]
	v_mfma_f32_16x16x32_bf16 v[56:59], v[132:135], v[194:197], v[56:59]
	v_mfma_f32_16x16x32_bf16 v[48:51], v[140:143], v[194:197], v[48:51]
	v_mfma_f32_16x16x32_bf16 v[40:43], v[132:135], v[208:211], v[40:43]
	v_mfma_f32_16x16x32_bf16 v[32:35], v[140:143], v[208:211], v[32:35]
	v_mfma_f32_16x16x32_bf16 v[24:27], v[132:135], v[216:219], v[24:27]
	v_mfma_f32_16x16x32_bf16 v[16:19], v[140:143], v[216:219], v[16:19]
	v_mfma_f32_16x16x32_bf16 v[64:67], v[136:139], v[190:193], v[64:67]
	v_mfma_f32_16x16x32_bf16 v[60:63], v[144:147], v[190:193], v[60:63]
	v_mfma_f32_16x16x32_bf16 v[56:59], v[136:139], v[204:207], v[56:59]
	v_mfma_f32_16x16x32_bf16 v[48:51], v[144:147], v[204:207], v[48:51]
	v_mfma_f32_16x16x32_bf16 v[40:43], v[136:139], v[212:215], v[40:43]
	v_mfma_f32_16x16x32_bf16 v[32:35], v[144:147], v[212:215], v[32:35]
	v_mfma_f32_16x16x32_bf16 v[24:27], v[136:139], v[220:223], v[24:27]
	v_mfma_f32_16x16x32_bf16 v[16:19], v[144:147], v[220:223], v[16:19]
	s_setprio 0
	s_setprio 1
	v_mfma_f32_16x16x32_bf16 v[52:55], v[170:173], v[186:189], v[52:55]
	v_mfma_f32_16x16x32_bf16 v[44:47], v[178:181], v[186:189], v[44:47]
	v_mfma_f32_16x16x32_bf16 v[36:39], v[170:173], v[194:197], v[36:39]
	v_mfma_f32_16x16x32_bf16 v[28:31], v[178:181], v[194:197], v[28:31]
	v_mfma_f32_16x16x32_bf16 v[20:23], v[170:173], v[208:211], v[20:23]
	v_mfma_f32_16x16x32_bf16 v[12:15], v[178:181], v[208:211], v[12:15]
	v_mfma_f32_16x16x32_bf16 v[8:11], v[170:173], v[216:219], v[8:11]
	v_mfma_f32_16x16x32_bf16 v[4:7], v[178:181], v[216:219], v[4:7]
	v_mfma_f32_16x16x32_bf16 v[52:55], v[174:177], v[190:193], v[52:55]
	v_mfma_f32_16x16x32_bf16 v[44:47], v[182:185], v[190:193], v[44:47]
	v_mfma_f32_16x16x32_bf16 v[36:39], v[174:177], v[204:207], v[36:39]
	v_mfma_f32_16x16x32_bf16 v[28:31], v[182:185], v[204:207], v[28:31]
	v_mfma_f32_16x16x32_bf16 v[20:23], v[174:177], v[212:215], v[20:23]
	v_mfma_f32_16x16x32_bf16 v[12:15], v[182:185], v[212:215], v[12:15]
	v_mfma_f32_16x16x32_bf16 v[8:11], v[174:177], v[220:223], v[8:11]
	v_mfma_f32_16x16x32_bf16 v[4:7], v[182:185], v[220:223], v[4:7]
	s_setprio 0
	s_barrier
	s_add_i32 s30, 0, 0x18000
	s_add_i32 s31, 0, 0x1c000
	v_add_u32_e32 v144, s30, v166
	v_add_u32_e32 v160, s31, v166
	ds_read_b128 v[132:135], v144
	ds_read_b128 v[136:139], v144 offset:1024
	ds_read_b128 v[140:143], v144 offset:2048
	ds_read_b128 v[144:147], v144 offset:3072
	ds_read_b128 v[170:173], v160
	ds_read_b128 v[174:177], v160 offset:1024
	ds_read_b128 v[178:181], v160 offset:2048
	ds_read_b128 v[182:185], v160 offset:3072
	s_add_u32 s26, s44, 0x80000
	s_addc_u32 s27, s45, 0
	s_mov_b32 m0, s62
	v_lshl_add_u64 v[228:229], s[26:27], 0, v[150:151]
	ds_read_b128 v[186:189], v168 offset:32768
	ds_read_b128 v[190:193], v168 offset:33792
	ds_read_b128 v[194:197], v168 offset:34816
	ds_read_b128 v[204:207], v168 offset:35840
	ds_read_b128 v[208:211], v168 offset:36864
	ds_read_b128 v[212:215], v168 offset:37888
	ds_read_b128 v[216:219], v168 offset:38912
	ds_read_b128 v[220:223], v168 offset:39936
	global_load_lds_dwordx4 v[228:229], off
	v_lshl_add_u64 v[228:229], s[26:27], 0, v[148:149]
	s_mov_b32 m0, s63
	s_nop 0
	global_load_lds_dwordx4 v[228:229], off
	s_waitcnt vmcnt(8)
	s_waitcnt lgkmcnt(0)
	s_barrier
	s_setprio 1
	s_waitcnt lgkmcnt(0)
	v_mfma_f32_16x16x32_bf16 v[128:131], v[132:135], v[186:189], v[128:131]
	v_mfma_f32_16x16x32_bf16 v[124:127], v[140:143], v[186:189], v[124:127]
	v_mfma_f32_16x16x32_bf16 v[116:119], v[132:135], v[194:197], v[116:119]
	v_mfma_f32_16x16x32_bf16 v[112:115], v[140:143], v[194:197], v[112:115]
	v_mfma_f32_16x16x32_bf16 v[104:107], v[132:135], v[208:211], v[104:107]
	v_mfma_f32_16x16x32_bf16 v[96:99], v[140:143], v[208:211], v[96:99]
	v_mfma_f32_16x16x32_bf16 v[88:91], v[132:135], v[216:219], v[88:91]
	v_mfma_f32_16x16x32_bf16 v[80:83], v[140:143], v[216:219], v[80:83]
	v_mfma_f32_16x16x32_bf16 v[128:131], v[136:139], v[190:193], v[128:131]
	v_mfma_f32_16x16x32_bf16 v[124:127], v[144:147], v[190:193], v[124:127]
	v_mfma_f32_16x16x32_bf16 v[116:119], v[136:139], v[204:207], v[116:119]
	v_mfma_f32_16x16x32_bf16 v[112:115], v[144:147], v[204:207], v[112:115]
	v_mfma_f32_16x16x32_bf16 v[104:107], v[136:139], v[212:215], v[104:107]
	v_mfma_f32_16x16x32_bf16 v[96:99], v[144:147], v[212:215], v[96:99]
	v_mfma_f32_16x16x32_bf16 v[88:91], v[136:139], v[220:223], v[88:91]
	v_mfma_f32_16x16x32_bf16 v[80:83], v[144:147], v[220:223], v[80:83]
	s_setprio 0
	s_setprio 1
	v_mfma_f32_16x16x32_bf16 v[120:123], v[170:173], v[186:189], v[120:123]
	v_mfma_f32_16x16x32_bf16 v[108:111], v[178:181], v[186:189], v[108:111]
	v_mfma_f32_16x16x32_bf16 v[100:103], v[170:173], v[194:197], v[100:103]
	v_mfma_f32_16x16x32_bf16 v[92:95], v[178:181], v[194:197], v[92:95]
	v_mfma_f32_16x16x32_bf16 v[84:87], v[170:173], v[208:211], v[84:87]
	v_mfma_f32_16x16x32_bf16 v[76:79], v[178:181], v[208:211], v[76:79]
	v_mfma_f32_16x16x32_bf16 v[72:75], v[170:173], v[216:219], v[72:75]
	v_mfma_f32_16x16x32_bf16 v[68:71], v[178:181], v[216:219], v[68:71]
	v_mfma_f32_16x16x32_bf16 v[120:123], v[174:177], v[190:193], v[120:123]
	v_mfma_f32_16x16x32_bf16 v[108:111], v[182:185], v[190:193], v[108:111]
	v_mfma_f32_16x16x32_bf16 v[100:103], v[174:177], v[204:207], v[100:103]
	v_mfma_f32_16x16x32_bf16 v[92:95], v[182:185], v[204:207], v[92:95]
	v_mfma_f32_16x16x32_bf16 v[84:87], v[174:177], v[212:215], v[84:87]
	v_mfma_f32_16x16x32_bf16 v[76:79], v[182:185], v[212:215], v[76:79]
	v_mfma_f32_16x16x32_bf16 v[72:75], v[174:177], v[220:223], v[72:75]
	v_mfma_f32_16x16x32_bf16 v[68:71], v[182:185], v[220:223], v[68:71]
	s_setprio 0
	s_barrier
; #define PG8_STAGE(bufoff, gbase, voff) do { _Pragma("unroll") for (int _i = 0; _i < 2; ++_i) \
;         __builtin_amdgcn_global_load_lds((const unsigned*)((const char*)(gbase) + (voff)[_i]), (LAS unsigned*)(lds + (bufoff) + ldsw + _i * 8192), 16, 0, 0); } while (0)
; #define PG8_LDA(dst, b, h) do { _Pragma("unroll") for (int m = 0; m < 4; ++m) _Pragma("unroll") for (int k = 0; k < 2; ++k) dst[m][k] = *(const LAS bf16x8*)(lds + PG8_SA(b, h) + aoff + m * 2048 + k * 1024); } while (0)
; #define PG8_MMA(ai, bj, At, Bt) do { __builtin_amdgcn_s_setprio(1); _Pragma("unroll") for (int m = 0; m < 4; ++m) _Pragma("unroll") for (int n = 0; n < 2; ++n) _Pragma("unroll") for (int k = 0; k < 2; ++k) \
;         acc[ai][bj][m][n] = __builtin_amdgcn_mfma_f32_16x16x32_bf16(Bt[n][k], At[m][k], acc[ai][bj][m][n], 0, 0, 0); __builtin_amdgcn_s_setprio(0); } while (0)
; #define PG8_WAIT_V(n) asm volatile("s_waitcnt vmcnt(" #n ")" ::: "memory")
; #define PG8_WAIT_L(n) asm volatile("s_waitcnt lgkmcnt(" #n ")" ::: "memory")
; #define PG8_BAR __builtin_amdgcn_s_barrier()
; #define PG8_SCHED __builtin_amdgcn_sched_barrier(0)
; template <class Epi, class Sched, bool ALIGN_EPI = true>
; __device__ __forceinline__ void gemm_phase(LAS unsigned char* lds, const Gemm g, const Sched& S, const Epi& E) {
;     ...
;             PG8_LDA(At, 1, 1); PG8_STAGE(PG8_SB(1, 0), b3, voffB); PG8_STAGE(PG8_SB(1, 1), b3 + hB, voffB); PG8_STAGE(PG8_SA(1, 0), a3, voffA);
;             PG8_WAIT_V(8); PG8_WAIT_L(0); PG8_BAR; PG8_MMA(1, 0, At, B0); PG8_MMA(1, 1, At, B1); PG8_BAR; PG8_SCHED;
;         }
;         if constexpr (ALIGN_EPI) { if (wr == 0) PG8_BAR; }
	s_add_i32 s26, s30, s59
	v_lshl_add_u64 v[156:157], v[156:157], 0, s[86:87]
	s_mov_b32 m0, s26
	ds_read_b128 v[186:189], v168 offset:49152
	ds_read_b128 v[190:193], v168 offset:50176
	ds_read_b128 v[194:197], v168 offset:51200
	ds_read_b128 v[204:207], v168 offset:52224
	ds_read_b128 v[208:211], v168 offset:53248
	ds_read_b128 v[212:215], v168 offset:54272
	ds_read_b128 v[216:219], v168 offset:55296
	ds_read_b128 v[220:223], v168 offset:56320
	global_load_lds_dwordx4 v[156:157], off
	s_add_i32 m0, s26, 0x2000
	s_add_u32 s26, s42, 0x80080
	v_lshl_add_u64 v[156:157], v[164:165], 0, s[86:87]
	s_addc_u32 s27, s43, 0
	s_add_i32 s30, s31, s59
	global_load_lds_dwordx4 v[156:157], off
	v_lshl_add_u64 v[156:157], s[26:27], 0, v[2:3]
	s_mov_b32 m0, s30
	s_nop 0
	global_load_lds_dwordx4 v[156:157], off
	v_lshl_add_u64 v[156:157], s[26:27], 0, v[0:1]
	s_add_i32 m0, s30, 0x2000
	s_nop 0
	global_load_lds_dwordx4 v[156:157], off
	v_lshl_add_u64 v[156:157], v[224:225], 0, s[86:87]
	s_mov_b32 m0, s64
	s_nop 0
	global_load_lds_dwordx4 v[156:157], off
	v_lshl_add_u64 v[156:157], v[226:227], 0, s[86:87]
	s_mov_b32 m0, s65
	s_nop 0
	global_load_lds_dwordx4 v[156:157], off
	s_waitcnt vmcnt(8)
	s_waitcnt lgkmcnt(0)
	s_barrier
	s_setprio 1
	s_waitcnt lgkmcnt(0)
	v_mfma_f32_16x16x32_bf16 v[64:67], v[132:135], v[186:189], v[64:67]
	v_mfma_f32_16x16x32_bf16 v[60:63], v[140:143], v[186:189], v[60:63]
	v_mfma_f32_16x16x32_bf16 v[56:59], v[132:135], v[194:197], v[56:59]
	v_mfma_f32_16x16x32_bf16 v[48:51], v[140:143], v[194:197], v[48:51]
	v_mfma_f32_16x16x32_bf16 v[40:43], v[132:135], v[208:211], v[40:43]
	v_mfma_f32_16x16x32_bf16 v[32:35], v[140:143], v[208:211], v[32:35]
	v_mfma_f32_16x16x32_bf16 v[24:27], v[132:135], v[216:219], v[24:27]
	v_mfma_f32_16x16x32_bf16 v[16:19], v[140:143], v[216:219], v[16:19]
	v_mfma_f32_16x16x32_bf16 v[64:67], v[136:139], v[190:193], v[64:67]
	v_mfma_f32_16x16x32_bf16 v[60:63], v[144:147], v[190:193], v[60:63]
	v_mfma_f32_16x16x32_bf16 v[56:59], v[136:139], v[204:207], v[56:59]
	v_mfma_f32_16x16x32_bf16 v[48:51], v[144:147], v[204:207], v[48:51]
	v_mfma_f32_16x16x32_bf16 v[40:43], v[136:139], v[212:215], v[40:43]
	v_mfma_f32_16x16x32_bf16 v[32:35], v[144:147], v[212:215], v[32:35]
	v_mfma_f32_16x16x32_bf16 v[24:27], v[136:139], v[220:223], v[24:27]
	v_mfma_f32_16x16x32_bf16 v[16:19], v[144:147], v[220:223], v[16:19]
	s_setprio 0
	s_setprio 1
	v_mfma_f32_16x16x32_bf16 v[52:55], v[170:173], v[186:189], v[52:55]
	v_mfma_f32_16x16x32_bf16 v[44:47], v[178:181], v[186:189], v[44:47]
	v_mfma_f32_16x16x32_bf16 v[36:39], v[170:173], v[194:197], v[36:39]
	v_mfma_f32_16x16x32_bf16 v[28:31], v[178:181], v[194:197], v[28:31]
	v_mfma_f32_16x16x32_bf16 v[20:23], v[170:173], v[208:211], v[20:23]
	v_mfma_f32_16x16x32_bf16 v[12:15], v[178:181], v[208:211], v[12:15]
	v_mfma_f32_16x16x32_bf16 v[8:11], v[170:173], v[216:219], v[8:11]
	v_mfma_f32_16x16x32_bf16 v[4:7], v[178:181], v[216:219], v[4:7]
	v_mfma_f32_16x16x32_bf16 v[52:55], v[174:177], v[190:193], v[52:55]
	v_mfma_f32_16x16x32_bf16 v[44:47], v[182:185], v[190:193], v[44:47]
	v_mfma_f32_16x16x32_bf16 v[36:39], v[174:177], v[204:207], v[36:39]
	v_mfma_f32_16x16x32_bf16 v[28:31], v[182:185], v[204:207], v[28:31]
	v_mfma_f32_16x16x32_bf16 v[20:23], v[174:177], v[212:215], v[20:23]
	v_mfma_f32_16x16x32_bf16 v[12:15], v[182:185], v[212:215], v[12:15]
	v_mfma_f32_16x16x32_bf16 v[8:11], v[174:177], v[220:223], v[8:11]
	v_mfma_f32_16x16x32_bf16 v[4:7], v[182:185], v[220:223], v[4:7]
	s_setprio 0
	s_barrier
	s_add_i32 s25, s25, 2
	s_add_u32 s6, s6, 0x100
	s_addc_u32 s7, s7, 0
	s_add_u32 s19, s19, 0x100
	s_addc_u32 s24, s24, 0
	s_cmp_gt_u32 s25, 29
	s_cbranch_scc0 .LBB0_77
	s_and_b64 vcc, exec, s[10:11]
	s_cbranch_vccz .LBB0_80
	s_barrier

; #define PG8_STAGE(bufoff, gbase, voff) do { _Pragma("unroll") for (int _i = 0; _i < 2; ++_i) \
;         __builtin_amdgcn_global_load_lds((const unsigned*)((const char*)(gbase) + (voff)[_i]), (LAS unsigned*)(lds + (bufoff) + ldsw + _i * 8192), 16, 0, 0); } while (0)
; #define PG8_LDA(dst, b, h) do { _Pragma("unroll") for (int m = 0; m < 4; ++m) _Pragma("unroll") for (int k = 0; k < 2; ++k) dst[m][k] = *(const LAS bf16x8*)(lds + PG8_SA(b, h) + aoff + m * 2048 + k * 1024); } while (0)
; #define PG8_LDB(dst, b, h) do { _Pragma("unroll") for (int n = 0; n < 2; ++n) _Pragma("unroll") for (int k = 0; k < 2; ++k) dst[n][k] = *(const LAS bf16x8*)(lds + PG8_SB(b, h) + boff + n * 2048 + k * 1024); } while (0)
; #define PG8_WAIT_V(n) asm volatile("s_waitcnt vmcnt(" #n ")" ::: "memory")
; #define PG8_BAR __builtin_amdgcn_s_barrier()
; template <class Epi, class Sched, bool ALIGN_EPI = true>
; __device__ __forceinline__ void gemm_phase(LAS unsigned char* lds, const Gemm g, const Sched& S, const Epi& E) {
;     ...
;         for (int t = 0; t < nt; t += 2) {
;             const bool last = (t == nt - 2);
;             const char* a1 = cA + (size_t)(t + 1) * kstep;
;             const char* a2 = last ? nA : cA + (size_t)(t + 2) * kstep; const char* b2 = last ? nB : cB + (size_t)(t + 2) * kstep;
;             const char* a3 = a2 + kstep; const char* b3 = b2 + kstep;
;             PG8_LDB(B0, 0, 0); PG8_LDB(B1, 0, 1); PG8_SCHED; PG8_LDA(At, 0, 0); PG8_STAGE(PG8_SA(1, 1), a1 + hA, voffA);
;             PG8_WAIT_V(8); PG8_WAIT_L(0); PG8_BAR; PG8_MMA(0, 0, At, B0); PG8_MMA(0, 1, At, B1); PG8_BAR; PG8_SCHED;
;             PG8_LDA(At, 0, 1); PG8_STAGE(PG8_SB(0, 0), b2, voffB); PG8_STAGE(PG8_SB(0, 1), b2 + hB, voffB); PG8_STAGE(PG8_SA(0, 0), a2, voffA);
;             PG8_WAIT_V(8); PG8_WAIT_L(0); PG8_BAR; PG8_MMA(1, 0, At, B0); PG8_MMA(1, 1, At, B1); PG8_BAR; PG8_SCHED;
;             PG8_LDB(B0, 1, 0); PG8_LDB(B1, 1, 1); PG8_SCHED; PG8_LDA(At, 1, 0); PG8_STAGE(PG8_SA(0, 1), a2 + hA, voffA);
;             PG8_WAIT_V(8); PG8_WAIT_L(0); PG8_BAR; PG8_MMA(0, 0, At, B0); PG8_MMA(0, 1, At, B1); PG8_BAR; PG8_SCHED;
;             PG8_LDA(At, 1, 1); PG8_STAGE(PG8_SB(1, 0), b3, voffB); PG8_STAGE(PG8_SB(1, 1), b3 + hB, voffB); PG8_STAGE(PG8_SA(1, 0), a3, voffA);
;             PG8_WAIT_V(8); PG8_WAIT_L(0); PG8_BAR; PG8_MMA(1, 0, At, B0); PG8_MMA(1, 1, At, B1); PG8_BAR; PG8_SCHED;
.LBB0_218:
	s_add_u32 s27, s38, 0xfff80080
	s_addc_u32 s30, s39, -1
	s_add_i32 s31, 0, 0x10000
	s_cmp_eq_u32 s26, 28
	s_cselect_b32 s43, s11, s30
	s_cselect_b32 s42, s18, s27
	v_add_u32_e32 v156, s31, v145
	s_cselect_b32 s41, s9, s25
	s_cselect_b32 s40, s19, s24
	s_add_i32 s27, 0, 0x14000
	ds_read_b128 v[140:143], v156
	ds_read_b128 v[148:151], v156 offset:1024
	ds_read_b128 v[152:155], v156 offset:2048
	ds_read_b128 v[164:167], v156 offset:3072
	v_add_u32_e32 v156, s27, v145
	ds_read_b128 v[168:171], v156
	ds_read_b128 v[172:175], v156 offset:1024
	ds_read_b128 v[176:179], v156 offset:2048
	ds_read_b128 v[180:183], v156 offset:3072
	v_lshl_add_u64 v[156:157], s[38:39], 0, v[136:137]
	s_add_i32 m0, s58, 0xc000
	ds_read_b128 v[184:187], v147
	ds_read_b128 v[188:191], v147 offset:1024
	ds_read_b128 v[192:195], v147 offset:2048
	ds_read_b128 v[204:207], v147 offset:3072
	ds_read_b128 v[208:211], v147 offset:4096
	ds_read_b128 v[212:215], v147 offset:5120
	ds_read_b128 v[216:219], v147 offset:6144
	ds_read_b128 v[220:223], v147 offset:7168
	global_load_lds_dwordx4 v[156:157], off
	v_lshl_add_u64 v[156:157], s[38:39], 0, v[138:139]
	s_add_i32 m0, s58, 0xe000
	s_nop 0
	global_load_lds_dwordx4 v[156:157], off
	s_waitcnt vmcnt(8)
	s_waitcnt lgkmcnt(0)
	s_barrier
	s_setprio 1
	s_waitcnt lgkmcnt(0)
	v_mfma_f32_16x16x32_bf16 v[128:131], v[140:143], v[184:187], v[128:131]
	v_mfma_f32_16x16x32_bf16 v[124:127], v[152:155], v[184:187], v[124:127]
	v_mfma_f32_16x16x32_bf16 v[120:123], v[140:143], v[192:195], v[120:123]
	v_mfma_f32_16x16x32_bf16 v[112:115], v[152:155], v[192:195], v[112:115]
	v_mfma_f32_16x16x32_bf16 v[104:107], v[140:143], v[208:211], v[104:107]
	v_mfma_f32_16x16x32_bf16 v[96:99], v[152:155], v[208:211], v[96:99]
	v_mfma_f32_16x16x32_bf16 v[88:91], v[140:143], v[216:219], v[88:91]
	v_mfma_f32_16x16x32_bf16 v[80:83], v[152:155], v[216:219], v[80:83]
	v_mfma_f32_16x16x32_bf16 v[128:131], v[148:151], v[188:191], v[128:131]
	v_mfma_f32_16x16x32_bf16 v[124:127], v[164:167], v[188:191], v[124:127]
	v_mfma_f32_16x16x32_bf16 v[120:123], v[148:151], v[204:207], v[120:123]
	v_mfma_f32_16x16x32_bf16 v[112:115], v[164:167], v[204:207], v[112:115]
	v_mfma_f32_16x16x32_bf16 v[104:107], v[148:151], v[212:215], v[104:107]
	v_mfma_f32_16x16x32_bf16 v[96:99], v[164:167], v[212:215], v[96:99]
	v_mfma_f32_16x16x32_bf16 v[88:91], v[148:151], v[220:223], v[88:91]
	v_mfma_f32_16x16x32_bf16 v[80:83], v[164:167], v[220:223], v[80:83]
	s_setprio 0
	s_setprio 1
	v_mfma_f32_16x16x32_bf16 v[116:119], v[168:171], v[184:187], v[116:119]
	v_mfma_f32_16x16x32_bf16 v[108:111], v[176:179], v[184:187], v[108:111]
	v_mfma_f32_16x16x32_bf16 v[100:103], v[168:171], v[192:195], v[100:103]
	v_mfma_f32_16x16x32_bf16 v[92:95], v[176:179], v[192:195], v[92:95]
	v_mfma_f32_16x16x32_bf16 v[84:87], v[168:171], v[208:211], v[84:87]
	v_mfma_f32_16x16x32_bf16 v[76:79], v[176:179], v[208:211], v[76:79]
	v_mfma_f32_16x16x32_bf16 v[72:75], v[168:171], v[216:219], v[72:75]
	v_mfma_f32_16x16x32_bf16 v[68:71], v[176:179], v[216:219], v[68:71]
	v_mfma_f32_16x16x32_bf16 v[116:119], v[172:175], v[188:191], v[116:119]
	v_mfma_f32_16x16x32_bf16 v[108:111], v[180:183], v[188:191], v[108:111]
	v_mfma_f32_16x16x32_bf16 v[100:103], v[172:175], v[204:207], v[100:103]
	v_mfma_f32_16x16x32_bf16 v[92:95], v[180:183], v[204:207], v[92:95]
	v_mfma_f32_16x16x32_bf16 v[84:87], v[172:175], v[212:215], v[84:87]
	v_mfma_f32_16x16x32_bf16 v[76:79], v[180:183], v[212:215], v[76:79]
	v_mfma_f32_16x16x32_bf16 v[72:75], v[172:175], v[220:223], v[72:75]
	v_mfma_f32_16x16x32_bf16 v[68:71], v[180:183], v[220:223], v[68:71]
	s_setprio 0
	s_barrier
	s_add_i32 s30, s31, s53
	v_lshl_add_u64 v[156:157], s[40:41], 0, v[2:3]
	s_mov_b32 m0, s30
	ds_read_b128 v[184:187], v147 offset:16384
	ds_read_b128 v[188:191], v147 offset:17408
	ds_read_b128 v[192:195], v147 offset:18432
	ds_read_b128 v[204:207], v147 offset:19456
	ds_read_b128 v[208:211], v147 offset:20480
	ds_read_b128 v[212:215], v147 offset:21504
	ds_read_b128 v[216:219], v147 offset:22528
	ds_read_b128 v[220:223], v147 offset:23552
	global_load_lds_dwordx4 v[156:157], off
	s_add_i32 m0, s30, 0x2000
	s_add_u32 s30, s40, 0x80000
	v_lshl_add_u64 v[196:197], s[40:41], 0, v[0:1]
	s_addc_u32 s31, s41, 0
	s_add_i32 s27, s27, s53
	global_load_lds_dwordx4 v[196:197], off
	v_lshl_add_u64 v[224:225], s[30:31], 0, v[2:3]
	s_mov_b32 m0, s27
	v_lshl_add_u64 v[226:227], s[42:43], 0, v[132:133]
	global_load_lds_dwordx4 v[224:225], off
	v_lshl_add_u64 v[224:225], s[30:31], 0, v[0:1]
	s_add_i32 m0, s27, 0x2000
	s_nop 0
	global_load_lds_dwordx4 v[224:225], off
	v_lshl_add_u64 v[224:225], s[42:43], 0, v[134:135]
	s_mov_b32 m0, s58
	s_nop 0
	global_load_lds_dwordx4 v[224:225], off
	s_mov_b32 m0, s59
	s_nop 0
	global_load_lds_dwordx4 v[226:227], off
	s_waitcnt vmcnt(8)
	s_waitcnt lgkmcnt(0)
	s_barrier
; #define PG8_STAGE(bufoff, gbase, voff) do { _Pragma("unroll") for (int _i = 0; _i < 2; ++_i) \
;         __builtin_amdgcn_global_load_lds((const unsigned*)((const char*)(gbase) + (voff)[_i]), (LAS unsigned*)(lds + (bufoff) + ldsw + _i * 8192), 16, 0, 0); } while (0)
; #define PG8_LDA(dst, b, h) do { _Pragma("unroll") for (int m = 0; m < 4; ++m) _Pragma("unroll") for (int k = 0; k < 2; ++k) dst[m][k] = *(const LAS bf16x8*)(lds + PG8_SA(b, h) + aoff + m * 2048 + k * 1024); } while (0)
; #define PG8_LDB(dst, b, h) do { _Pragma("unroll") for (int n = 0; n < 2; ++n) _Pragma("unroll") for (int k = 0; k < 2; ++k) dst[n][k] = *(const LAS bf16x8*)(lds + PG8_SB(b, h) + boff + n * 2048 + k * 1024); } while (0)
; #define PG8_MMA(ai, bj, At, Bt) do { __builtin_amdgcn_s_setprio(1); _Pragma("unroll") for (int m = 0; m < 4; ++m) _Pragma("unroll") for (int n = 0; n < 2; ++n) _Pragma("unroll") for (int k = 0; k < 2; ++k) \
;         acc[ai][bj][m][n] = __builtin_amdgcn_mfma_f32_16x16x32_bf16(Bt[n][k], At[m][k], acc[ai][bj][m][n], 0, 0, 0); __builtin_amdgcn_s_setprio(0); } while (0)
; #define PG8_WAIT_V(n) asm volatile("s_waitcnt vmcnt(" #n ")" ::: "memory")
; #define PG8_WAIT_L(n) asm volatile("s_waitcnt lgkmcnt(" #n ")" ::: "memory")
; #define PG8_BAR __builtin_amdgcn_s_barrier()
; #define PG8_SCHED __builtin_amdgcn_sched_barrier(0)
; template <class Epi, class Sched, bool ALIGN_EPI = true>
; __device__ __forceinline__ void gemm_phase(LAS unsigned char* lds, const Gemm g, const Sched& S, const Epi& E) {
;     ...
;             PG8_LDB(B0, 0, 0); PG8_LDB(B1, 0, 1); PG8_SCHED; PG8_LDA(At, 0, 0); PG8_STAGE(PG8_SA(1, 1), a1 + hA, voffA);
;             PG8_WAIT_V(8); PG8_WAIT_L(0); PG8_BAR; PG8_MMA(0, 0, At, B0); PG8_MMA(0, 1, At, B1); PG8_BAR; PG8_SCHED;
;             PG8_LDA(At, 0, 1); PG8_STAGE(PG8_SB(0, 0), b2, voffB); PG8_STAGE(PG8_SB(0, 1), b2 + hB, voffB); PG8_STAGE(PG8_SA(0, 0), a2, voffA);
;             PG8_WAIT_V(8); PG8_WAIT_L(0); PG8_BAR; PG8_MMA(1, 0, At, B0); PG8_MMA(1, 1, At, B1); PG8_BAR; PG8_SCHED;
;             PG8_LDB(B0, 1, 0); PG8_LDB(B1, 1, 1); PG8_SCHED; PG8_LDA(At, 1, 0); PG8_STAGE(PG8_SA(0, 1), a2 + hA, voffA);
;             PG8_WAIT_V(8); PG8_WAIT_L(0); PG8_BAR; PG8_MMA(0, 0, At, B0); PG8_MMA(0, 1, At, B1); PG8_BAR; PG8_SCHED;
	s_setprio 1
	s_waitcnt lgkmcnt(0)
	v_mfma_f32_16x16x32_bf16 v[64:67], v[140:143], v[184:187], v[64:67]
	v_mfma_f32_16x16x32_bf16 v[60:63], v[152:155], v[184:187], v[60:63]
	v_mfma_f32_16x16x32_bf16 v[56:59], v[140:143], v[192:195], v[56:59]
	v_mfma_f32_16x16x32_bf16 v[48:51], v[152:155], v[192:195], v[48:51]
	v_mfma_f32_16x16x32_bf16 v[40:43], v[140:143], v[208:211], v[40:43]
	v_mfma_f32_16x16x32_bf16 v[32:35], v[152:155], v[208:211], v[32:35]
	v_mfma_f32_16x16x32_bf16 v[24:27], v[140:143], v[216:219], v[24:27]
	v_mfma_f32_16x16x32_bf16 v[16:19], v[152:155], v[216:219], v[16:19]
	v_mfma_f32_16x16x32_bf16 v[64:67], v[148:151], v[188:191], v[64:67]
	v_mfma_f32_16x16x32_bf16 v[60:63], v[164:167], v[188:191], v[60:63]
	v_mfma_f32_16x16x32_bf16 v[56:59], v[148:151], v[204:207], v[56:59]
	v_mfma_f32_16x16x32_bf16 v[48:51], v[164:167], v[204:207], v[48:51]
	v_mfma_f32_16x16x32_bf16 v[40:43], v[148:151], v[212:215], v[40:43]
	v_mfma_f32_16x16x32_bf16 v[32:35], v[164:167], v[212:215], v[32:35]
	v_mfma_f32_16x16x32_bf16 v[24:27], v[148:151], v[220:223], v[24:27]
	v_mfma_f32_16x16x32_bf16 v[16:19], v[164:167], v[220:223], v[16:19]
	s_setprio 0
	s_setprio 1
	v_mfma_f32_16x16x32_bf16 v[52:55], v[168:171], v[184:187], v[52:55]
	v_mfma_f32_16x16x32_bf16 v[44:47], v[176:179], v[184:187], v[44:47]
	v_mfma_f32_16x16x32_bf16 v[36:39], v[168:171], v[192:195], v[36:39]
	v_mfma_f32_16x16x32_bf16 v[28:31], v[176:179], v[192:195], v[28:31]
	v_mfma_f32_16x16x32_bf16 v[20:23], v[168:171], v[208:211], v[20:23]
	v_mfma_f32_16x16x32_bf16 v[12:15], v[176:179], v[208:211], v[12:15]
	v_mfma_f32_16x16x32_bf16 v[8:11], v[168:171], v[216:219], v[8:11]
	v_mfma_f32_16x16x32_bf16 v[4:7], v[176:179], v[216:219], v[4:7]
	v_mfma_f32_16x16x32_bf16 v[52:55], v[172:175], v[188:191], v[52:55]
	v_mfma_f32_16x16x32_bf16 v[44:47], v[180:183], v[188:191], v[44:47]
	v_mfma_f32_16x16x32_bf16 v[36:39], v[172:175], v[204:207], v[36:39]
	v_mfma_f32_16x16x32_bf16 v[28:31], v[180:183], v[204:207], v[28:31]
	v_mfma_f32_16x16x32_bf16 v[20:23], v[172:175], v[212:215], v[20:23]
	v_mfma_f32_16x16x32_bf16 v[12:15], v[180:183], v[212:215], v[12:15]
	v_mfma_f32_16x16x32_bf16 v[8:11], v[172:175], v[220:223], v[8:11]
	v_mfma_f32_16x16x32_bf16 v[4:7], v[180:183], v[220:223], v[4:7]
	s_setprio 0
	s_barrier
	s_add_i32 s27, 0, 0x18000
	v_add_u32_e32 v158, s27, v145
	s_add_i32 s65, 0, 0x1c000
	ds_read_b128 v[140:143], v158
	ds_read_b128 v[148:151], v158 offset:1024
	ds_read_b128 v[152:155], v158 offset:2048
	ds_read_b128 v[164:167], v158 offset:3072
	v_add_u32_e32 v158, s65, v145
	ds_read_b128 v[168:171], v158
	ds_read_b128 v[172:175], v158 offset:1024
	ds_read_b128 v[176:179], v158 offset:2048
	ds_read_b128 v[180:183], v158 offset:3072
	s_add_u32 s30, s42, 0x80000
	s_addc_u32 s31, s43, 0
	s_mov_b32 m0, s60
	v_lshl_add_u64 v[228:229], s[30:31], 0, v[134:135]
	ds_read_b128 v[184:187], v147 offset:32768
	ds_read_b128 v[188:191], v147 offset:33792
	ds_read_b128 v[192:195], v147 offset:34816
	ds_read_b128 v[204:207], v147 offset:35840
	ds_read_b128 v[208:211], v147 offset:36864
	ds_read_b128 v[212:215], v147 offset:37888
	ds_read_b128 v[216:219], v147 offset:38912
	ds_read_b128 v[220:223], v147 offset:39936
	global_load_lds_dwordx4 v[228:229], off
	v_lshl_add_u64 v[228:229], s[30:31], 0, v[132:133]
	s_mov_b32 m0, s61
	s_nop 0
	global_load_lds_dwordx4 v[228:229], off
	s_waitcnt vmcnt(8)
	s_waitcnt lgkmcnt(0)
	s_barrier
	s_setprio 1
	s_waitcnt lgkmcnt(0)
	v_mfma_f32_16x16x32_bf16 v[128:131], v[140:143], v[184:187], v[128:131]
	v_mfma_f32_16x16x32_bf16 v[124:127], v[152:155], v[184:187], v[124:127]
	v_mfma_f32_16x16x32_bf16 v[120:123], v[140:143], v[192:195], v[120:123]
	v_mfma_f32_16x16x32_bf16 v[112:115], v[152:155], v[192:195], v[112:115]
	v_mfma_f32_16x16x32_bf16 v[104:107], v[140:143], v[208:211], v[104:107]
	v_mfma_f32_16x16x32_bf16 v[96:99], v[152:155], v[208:211], v[96:99]
	v_mfma_f32_16x16x32_bf16 v[88:91], v[140:143], v[216:219], v[88:91]
	v_mfma_f32_16x16x32_bf16 v[80:83], v[152:155], v[216:219], v[80:83]
	v_mfma_f32_16x16x32_bf16 v[128:131], v[148:151], v[188:191], v[128:131]
	v_mfma_f32_16x16x32_bf16 v[124:127], v[164:167], v[188:191], v[124:127]
	v_mfma_f32_16x16x32_bf16 v[120:123], v[148:151], v[204:207], v[120:123]
	v_mfma_f32_16x16x32_bf16 v[112:115], v[164:167], v[204:207], v[112:115]
	v_mfma_f32_16x16x32_bf16 v[104:107], v[148:151], v[212:215], v[104:107]
	v_mfma_f32_16x16x32_bf16 v[96:99], v[164:167], v[212:215], v[96:99]
	v_mfma_f32_16x16x32_bf16 v[88:91], v[148:151], v[220:223], v[88:91]
	v_mfma_f32_16x16x32_bf16 v[80:83], v[164:167], v[220:223], v[80:83]
	s_setprio 0
	s_setprio 1
	v_mfma_f32_16x16x32_bf16 v[116:119], v[168:171], v[184:187], v[116:119]
	v_mfma_f32_16x16x32_bf16 v[108:111], v[176:179], v[184:187], v[108:111]
	v_mfma_f32_16x16x32_bf16 v[100:103], v[168:171], v[192:195], v[100:103]
	v_mfma_f32_16x16x32_bf16 v[92:95], v[176:179], v[192:195], v[92:95]
	v_mfma_f32_16x16x32_bf16 v[84:87], v[168:171], v[208:211], v[84:87]
	v_mfma_f32_16x16x32_bf16 v[76:79], v[176:179], v[208:211], v[76:79]
	v_mfma_f32_16x16x32_bf16 v[72:75], v[168:171], v[216:219], v[72:75]
	v_mfma_f32_16x16x32_bf16 v[68:71], v[176:179], v[216:219], v[68:71]
	v_mfma_f32_16x16x32_bf16 v[116:119], v[172:175], v[188:191], v[116:119]
	v_mfma_f32_16x16x32_bf16 v[108:111], v[180:183], v[188:191], v[108:111]
	v_mfma_f32_16x16x32_bf16 v[100:103], v[172:175], v[204:207], v[100:103]
	v_mfma_f32_16x16x32_bf16 v[92:95], v[180:183], v[204:207], v[92:95]
	v_mfma_f32_16x16x32_bf16 v[84:87], v[172:175], v[212:215], v[84:87]
	v_mfma_f32_16x16x32_bf16 v[76:79], v[180:183], v[212:215], v[76:79]
	v_mfma_f32_16x16x32_bf16 v[72:75], v[172:175], v[220:223], v[72:75]
	v_mfma_f32_16x16x32_bf16 v[68:71], v[180:183], v[220:223], v[68:71]
	s_setprio 0
	s_barrier
; #define PG8_STAGE(bufoff, gbase, voff) do { _Pragma("unroll") for (int _i = 0; _i < 2; ++_i) \
;         __builtin_amdgcn_global_load_lds((const unsigned*)((const char*)(gbase) + (voff)[_i]), (LAS unsigned*)(lds + (bufoff) + ldsw + _i * 8192), 16, 0, 0); } while (0)
; #define PG8_LDA(dst, b, h) do { _Pragma("unroll") for (int m = 0; m < 4; ++m) _Pragma("unroll") for (int k = 0; k < 2; ++k) dst[m][k] = *(const LAS bf16x8*)(lds + PG8_SA(b, h) + aoff + m * 2048 + k * 1024); } while (0)
; #define PG8_MMA(ai, bj, At, Bt) do { __builtin_amdgcn_s_setprio(1); _Pragma("unroll") for (int m = 0; m < 4; ++m) _Pragma("unroll") for (int n = 0; n < 2; ++n) _Pragma("unroll") for (int k = 0; k < 2; ++k) \
;         acc[ai][bj][m][n] = __builtin_amdgcn_mfma_f32_16x16x32_bf16(Bt[n][k], At[m][k], acc[ai][bj][m][n], 0, 0, 0); __builtin_amdgcn_s_setprio(0); } while (0)
; #define PG8_WAIT_V(n) asm volatile("s_waitcnt vmcnt(" #n ")" ::: "memory")
; #define PG8_WAIT_L(n) asm volatile("s_waitcnt lgkmcnt(" #n ")" ::: "memory")
; #define PG8_BAR __builtin_amdgcn_s_barrier()
; #define PG8_SCHED __builtin_amdgcn_sched_barrier(0)
; template <class Epi, class Sched, bool ALIGN_EPI = true>
; __device__ __forceinline__ void gemm_phase(LAS unsigned char* lds, const Gemm g, const Sched& S, const Epi& E) {
;     ...
;             PG8_LDA(At, 1, 1); PG8_STAGE(PG8_SB(1, 0), b3, voffB); PG8_STAGE(PG8_SB(1, 1), b3 + hB, voffB); PG8_STAGE(PG8_SA(1, 0), a3, voffA);
;             PG8_WAIT_V(8); PG8_WAIT_L(0); PG8_BAR; PG8_MMA(1, 0, At, B0); PG8_MMA(1, 1, At, B1); PG8_BAR; PG8_SCHED;
;         }
;         if constexpr (ALIGN_EPI) { if (wr == 0) PG8_BAR; }
	s_add_i32 s27, s27, s53
	v_lshl_add_u64 v[156:157], v[156:157], 0, s[86:87]
	s_mov_b32 m0, s27
	ds_read_b128 v[184:187], v147 offset:49152
	ds_read_b128 v[188:191], v147 offset:50176
	ds_read_b128 v[192:195], v147 offset:51200
	ds_read_b128 v[204:207], v147 offset:52224
	ds_read_b128 v[208:211], v147 offset:53248
	ds_read_b128 v[212:215], v147 offset:54272
	ds_read_b128 v[216:219], v147 offset:55296
	ds_read_b128 v[220:223], v147 offset:56320
	global_load_lds_dwordx4 v[156:157], off
	s_add_i32 m0, s27, 0x2000
	s_add_u32 s30, s40, 0x80080
	v_lshl_add_u64 v[156:157], v[196:197], 0, s[86:87]
	s_addc_u32 s31, s41, 0
	s_add_i32 s27, s65, s53
	global_load_lds_dwordx4 v[156:157], off
	v_lshl_add_u64 v[156:157], s[30:31], 0, v[2:3]
	s_mov_b32 m0, s27
	s_nop 0
	global_load_lds_dwordx4 v[156:157], off
	v_lshl_add_u64 v[156:157], s[30:31], 0, v[0:1]
	s_add_i32 m0, s27, 0x2000
	s_nop 0
	global_load_lds_dwordx4 v[156:157], off
	v_lshl_add_u64 v[156:157], v[224:225], 0, s[86:87]
	s_mov_b32 m0, s62
	s_nop 0
	global_load_lds_dwordx4 v[156:157], off
	v_lshl_add_u64 v[156:157], v[226:227], 0, s[86:87]
	s_mov_b32 m0, s63
	s_nop 0
	global_load_lds_dwordx4 v[156:157], off
	s_waitcnt vmcnt(8)
	s_waitcnt lgkmcnt(0)
	s_barrier
	s_setprio 1
	s_waitcnt lgkmcnt(0)
	v_mfma_f32_16x16x32_bf16 v[64:67], v[140:143], v[184:187], v[64:67]
	v_mfma_f32_16x16x32_bf16 v[60:63], v[152:155], v[184:187], v[60:63]
	v_mfma_f32_16x16x32_bf16 v[56:59], v[140:143], v[192:195], v[56:59]
	v_mfma_f32_16x16x32_bf16 v[48:51], v[152:155], v[192:195], v[48:51]
	v_mfma_f32_16x16x32_bf16 v[40:43], v[140:143], v[208:211], v[40:43]
	v_mfma_f32_16x16x32_bf16 v[32:35], v[152:155], v[208:211], v[32:35]
	v_mfma_f32_16x16x32_bf16 v[24:27], v[140:143], v[216:219], v[24:27]
	v_mfma_f32_16x16x32_bf16 v[16:19], v[152:155], v[216:219], v[16:19]
	v_mfma_f32_16x16x32_bf16 v[64:67], v[148:151], v[188:191], v[64:67]
	v_mfma_f32_16x16x32_bf16 v[60:63], v[164:167], v[188:191], v[60:63]
	v_mfma_f32_16x16x32_bf16 v[56:59], v[148:151], v[204:207], v[56:59]
	v_mfma_f32_16x16x32_bf16 v[48:51], v[164:167], v[204:207], v[48:51]
	v_mfma_f32_16x16x32_bf16 v[40:43], v[148:151], v[212:215], v[40:43]
	v_mfma_f32_16x16x32_bf16 v[32:35], v[164:167], v[212:215], v[32:35]
	v_mfma_f32_16x16x32_bf16 v[24:27], v[148:151], v[220:223], v[24:27]
	v_mfma_f32_16x16x32_bf16 v[16:19], v[164:167], v[220:223], v[16:19]
	s_setprio 0
	s_setprio 1
	v_mfma_f32_16x16x32_bf16 v[52:55], v[168:171], v[184:187], v[52:55]
	v_mfma_f32_16x16x32_bf16 v[44:47], v[176:179], v[184:187], v[44:47]
	v_mfma_f32_16x16x32_bf16 v[36:39], v[168:171], v[192:195], v[36:39]
	v_mfma_f32_16x16x32_bf16 v[28:31], v[176:179], v[192:195], v[28:31]
	v_mfma_f32_16x16x32_bf16 v[20:23], v[168:171], v[208:211], v[20:23]
	v_mfma_f32_16x16x32_bf16 v[12:15], v[176:179], v[208:211], v[12:15]
	v_mfma_f32_16x16x32_bf16 v[8:11], v[168:171], v[216:219], v[8:11]
	v_mfma_f32_16x16x32_bf16 v[4:7], v[176:179], v[216:219], v[4:7]
	v_mfma_f32_16x16x32_bf16 v[52:55], v[172:175], v[188:191], v[52:55]
	v_mfma_f32_16x16x32_bf16 v[44:47], v[180:183], v[188:191], v[44:47]
	v_mfma_f32_16x16x32_bf16 v[36:39], v[172:175], v[204:207], v[36:39]
	v_mfma_f32_16x16x32_bf16 v[28:31], v[180:183], v[204:207], v[28:31]
	v_mfma_f32_16x16x32_bf16 v[20:23], v[172:175], v[212:215], v[20:23]
	v_mfma_f32_16x16x32_bf16 v[12:15], v[180:183], v[212:215], v[12:15]
	v_mfma_f32_16x16x32_bf16 v[8:11], v[172:175], v[220:223], v[8:11]
	v_mfma_f32_16x16x32_bf16 v[4:7], v[180:183], v[220:223], v[4:7]
	s_setprio 0
	s_barrier
	s_add_i32 s26, s26, 2
	s_add_u32 s38, s38, 0x100
	s_addc_u32 s39, s39, 0
	s_add_u32 s24, s24, 0x100
	s_addc_u32 s25, s25, 0
	s_cmp_gt_u32 s26, 29
	s_cbranch_scc0 .LBB0_218
	s_and_b64 vcc, exec, s[6:7]
	s_cbranch_vccz .LBB0_221
	s_barrier

; #define PG8_STAGE(bufoff, gbase, voff) do { _Pragma("unroll") for (int _i = 0; _i < 2; ++_i) \
;         __builtin_amdgcn_global_load_lds((const unsigned*)((const char*)(gbase) + (voff)[_i]), (LAS unsigned*)(lds + (bufoff) + ldsw + _i * 8192), 16, 0, 0); } while (0)
; #define PG8_LDA(dst, b, h) do { _Pragma("unroll") for (int m = 0; m < 4; ++m) _Pragma("unroll") for (int k = 0; k < 2; ++k) dst[m][k] = *(const LAS bf16x8*)(lds + PG8_SA(b, h) + aoff + m * 2048 + k * 1024); } while (0)
; #define PG8_LDB(dst, b, h) do { _Pragma("unroll") for (int n = 0; n < 2; ++n) _Pragma("unroll") for (int k = 0; k < 2; ++k) dst[n][k] = *(const LAS bf16x8*)(lds + PG8_SB(b, h) + boff + n * 2048 + k * 1024); } while (0)
; #define PG8_WAIT_V(n) asm volatile("s_waitcnt vmcnt(" #n ")" ::: "memory")
; #define PG8_BAR __builtin_amdgcn_s_barrier()
; template <class Epi, class Sched, bool ALIGN_EPI = true>
; __device__ __forceinline__ void gemm_phase(LAS unsigned char* lds, const Gemm g, const Sched& S, const Epi& E) {
;     ...
;         for (int t = 0; t < nt; t += 2) {
;             const bool last = (t == nt - 2);
;             const char* a1 = cA + (size_t)(t + 1) * kstep;
;             const char* a2 = last ? nA : cA + (size_t)(t + 2) * kstep; const char* b2 = last ? nB : cB + (size_t)(t + 2) * kstep;
;             const char* a3 = a2 + kstep; const char* b3 = b2 + kstep;
;             PG8_LDB(B0, 0, 0); PG8_LDB(B1, 0, 1); PG8_SCHED; PG8_LDA(At, 0, 0); PG8_STAGE(PG8_SA(1, 1), a1 + hA, voffA);
;             PG8_WAIT_V(8); PG8_WAIT_L(0); PG8_BAR; PG8_MMA(0, 0, At, B0); PG8_MMA(0, 1, At, B1); PG8_BAR; PG8_SCHED;
;             PG8_LDA(At, 0, 1); PG8_STAGE(PG8_SB(0, 0), b2, voffB); PG8_STAGE(PG8_SB(0, 1), b2 + hB, voffB); PG8_STAGE(PG8_SA(0, 0), a2, voffA);
;             PG8_WAIT_V(8); PG8_WAIT_L(0); PG8_BAR; PG8_MMA(1, 0, At, B0); PG8_MMA(1, 1, At, B1); PG8_BAR; PG8_SCHED;
;             PG8_LDB(B0, 1, 0); PG8_LDB(B1, 1, 1); PG8_SCHED; PG8_LDA(At, 1, 0); PG8_STAGE(PG8_SA(0, 1), a2 + hA, voffA);
;             PG8_WAIT_V(8); PG8_WAIT_L(0); PG8_BAR; PG8_MMA(0, 0, At, B0); PG8_MMA(0, 1, At, B1); PG8_BAR; PG8_SCHED;
;             PG8_LDA(At, 1, 1); PG8_STAGE(PG8_SB(1, 0), b3, voffB); PG8_STAGE(PG8_SB(1, 1), b3 + hB, voffB); PG8_STAGE(PG8_SA(1, 0), a3, voffA);
;             PG8_WAIT_V(8); PG8_WAIT_L(0); PG8_BAR; PG8_MMA(1, 0, At, B0); PG8_MMA(1, 1, At, B1); PG8_BAR; PG8_SCHED;
.LBB0_667:
	s_add_u32 vcc_lo, s10, 0x100
	s_addc_u32 vcc_hi, s11, 0
	s_add_u32 s25, s18, s10
	s_addc_u32 s26, s19, s11
	s_add_i32 s27, 0, 0x10000
	s_cmp_eq_u32 s24, 28
	s_cselect_b32 s65, s16, s26
	s_cselect_b32 s26, 0, vcc_lo
	s_cselect_b32 s64, s17, s25
	s_cselect_b32 s25, 0, vcc_hi
	s_add_u32 s62, s14, s26
	v_add_u32_e32 v160, s27, v186
	s_addc_u32 s63, s15, s25
	s_add_i32 s25, 0, 0x14000
	ds_read_b128 v[136:139], v160
	ds_read_b128 v[140:143], v160 offset:1024
	ds_read_b128 v[144:147], v160 offset:2048
	ds_read_b128 v[170:173], v160 offset:3072
	v_add_u32_e32 v160, s25, v186
	ds_read_b128 v[174:177], v160
	ds_read_b128 v[178:181], v160 offset:1024
	ds_read_b128 v[182:185], v160 offset:2048
	ds_read_b128 v[208:211], v160 offset:3072
	v_lshl_add_u64 v[244:245], v[132:133], 0, s[10:11]
	s_add_i32 m0, s53, 0xc000
	ds_read_b128 v[212:215], v197
	ds_read_b128 v[216:219], v197 offset:1024
	ds_read_b128 v[220:223], v197 offset:2048
	ds_read_b128 v[224:227], v197 offset:3072
	ds_read_b128 v[228:231], v197 offset:4096
	ds_read_b128 v[232:235], v197 offset:5120
	ds_read_b128 v[236:239], v197 offset:6144
	ds_read_b128 v[240:243], v197 offset:7168
	global_load_lds_dwordx4 v[244:245], off
	v_lshl_add_u64 v[244:245], v[134:135], 0, s[10:11]
	s_add_i32 m0, s53, 0xe000
	s_nop 0
	global_load_lds_dwordx4 v[244:245], off
	s_waitcnt vmcnt(8)
	s_waitcnt lgkmcnt(0)
	s_barrier
	s_setprio 1
	s_waitcnt lgkmcnt(0)
	v_mfma_f32_16x16x32_bf16 v[36:39], v[136:139], v[212:215], v[36:39]
	v_mfma_f32_16x16x32_bf16 v[40:43], v[144:147], v[212:215], v[40:43]
	v_mfma_f32_16x16x32_bf16 v[68:71], v[136:139], v[220:223], v[68:71]
	v_mfma_f32_16x16x32_bf16 v[72:75], v[144:147], v[220:223], v[72:75]
	v_mfma_f32_16x16x32_bf16 v[100:103], v[136:139], v[228:231], v[100:103]
	v_mfma_f32_16x16x32_bf16 v[104:107], v[144:147], v[228:231], v[104:107]
	v_mfma_f32_16x16x32_bf16 v[128:131], v[136:139], v[236:239], v[128:131]
	v_mfma_f32_16x16x32_bf16 v[124:127], v[144:147], v[236:239], v[124:127]
	v_mfma_f32_16x16x32_bf16 v[36:39], v[140:143], v[216:219], v[36:39]
	v_mfma_f32_16x16x32_bf16 v[40:43], v[170:173], v[216:219], v[40:43]
	v_mfma_f32_16x16x32_bf16 v[68:71], v[140:143], v[224:227], v[68:71]
	v_mfma_f32_16x16x32_bf16 v[72:75], v[170:173], v[224:227], v[72:75]
	v_mfma_f32_16x16x32_bf16 v[100:103], v[140:143], v[232:235], v[100:103]
	v_mfma_f32_16x16x32_bf16 v[104:107], v[170:173], v[232:235], v[104:107]
	v_mfma_f32_16x16x32_bf16 v[128:131], v[140:143], v[240:243], v[128:131]
	v_mfma_f32_16x16x32_bf16 v[124:127], v[170:173], v[240:243], v[124:127]
	s_setprio 0
	s_setprio 1
	v_mfma_f32_16x16x32_bf16 v[8:11], v[174:177], v[212:215], v[8:11]
	v_mfma_f32_16x16x32_bf16 v[4:7], v[182:185], v[212:215], v[4:7]
	v_mfma_f32_16x16x32_bf16 v[32:35], v[174:177], v[220:223], v[32:35]
	v_mfma_f32_16x16x32_bf16 v[28:31], v[182:185], v[220:223], v[28:31]
	v_mfma_f32_16x16x32_bf16 v[56:59], v[174:177], v[228:231], v[56:59]
	v_mfma_f32_16x16x32_bf16 v[52:55], v[182:185], v[228:231], v[52:55]
	v_mfma_f32_16x16x32_bf16 v[80:83], v[174:177], v[236:239], v[80:83]
	v_mfma_f32_16x16x32_bf16 v[76:79], v[182:185], v[236:239], v[76:79]
	v_mfma_f32_16x16x32_bf16 v[8:11], v[178:181], v[216:219], v[8:11]
	v_mfma_f32_16x16x32_bf16 v[4:7], v[208:211], v[216:219], v[4:7]
	v_mfma_f32_16x16x32_bf16 v[32:35], v[178:181], v[224:227], v[32:35]
	v_mfma_f32_16x16x32_bf16 v[28:31], v[208:211], v[224:227], v[28:31]
	v_mfma_f32_16x16x32_bf16 v[56:59], v[178:181], v[232:235], v[56:59]
	v_mfma_f32_16x16x32_bf16 v[52:55], v[208:211], v[232:235], v[52:55]
	v_mfma_f32_16x16x32_bf16 v[80:83], v[178:181], v[240:243], v[80:83]
	v_mfma_f32_16x16x32_bf16 v[76:79], v[208:211], v[240:243], v[76:79]
	s_setprio 0
	s_barrier
	s_add_i32 s10, s27, s67
	v_lshl_add_u64 v[244:245], s[62:63], 0, v[2:3]
	s_mov_b32 m0, s10
	ds_read_b128 v[212:215], v197 offset:16384
	ds_read_b128 v[216:219], v197 offset:17408
	ds_read_b128 v[220:223], v197 offset:18432
	ds_read_b128 v[224:227], v197 offset:19456
	ds_read_b128 v[228:231], v197 offset:20480
	ds_read_b128 v[232:235], v197 offset:21504
	ds_read_b128 v[236:239], v197 offset:22528
	ds_read_b128 v[240:243], v197 offset:23552
	global_load_lds_dwordx4 v[244:245], off
	s_add_i32 m0, s10, 0x2000
	s_add_u32 s10, s62, 0x80000
	v_lshl_add_u64 v[246:247], s[62:63], 0, v[150:151]
	s_addc_u32 s11, s63, 0
	s_add_i32 s25, s25, s67
	global_load_lds_dwordx4 v[246:247], off
	v_lshl_add_u64 v[248:249], s[10:11], 0, v[2:3]
	s_mov_b32 m0, s25
	v_lshl_add_u64 v[160:161], s[64:65], 0, v[148:149]
	global_load_lds_dwordx4 v[248:249], off
	v_lshl_add_u64 v[248:249], s[10:11], 0, v[150:151]
	s_add_i32 m0, s25, 0x2000
	s_nop 0
	global_load_lds_dwordx4 v[248:249], off
	v_lshl_add_u64 v[248:249], s[64:65], 0, v[0:1]
	s_mov_b32 m0, s53
	s_nop 0
	global_load_lds_dwordx4 v[248:249], off
	s_mov_b32 m0, s66
	s_nop 0
	global_load_lds_dwordx4 v[160:161], off
	s_waitcnt vmcnt(8)
	s_waitcnt lgkmcnt(0)
	s_barrier
; #define PG8_STAGE(bufoff, gbase, voff) do { _Pragma("unroll") for (int _i = 0; _i < 2; ++_i) \
;         __builtin_amdgcn_global_load_lds((const unsigned*)((const char*)(gbase) + (voff)[_i]), (LAS unsigned*)(lds + (bufoff) + ldsw + _i * 8192), 16, 0, 0); } while (0)
; #define PG8_LDA(dst, b, h) do { _Pragma("unroll") for (int m = 0; m < 4; ++m) _Pragma("unroll") for (int k = 0; k < 2; ++k) dst[m][k] = *(const LAS bf16x8*)(lds + PG8_SA(b, h) + aoff + m * 2048 + k * 1024); } while (0)
; #define PG8_LDB(dst, b, h) do { _Pragma("unroll") for (int n = 0; n < 2; ++n) _Pragma("unroll") for (int k = 0; k < 2; ++k) dst[n][k] = *(const LAS bf16x8*)(lds + PG8_SB(b, h) + boff + n * 2048 + k * 1024); } while (0)
; #define PG8_MMA(ai, bj, At, Bt) do { __builtin_amdgcn_s_setprio(1); _Pragma("unroll") for (int m = 0; m < 4; ++m) _Pragma("unroll") for (int n = 0; n < 2; ++n) _Pragma("unroll") for (int k = 0; k < 2; ++k) \
;         acc[ai][bj][m][n] = __builtin_amdgcn_mfma_f32_16x16x32_bf16(Bt[n][k], At[m][k], acc[ai][bj][m][n], 0, 0, 0); __builtin_amdgcn_s_setprio(0); } while (0)
; #define PG8_WAIT_V(n) asm volatile("s_waitcnt vmcnt(" #n ")" ::: "memory")
; #define PG8_WAIT_L(n) asm volatile("s_waitcnt lgkmcnt(" #n ")" ::: "memory")
; #define PG8_BAR __builtin_amdgcn_s_barrier()
; #define PG8_SCHED __builtin_amdgcn_sched_barrier(0)
; template <class Epi, class Sched, bool ALIGN_EPI = true>
; __device__ __forceinline__ void gemm_phase(LAS unsigned char* lds, const Gemm g, const Sched& S, const Epi& E) {
;     ...
;             PG8_LDB(B0, 0, 0); PG8_LDB(B1, 0, 1); PG8_SCHED; PG8_LDA(At, 0, 0); PG8_STAGE(PG8_SA(1, 1), a1 + hA, voffA);
;             PG8_WAIT_V(8); PG8_WAIT_L(0); PG8_BAR; PG8_MMA(0, 0, At, B0); PG8_MMA(0, 1, At, B1); PG8_BAR; PG8_SCHED;
;             PG8_LDA(At, 0, 1); PG8_STAGE(PG8_SB(0, 0), b2, voffB); PG8_STAGE(PG8_SB(0, 1), b2 + hB, voffB); PG8_STAGE(PG8_SA(0, 0), a2, voffA);
;             PG8_WAIT_V(8); PG8_WAIT_L(0); PG8_BAR; PG8_MMA(1, 0, At, B0); PG8_MMA(1, 1, At, B1); PG8_BAR; PG8_SCHED;
;             PG8_LDB(B0, 1, 0); PG8_LDB(B1, 1, 1); PG8_SCHED; PG8_LDA(At, 1, 0); PG8_STAGE(PG8_SA(0, 1), a2 + hA, voffA);
;             PG8_WAIT_V(8); PG8_WAIT_L(0); PG8_BAR; PG8_MMA(0, 0, At, B0); PG8_MMA(0, 1, At, B1); PG8_BAR; PG8_SCHED;
	s_setprio 1
	s_waitcnt lgkmcnt(0)
	v_mfma_f32_16x16x32_bf16 v[120:123], v[136:139], v[212:215], v[120:123]
	v_mfma_f32_16x16x32_bf16 v[116:119], v[144:147], v[212:215], v[116:119]
	v_mfma_f32_16x16x32_bf16 v[96:99], v[136:139], v[220:223], v[96:99]
	v_mfma_f32_16x16x32_bf16 v[92:95], v[144:147], v[220:223], v[92:95]
	v_mfma_f32_16x16x32_bf16 v[64:67], v[136:139], v[228:231], v[64:67]
	v_mfma_f32_16x16x32_bf16 v[60:63], v[144:147], v[228:231], v[60:63]
	v_mfma_f32_16x16x32_bf16 v[24:27], v[136:139], v[236:239], v[24:27]
	v_mfma_f32_16x16x32_bf16 v[20:23], v[144:147], v[236:239], v[20:23]
	v_mfma_f32_16x16x32_bf16 v[120:123], v[140:143], v[216:219], v[120:123]
	v_mfma_f32_16x16x32_bf16 v[116:119], v[170:173], v[216:219], v[116:119]
	v_mfma_f32_16x16x32_bf16 v[96:99], v[140:143], v[224:227], v[96:99]
	v_mfma_f32_16x16x32_bf16 v[92:95], v[170:173], v[224:227], v[92:95]
	v_mfma_f32_16x16x32_bf16 v[64:67], v[140:143], v[232:235], v[64:67]
	v_mfma_f32_16x16x32_bf16 v[60:63], v[170:173], v[232:235], v[60:63]
	v_mfma_f32_16x16x32_bf16 v[24:27], v[140:143], v[240:243], v[24:27]
	v_mfma_f32_16x16x32_bf16 v[20:23], v[170:173], v[240:243], v[20:23]
	s_setprio 0
	s_setprio 1
	v_mfma_f32_16x16x32_bf16 v[112:115], v[174:177], v[212:215], v[112:115]
	v_mfma_f32_16x16x32_bf16 v[108:111], v[182:185], v[212:215], v[108:111]
	v_mfma_f32_16x16x32_bf16 v[88:91], v[174:177], v[220:223], v[88:91]
	v_mfma_f32_16x16x32_bf16 v[84:87], v[182:185], v[220:223], v[84:87]
	v_mfma_f32_16x16x32_bf16 v[48:51], v[174:177], v[228:231], v[48:51]
	v_mfma_f32_16x16x32_bf16 v[44:47], v[182:185], v[228:231], v[44:47]
	v_mfma_f32_16x16x32_bf16 v[16:19], v[174:177], v[236:239], v[16:19]
	v_mfma_f32_16x16x32_bf16 v[12:15], v[182:185], v[236:239], v[12:15]
	v_mfma_f32_16x16x32_bf16 v[112:115], v[178:181], v[216:219], v[112:115]
	v_mfma_f32_16x16x32_bf16 v[108:111], v[208:211], v[216:219], v[108:111]
	v_mfma_f32_16x16x32_bf16 v[88:91], v[178:181], v[224:227], v[88:91]
	v_mfma_f32_16x16x32_bf16 v[84:87], v[208:211], v[224:227], v[84:87]
	v_mfma_f32_16x16x32_bf16 v[48:51], v[178:181], v[232:235], v[48:51]
	v_mfma_f32_16x16x32_bf16 v[44:47], v[208:211], v[232:235], v[44:47]
	v_mfma_f32_16x16x32_bf16 v[16:19], v[178:181], v[240:243], v[16:19]
	v_mfma_f32_16x16x32_bf16 v[12:15], v[208:211], v[240:243], v[12:15]
	s_setprio 0
	s_barrier
	s_add_i32 s25, 0, 0x18000
	v_add_u32_e32 v162, s25, v186
	s_add_i32 s26, 0, 0x1c000
	ds_read_b128 v[136:139], v162
	ds_read_b128 v[140:143], v162 offset:1024
	ds_read_b128 v[144:147], v162 offset:2048
	ds_read_b128 v[170:173], v162 offset:3072
	v_add_u32_e32 v162, s26, v186
	ds_read_b128 v[174:177], v162
	ds_read_b128 v[178:181], v162 offset:1024
	ds_read_b128 v[182:185], v162 offset:2048
	ds_read_b128 v[208:211], v162 offset:3072
	s_add_u32 s10, s64, 0x80000
	s_addc_u32 s11, s65, 0
	s_mov_b32 m0, s75
	v_lshl_add_u64 v[162:163], s[10:11], 0, v[0:1]
	ds_read_b128 v[212:215], v197 offset:32768
	ds_read_b128 v[216:219], v197 offset:33792
	ds_read_b128 v[220:223], v197 offset:34816
	ds_read_b128 v[224:227], v197 offset:35840
	ds_read_b128 v[228:231], v197 offset:36864
	ds_read_b128 v[232:235], v197 offset:37888
	ds_read_b128 v[236:239], v197 offset:38912
	ds_read_b128 v[240:243], v197 offset:39936
	global_load_lds_dwordx4 v[162:163], off
	v_lshl_add_u64 v[162:163], s[10:11], 0, v[148:149]
	s_mov_b32 m0, s76
	s_nop 0
	global_load_lds_dwordx4 v[162:163], off
	s_waitcnt vmcnt(8)
	s_waitcnt lgkmcnt(0)
	s_barrier
	s_setprio 1
	s_waitcnt lgkmcnt(0)
	v_mfma_f32_16x16x32_bf16 v[36:39], v[136:139], v[212:215], v[36:39]
	v_mfma_f32_16x16x32_bf16 v[40:43], v[144:147], v[212:215], v[40:43]
	v_mfma_f32_16x16x32_bf16 v[68:71], v[136:139], v[220:223], v[68:71]
	v_mfma_f32_16x16x32_bf16 v[72:75], v[144:147], v[220:223], v[72:75]
	v_mfma_f32_16x16x32_bf16 v[100:103], v[136:139], v[228:231], v[100:103]
	v_mfma_f32_16x16x32_bf16 v[104:107], v[144:147], v[228:231], v[104:107]
	v_mfma_f32_16x16x32_bf16 v[128:131], v[136:139], v[236:239], v[128:131]
	v_mfma_f32_16x16x32_bf16 v[124:127], v[144:147], v[236:239], v[124:127]
	v_mfma_f32_16x16x32_bf16 v[36:39], v[140:143], v[216:219], v[36:39]
	v_mfma_f32_16x16x32_bf16 v[40:43], v[170:173], v[216:219], v[40:43]
	v_mfma_f32_16x16x32_bf16 v[68:71], v[140:143], v[224:227], v[68:71]
	v_mfma_f32_16x16x32_bf16 v[72:75], v[170:173], v[224:227], v[72:75]
	v_mfma_f32_16x16x32_bf16 v[100:103], v[140:143], v[232:235], v[100:103]
	v_mfma_f32_16x16x32_bf16 v[104:107], v[170:173], v[232:235], v[104:107]
	v_mfma_f32_16x16x32_bf16 v[128:131], v[140:143], v[240:243], v[128:131]
	v_mfma_f32_16x16x32_bf16 v[124:127], v[170:173], v[240:243], v[124:127]
	s_setprio 0
	s_setprio 1
	v_mfma_f32_16x16x32_bf16 v[8:11], v[174:177], v[212:215], v[8:11]
	v_mfma_f32_16x16x32_bf16 v[4:7], v[182:185], v[212:215], v[4:7]
	v_mfma_f32_16x16x32_bf16 v[32:35], v[174:177], v[220:223], v[32:35]
	v_mfma_f32_16x16x32_bf16 v[28:31], v[182:185], v[220:223], v[28:31]
	v_mfma_f32_16x16x32_bf16 v[56:59], v[174:177], v[228:231], v[56:59]
	v_mfma_f32_16x16x32_bf16 v[52:55], v[182:185], v[228:231], v[52:55]
	v_mfma_f32_16x16x32_bf16 v[80:83], v[174:177], v[236:239], v[80:83]
	v_mfma_f32_16x16x32_bf16 v[76:79], v[182:185], v[236:239], v[76:79]
	v_mfma_f32_16x16x32_bf16 v[8:11], v[178:181], v[216:219], v[8:11]
	v_mfma_f32_16x16x32_bf16 v[4:7], v[208:211], v[216:219], v[4:7]
	v_mfma_f32_16x16x32_bf16 v[32:35], v[178:181], v[224:227], v[32:35]
	v_mfma_f32_16x16x32_bf16 v[28:31], v[208:211], v[224:227], v[28:31]
	v_mfma_f32_16x16x32_bf16 v[56:59], v[178:181], v[232:235], v[56:59]
	v_mfma_f32_16x16x32_bf16 v[52:55], v[208:211], v[232:235], v[52:55]
	v_mfma_f32_16x16x32_bf16 v[80:83], v[178:181], v[240:243], v[80:83]
	v_mfma_f32_16x16x32_bf16 v[76:79], v[208:211], v[240:243], v[76:79]
	s_setprio 0
	s_barrier
; #define PG8_STAGE(bufoff, gbase, voff) do { _Pragma("unroll") for (int _i = 0; _i < 2; ++_i) \
;         __builtin_amdgcn_global_load_lds((const unsigned*)((const char*)(gbase) + (voff)[_i]), (LAS unsigned*)(lds + (bufoff) + ldsw + _i * 8192), 16, 0, 0); } while (0)
; #define PG8_LDA(dst, b, h) do { _Pragma("unroll") for (int m = 0; m < 4; ++m) _Pragma("unroll") for (int k = 0; k < 2; ++k) dst[m][k] = *(const LAS bf16x8*)(lds + PG8_SA(b, h) + aoff + m * 2048 + k * 1024); } while (0)
; #define PG8_MMA(ai, bj, At, Bt) do { __builtin_amdgcn_s_setprio(1); _Pragma("unroll") for (int m = 0; m < 4; ++m) _Pragma("unroll") for (int n = 0; n < 2; ++n) _Pragma("unroll") for (int k = 0; k < 2; ++k) \
;         acc[ai][bj][m][n] = __builtin_amdgcn_mfma_f32_16x16x32_bf16(Bt[n][k], At[m][k], acc[ai][bj][m][n], 0, 0, 0); __builtin_amdgcn_s_setprio(0); } while (0)
; #define PG8_WAIT_V(n) asm volatile("s_waitcnt vmcnt(" #n ")" ::: "memory")
; #define PG8_WAIT_L(n) asm volatile("s_waitcnt lgkmcnt(" #n ")" ::: "memory")
; #define PG8_BAR __builtin_amdgcn_s_barrier()
; #define PG8_SCHED __builtin_amdgcn_sched_barrier(0)
; template <class Epi, class Sched, bool ALIGN_EPI = true>
; __device__ __forceinline__ void gemm_phase(LAS unsigned char* lds, const Gemm g, const Sched& S, const Epi& E) {
;     ...
;             PG8_LDA(At, 1, 1); PG8_STAGE(PG8_SB(1, 0), b3, voffB); PG8_STAGE(PG8_SB(1, 1), b3 + hB, voffB); PG8_STAGE(PG8_SA(1, 0), a3, voffA);
;             PG8_WAIT_V(8); PG8_WAIT_L(0); PG8_BAR; PG8_MMA(1, 0, At, B0); PG8_MMA(1, 1, At, B1); PG8_BAR; PG8_SCHED;
;         }
;         if constexpr (ALIGN_EPI) { if (wr == 0) PG8_BAR; }
	s_add_i32 s10, s25, s67
	v_lshl_add_u64 v[162:163], v[244:245], 0, s[86:87]
	s_mov_b32 m0, s10
	ds_read_b128 v[212:215], v197 offset:49152
	ds_read_b128 v[216:219], v197 offset:50176
	ds_read_b128 v[220:223], v197 offset:51200
	ds_read_b128 v[224:227], v197 offset:52224
	ds_read_b128 v[228:231], v197 offset:53248
	ds_read_b128 v[232:235], v197 offset:54272
	ds_read_b128 v[236:239], v197 offset:55296
	ds_read_b128 v[240:243], v197 offset:56320
	global_load_lds_dwordx4 v[162:163], off
	s_add_i32 m0, s10, 0x2000
	s_add_u32 s10, s62, 0x80080
	v_lshl_add_u64 v[162:163], v[246:247], 0, s[86:87]
	s_addc_u32 s11, s63, 0
	s_add_i32 s25, s26, s67
	global_load_lds_dwordx4 v[162:163], off
	v_lshl_add_u64 v[162:163], s[10:11], 0, v[2:3]
	s_mov_b32 m0, s25
	v_lshl_add_u64 v[160:161], v[160:161], 0, s[86:87]
	global_load_lds_dwordx4 v[162:163], off
	v_lshl_add_u64 v[162:163], s[10:11], 0, v[150:151]
	s_add_i32 m0, s25, 0x2000
	s_nop 0
	global_load_lds_dwordx4 v[162:163], off
	v_lshl_add_u64 v[162:163], v[248:249], 0, s[86:87]
	s_mov_b32 m0, s79
	s_nop 0
	global_load_lds_dwordx4 v[162:163], off
	s_mov_b32 m0, s80
	s_nop 0
	global_load_lds_dwordx4 v[160:161], off
	s_waitcnt vmcnt(8)
	s_waitcnt lgkmcnt(0)
	s_barrier
	s_setprio 1
	s_waitcnt lgkmcnt(0)
	v_mfma_f32_16x16x32_bf16 v[120:123], v[136:139], v[212:215], v[120:123]
	v_mfma_f32_16x16x32_bf16 v[116:119], v[144:147], v[212:215], v[116:119]
	v_mfma_f32_16x16x32_bf16 v[96:99], v[136:139], v[220:223], v[96:99]
	v_mfma_f32_16x16x32_bf16 v[92:95], v[144:147], v[220:223], v[92:95]
	v_mfma_f32_16x16x32_bf16 v[64:67], v[136:139], v[228:231], v[64:67]
	v_mfma_f32_16x16x32_bf16 v[60:63], v[144:147], v[228:231], v[60:63]
	v_mfma_f32_16x16x32_bf16 v[24:27], v[136:139], v[236:239], v[24:27]
	v_mfma_f32_16x16x32_bf16 v[20:23], v[144:147], v[236:239], v[20:23]
	v_mfma_f32_16x16x32_bf16 v[120:123], v[140:143], v[216:219], v[120:123]
	v_mfma_f32_16x16x32_bf16 v[116:119], v[170:173], v[216:219], v[116:119]
	v_mfma_f32_16x16x32_bf16 v[96:99], v[140:143], v[224:227], v[96:99]
	v_mfma_f32_16x16x32_bf16 v[92:95], v[170:173], v[224:227], v[92:95]
	v_mfma_f32_16x16x32_bf16 v[64:67], v[140:143], v[232:235], v[64:67]
	v_mfma_f32_16x16x32_bf16 v[60:63], v[170:173], v[232:235], v[60:63]
	v_mfma_f32_16x16x32_bf16 v[24:27], v[140:143], v[240:243], v[24:27]
	v_mfma_f32_16x16x32_bf16 v[20:23], v[170:173], v[240:243], v[20:23]
	s_setprio 0
	s_setprio 1
	v_mfma_f32_16x16x32_bf16 v[112:115], v[174:177], v[212:215], v[112:115]
	v_mfma_f32_16x16x32_bf16 v[108:111], v[182:185], v[212:215], v[108:111]
	v_mfma_f32_16x16x32_bf16 v[88:91], v[174:177], v[220:223], v[88:91]
	v_mfma_f32_16x16x32_bf16 v[84:87], v[182:185], v[220:223], v[84:87]
	v_mfma_f32_16x16x32_bf16 v[48:51], v[174:177], v[228:231], v[48:51]
	v_mfma_f32_16x16x32_bf16 v[44:47], v[182:185], v[228:231], v[44:47]
	v_mfma_f32_16x16x32_bf16 v[16:19], v[174:177], v[236:239], v[16:19]
	v_mfma_f32_16x16x32_bf16 v[12:15], v[182:185], v[236:239], v[12:15]
	v_mfma_f32_16x16x32_bf16 v[112:115], v[178:181], v[216:219], v[112:115]
	v_mfma_f32_16x16x32_bf16 v[108:111], v[208:211], v[216:219], v[108:111]
	v_mfma_f32_16x16x32_bf16 v[88:91], v[178:181], v[224:227], v[88:91]
	v_mfma_f32_16x16x32_bf16 v[84:87], v[208:211], v[224:227], v[84:87]
	v_mfma_f32_16x16x32_bf16 v[48:51], v[178:181], v[232:235], v[48:51]
	v_mfma_f32_16x16x32_bf16 v[44:47], v[208:211], v[232:235], v[44:47]
	v_mfma_f32_16x16x32_bf16 v[16:19], v[178:181], v[240:243], v[16:19]
	v_mfma_f32_16x16x32_bf16 v[12:15], v[208:211], v[240:243], v[12:15]
	s_setprio 0
	s_barrier
	s_add_i32 s24, s24, 2
	s_cmp_gt_u32 s24, 29
	s_mov_b64 s[10:11], vcc
	s_cbranch_scc0 .LBB0_667
	s_and_b64 vcc, exec, s[44:45]
	s_cbranch_vccz .LBB0_670
	s_barrier

;     __device__ __forceinline__ void operator()(f32x4 (&acc)[2][2][4][2], const Unit& u, int wr, int wc, int fr, int fq, int wid, int lane) const {
;     ...
;         if (lane < 32) {
;             float mt[8], m2[8]; float ms = 0.f;
; #pragma unroll
;             for (int t = 0; t < 8; ++t) { const unsigned long long w = __hip_atomic_load(slot + t, __ATOMIC_RELAXED, __HIP_MEMORY_SCOPE_AGENT); mt[t] = __uint_as_float((unsigned)w); m2[t] = __uint_as_float((unsigned)(w >> 32)); ms += mt[t]; }
;             const float mean = ms * 0.125f; float q = 0.f;
; #pragma unroll
;             for (int t = 0; t < 8; ++t) { const float dm = mt[t] - mean; q += m2[t] + 256.0f * dm * dm; }
;             S[row] = (f32x2){mean, 1.0f / sqrtf(q * (1.0f / 2048.0f) + LN_EPS)};
;         }
.LBB0_745:
	s_waitcnt vmcnt(0) lgkmcnt(0)
	s_barrier
	s_and_saveexec_b64 s[62:63], s[6:7]
	s_cbranch_execz .LBB0_747
	s_waitcnt lgkmcnt(0)
	global_load_dwordx2 v[134:135], v[132:133], off sc1
	global_load_dwordx2 v[136:137], v[132:133], off offset:8 sc1
	global_load_dwordx2 v[138:139], v[132:133], off offset:16 sc1
	global_load_dwordx2 v[140:141], v[132:133], off offset:24 sc1
	global_load_dwordx2 v[142:143], v[132:133], off offset:32 sc1
	global_load_dwordx2 v[144:145], v[132:133], off offset:40 sc1
	global_load_dwordx2 v[146:147], v[132:133], off offset:48 sc1
	global_load_dwordx2 v[160:161], v[132:133], off offset:56 sc1
	s_mov_b32 s10, 0xf800000
	s_waitcnt vmcnt(7)
	v_add_f32_e32 v162, 0, v134
	s_waitcnt vmcnt(6)
	v_add_f32_e32 v162, v162, v136
	s_waitcnt vmcnt(5)
	v_add_f32_e32 v162, v162, v138
	s_waitcnt vmcnt(4)
	v_add_f32_e32 v162, v162, v140
	s_waitcnt vmcnt(3)
	v_add_f32_e32 v162, v162, v142
	s_waitcnt vmcnt(2)
	v_add_f32_e32 v162, v162, v144
	s_waitcnt vmcnt(1)
	v_add_f32_e32 v162, v162, v146
	s_waitcnt vmcnt(0)
	v_add_f32_e32 v133, v162, v160
	v_fmamk_f32 v134, v133, 0xbe000000, v134
	v_mul_f32_e32 v162, 0x43800000, v134
	v_fmac_f32_e32 v135, v134, v162
	v_add_f32_e32 v134, 0, v135
	v_fmamk_f32 v135, v133, 0xbe000000, v136
	v_mul_f32_e32 v136, 0x43800000, v135
	v_fmac_f32_e32 v137, v135, v136
	v_fmamk_f32 v135, v133, 0xbe000000, v138
	v_mul_f32_e32 v136, 0x43800000, v135
	v_fmac_f32_e32 v139, v135, v136
	v_fmamk_f32 v135, v133, 0xbe000000, v140
	v_mul_f32_e32 v136, 0x43800000, v135
	v_fmac_f32_e32 v141, v135, v136
	v_fmamk_f32 v135, v133, 0xbe000000, v142
	v_mul_f32_e32 v136, 0x43800000, v135
	v_add_f32_e32 v134, v137, v134
	v_fmac_f32_e32 v143, v135, v136
	v_fmamk_f32 v135, v133, 0xbe000000, v144
	v_add_f32_e32 v134, v139, v134
	v_mul_f32_e32 v136, 0x43800000, v135
	v_add_f32_e32 v134, v141, v134
	v_fmac_f32_e32 v145, v135, v136
	v_fmamk_f32 v135, v133, 0xbe000000, v146
	v_mul_f32_e32 v132, 0x3e000000, v133
	v_add_f32_e32 v134, v143, v134
	v_mul_f32_e32 v136, 0x43800000, v135
	v_fmamk_f32 v133, v133, 0xbe000000, v160
	v_add_f32_e32 v134, v145, v134
	v_fmac_f32_e32 v147, v135, v136
	v_mul_f32_e32 v135, 0x43800000, v133
	v_add_f32_e32 v134, v147, v134
	v_fmac_f32_e32 v161, v133, v135
	v_add_f32_e32 v133, v161, v134
	v_fmamk_f32 v133, v133, 0x3a000000, v200
	v_cmp_gt_f32_e32 vcc, s10, v133
	v_mul_f32_e32 v134, 0x4f800000, v133
	s_nop 0
	v_cndmask_b32_e32 v133, v133, v134, vcc
	v_sqrt_f32_e32 v134, v133
	s_nop 0
	v_add_u32_e32 v135, -1, v134
	v_fma_f32 v136, -v135, v134, v133
	v_cmp_ge_f32_e64 s[10:11], 0, v136
	v_add_u32_e32 v136, 1, v134
	s_nop 0
	v_cndmask_b32_e64 v135, v134, v135, s[10:11]
	v_fma_f32 v134, -v136, v134, v133
	v_cmp_lt_f32_e64 s[10:11], 0, v134
	s_nop 1
	v_cndmask_b32_e64 v134, v135, v136, s[10:11]
	v_mul_f32_e32 v135, 0x37800000, v134
	v_cndmask_b32_e32 v134, v134, v135, vcc
	v_cmp_class_f32_e32 vcc, v133, v201
	s_nop 1
	v_cndmask_b32_e32 v133, v134, v133, vcc
	v_div_scale_f32 v134, s[10:11], v133, v133, 1.0
	v_rcp_f32_e32 v135, v134
	s_nop 0
	v_fma_f32 v136, -v134, v135, 1.0
	v_fmac_f32_e32 v135, v136, v135
	v_div_scale_f32 v136, vcc, 1.0, v133, 1.0
	v_mul_f32_e32 v137, v136, v135
	v_fma_f32 v138, -v134, v137, v136
	v_fmac_f32_e32 v137, v138, v135
	v_fma_f32 v134, -v134, v137, v136
	v_div_fmas_f32 v134, v134, v135, v137
	v_div_fixup_f32 v133, v134, v133, 1.0
	v_lshl_add_u32 v134, v188, 3, s51
	ds_write_b64 v134, v[132:133]

;     __device__ __forceinline__ void operator()(f32x4 (&acc)[2][2][4][2], const Unit& u, int wr, int wc, int fr_, int fq_, int wid, int lane_) const {
;     ...
;             const int t = wid * 64 + lane, kind = t >> 6, pr = t & 63, bj = kind >> 2, tap = kind & 3;
;             const float* src = (tap < 3) ? (cw + (size_t)tap * FF2 + bj * FF + u.pn * 128 + 2 * pr) : (cb + bj * FF + u.pn * 128 + 2 * pr);
;             const f32x2 wv = *(const f32x2*)src;
; template <class Epi, class Sched, bool ALIGN_EPI = true>
; __device__ __forceinline__ void gemm_phase(LAS unsigned char* lds, const Gemm g, const Sched& S, const Epi& E) {
;     ...
; #pragma unroll
;         for (int a = 0; a < 2; ++a)
; #pragma unroll
;             for (int b = 0; b < 2; ++b)
; #pragma unroll
;                 for (int m = 0; m < 4; ++m)
; #pragma unroll
;                     for (int n = 0; n < 2; ++n) acc[a][b][m][n] = (f32x4){0.f, 0.f, 0.f, 0.f};
;         cur = nxt; cA = nA; cB = nB; ++ui;
.LBB0_827:
	s_ashr_i32 s39, s38, 31
	s_lshl_b64 s[16:17], s[38:39], 20
	s_add_u32 s40, s46, s16
	s_addc_u32 s41, s47, s17
	s_and_b64 s[16:17], s[4:5], exec
	s_cselect_b32 s16, s41, s7
	s_cselect_b32 s17, s40, s6
	s_ashr_i32 s15, s14, 31
	s_lshl_b64 s[18:19], s[14:15], 20
	s_add_u32 s42, s53, s18
	s_addc_u32 s43, s60, s19
	s_and_b64 s[18:19], s[4:5], exec
	s_cselect_b32 s15, s43, s45
	s_cselect_b32 s18, s42, s44
	s_add_u32 s6, s6, 0x80080
	s_addc_u32 s7, s7, 0
	s_add_u32 s19, s44, 0x100
	v_mov_b32_e32 v4, 0
	s_addc_u32 s24, s45, 0
	s_mov_b32 s25, -2
	v_mov_b32_e32 v5, v4
	v_mov_b32_e32 v6, v4
	v_mov_b32_e32 v7, v4
	v_mov_b32_e32 v52, v4
	v_mov_b32_e32 v53, v4
	v_mov_b32_e32 v54, v4
	v_mov_b32_e32 v55, v4
	v_mov_b32_e32 v8, v4
	v_mov_b32_e32 v9, v4
	v_mov_b32_e32 v10, v4
	v_mov_b32_e32 v11, v4
	v_mov_b32_e32 v76, v4
	v_mov_b32_e32 v77, v4
	v_mov_b32_e32 v78, v4
	v_mov_b32_e32 v79, v4
	v_mov_b32_e32 v16, v4
	v_mov_b32_e32 v17, v4
	v_mov_b32_e32 v18, v4
	v_mov_b32_e32 v19, v4
	v_mov_b32_e32 v92, v4
	v_mov_b32_e32 v93, v4
	v_mov_b32_e32 v94, v4
	v_mov_b32_e32 v95, v4
	v_mov_b32_e32 v20, v4
	v_mov_b32_e32 v21, v4
	v_mov_b32_e32 v22, v4
	v_mov_b32_e32 v23, v4
	v_mov_b32_e32 v104, v4
	v_mov_b32_e32 v105, v4
	v_mov_b32_e32 v106, v4
	v_mov_b32_e32 v107, v4
	v_mov_b32_e32 v48, v4
	v_mov_b32_e32 v49, v4
	v_mov_b32_e32 v50, v4
	v_mov_b32_e32 v51, v4
	v_mov_b32_e32 v12, v4
	v_mov_b32_e32 v13, v4
	v_mov_b32_e32 v14, v4
	v_mov_b32_e32 v15, v4
	v_mov_b32_e32 v56, v4
	v_mov_b32_e32 v57, v4
	v_mov_b32_e32 v58, v4
	v_mov_b32_e32 v59, v4
	v_mov_b32_e32 v24, v4
	v_mov_b32_e32 v25, v4
	v_mov_b32_e32 v26, v4
	v_mov_b32_e32 v27, v4
	v_mov_b32_e32 v64, v4
	v_mov_b32_e32 v65, v4
	v_mov_b32_e32 v66, v4
	v_mov_b32_e32 v67, v4
	v_mov_b32_e32 v40, v4
	v_mov_b32_e32 v41, v4
	v_mov_b32_e32 v42, v4
	v_mov_b32_e32 v43, v4
	v_mov_b32_e32 v68, v4
	v_mov_b32_e32 v69, v4
	v_mov_b32_e32 v70, v4
	v_mov_b32_e32 v71, v4
	v_mov_b32_e32 v60, v4
	v_mov_b32_e32 v61, v4
	v_mov_b32_e32 v62, v4
	v_mov_b32_e32 v63, v4
	v_mov_b32_e32 v28, v4
	v_mov_b32_e32 v29, v4
	v_mov_b32_e32 v30, v4
	v_mov_b32_e32 v31, v4
	v_mov_b32_e32 v112, v4
	v_mov_b32_e32 v113, v4
	v_mov_b32_e32 v114, v4
	v_mov_b32_e32 v115, v4
	v_mov_b32_e32 v32, v4
	v_mov_b32_e32 v33, v4
	v_mov_b32_e32 v34, v4
	v_mov_b32_e32 v35, v4
	v_mov_b32_e32 v120, v4
	v_mov_b32_e32 v121, v4
	v_mov_b32_e32 v122, v4
	v_mov_b32_e32 v123, v4
	v_mov_b32_e32 v36, v4
	v_mov_b32_e32 v37, v4
	v_mov_b32_e32 v38, v4
	v_mov_b32_e32 v39, v4
	v_mov_b32_e32 v124, v4
	v_mov_b32_e32 v125, v4
	v_mov_b32_e32 v126, v4
	v_mov_b32_e32 v127, v4
	v_mov_b32_e32 v44, v4
	v_mov_b32_e32 v45, v4
	v_mov_b32_e32 v46, v4
	v_mov_b32_e32 v47, v4
	v_mov_b32_e32 v128, v4
	v_mov_b32_e32 v129, v4
	v_mov_b32_e32 v130, v4
	v_mov_b32_e32 v131, v4
	v_mov_b32_e32 v80, v4
	v_mov_b32_e32 v81, v4
	v_mov_b32_e32 v82, v4
	v_mov_b32_e32 v83, v4
	v_mov_b32_e32 v72, v4
	v_mov_b32_e32 v73, v4
	v_mov_b32_e32 v74, v4
	v_mov_b32_e32 v75, v4
	v_mov_b32_e32 v84, v4
	v_mov_b32_e32 v85, v4
	v_mov_b32_e32 v86, v4
	v_mov_b32_e32 v87, v4
	v_mov_b32_e32 v88, v4
	v_mov_b32_e32 v89, v4
	v_mov_b32_e32 v90, v4
	v_mov_b32_e32 v91, v4
	v_mov_b32_e32 v96, v4
	v_mov_b32_e32 v97, v4
	v_mov_b32_e32 v98, v4
	v_mov_b32_e32 v99, v4
	v_mov_b32_e32 v108, v4
	v_mov_b32_e32 v109, v4
	v_mov_b32_e32 v110, v4
	v_mov_b32_e32 v111, v4
	v_mov_b32_e32 v100, v4
	v_mov_b32_e32 v101, v4
	v_mov_b32_e32 v102, v4
	v_mov_b32_e32 v103, v4
	v_mov_b32_e32 v116, v4
	v_mov_b32_e32 v117, v4
	v_mov_b32_e32 v118, v4
	v_mov_b32_e32 v119, v4
	v_add_u32_e32 v228, s77, v158
	v_ashrrev_i32_e32 v229, 6, v228
	v_and_b32_e32 v230, 3, v229
	v_lshrrev_b32_e32 v231, 8, v228
	v_mul_u32_u24_e32 v228, 0x2c00, v230
	v_lshlrev_b32_e32 v228, 2, v228
	v_mov_b32_e32 v229, 0
	v_lshl_add_u64 v[232:233], s[2:3], 0, v[228:229]
	v_mov_b32_e32 v228, s9
	v_cmp_eq_u32_e32 vcc, 3, v230
	v_mul_i32_i24_e32 v234, 0x1600, v231
	v_ashrrev_i32_e32 v235, 31, v234
	v_cndmask_b32_e32 v233, v233, v228, vcc
	v_mov_b32_e32 v228, s8
	v_cndmask_b32_e32 v232, v232, v228, vcc
	v_lshl_add_u64 v[232:233], v[234:235], 2, v[232:233]
	s_lshl_b32 s26, s82, 7
	s_ashr_i32 s27, s26, 31
	v_lshl_add_u64 v[232:233], s[26:27], 2, v[232:233]
	v_and_b32_e32 v228, 63, v158
	v_lshlrev_b32_e32 v228, 3, v228
	v_mov_b32_e32 v229, 0
	v_lshl_add_u64 v[232:233], v[232:233], 0, v[228:229]
	global_load_dwordx2 v[226:227], v[232:233], off
; #define PG8_STAGE(bufoff, gbase, voff) do { _Pragma("unroll") for (int _i = 0; _i < 2; ++_i) \
;         __builtin_amdgcn_global_load_lds((const unsigned*)((const char*)(gbase) + (voff)[_i]), (LAS unsigned*)(lds + (bufoff) + ldsw + _i * 8192), 16, 0, 0); } while (0)
; #define PG8_LDA(dst, b, h) do { _Pragma("unroll") for (int m = 0; m < 4; ++m) _Pragma("unroll") for (int k = 0; k < 2; ++k) dst[m][k] = *(const LAS bf16x8*)(lds + PG8_SA(b, h) + aoff + m * 2048 + k * 1024); } while (0)
; #define PG8_LDB(dst, b, h) do { _Pragma("unroll") for (int n = 0; n < 2; ++n) _Pragma("unroll") for (int k = 0; k < 2; ++k) dst[n][k] = *(const LAS bf16x8*)(lds + PG8_SB(b, h) + boff + n * 2048 + k * 1024); } while (0)
; #define PG8_WAIT_V(n) asm volatile("s_waitcnt vmcnt(" #n ")" ::: "memory")
; #define PG8_BAR __builtin_amdgcn_s_barrier()
; template <class Epi, class Sched, bool ALIGN_EPI = true>
; __device__ __forceinline__ void gemm_phase(LAS unsigned char* lds, const Gemm g, const Sched& S, const Epi& E) {
;     ...
;         for (int t = 0; t < nt; t += 2) {
;             const bool last = (t == nt - 2);
;             const char* a1 = cA + (size_t)(t + 1) * kstep;
;             const char* a2 = last ? nA : cA + (size_t)(t + 2) * kstep; const char* b2 = last ? nB : cB + (size_t)(t + 2) * kstep;
;             const char* a3 = a2 + kstep; const char* b3 = b2 + kstep;
;             PG8_LDB(B0, 0, 0); PG8_LDB(B1, 0, 1); PG8_SCHED; PG8_LDA(At, 0, 0); PG8_STAGE(PG8_SA(1, 1), a1 + hA, voffA);
;             PG8_WAIT_V(8); PG8_WAIT_L(0); PG8_BAR; PG8_MMA(0, 0, At, B0); PG8_MMA(0, 1, At, B1); PG8_BAR; PG8_SCHED;
;             PG8_LDA(At, 0, 1); PG8_STAGE(PG8_SB(0, 0), b2, voffB); PG8_STAGE(PG8_SB(0, 1), b2 + hB, voffB); PG8_STAGE(PG8_SA(0, 0), a2, voffA);
;             PG8_WAIT_V(8); PG8_WAIT_L(0); PG8_BAR; PG8_MMA(1, 0, At, B0); PG8_MMA(1, 1, At, B1); PG8_BAR; PG8_SCHED;
;             PG8_LDB(B0, 1, 0); PG8_LDB(B1, 1, 1); PG8_SCHED; PG8_LDA(At, 1, 0); PG8_STAGE(PG8_SA(0, 1), a2 + hA, voffA);
;             PG8_WAIT_V(8); PG8_WAIT_L(0); PG8_BAR; PG8_MMA(0, 0, At, B0); PG8_MMA(0, 1, At, B1); PG8_BAR; PG8_SCHED;
;             PG8_LDA(At, 1, 1); PG8_STAGE(PG8_SB(1, 0), b3, voffB); PG8_STAGE(PG8_SB(1, 1), b3 + hB, voffB); PG8_STAGE(PG8_SA(1, 0), a3, voffA);
;             PG8_WAIT_V(8); PG8_WAIT_L(0); PG8_BAR; PG8_MMA(1, 0, At, B0); PG8_MMA(1, 1, At, B1); PG8_BAR; PG8_SCHED;
.LBB0_828:
	s_add_u32 s26, s6, 0xfff80080
	s_addc_u32 s27, s7, -1
	s_add_i32 s30, 0, 0x10000
	s_cmp_eq_u32 s25, 28
	s_cselect_b32 s59, s16, s27
	s_cselect_b32 s58, s17, s26
	v_add_u32_e32 v2, s30, v204
	s_cselect_b32 s45, s15, s24
	s_cselect_b32 s44, s18, s19
	s_add_i32 s31, 0, 0x14000
	ds_read_b128 v[132:135], v2
	ds_read_b128 v[136:139], v2 offset:1024
	ds_read_b128 v[140:143], v2 offset:2048
	ds_read_b128 v[144:147], v2 offset:3072
	v_add_u32_e32 v2, s31, v204
	ds_read_b128 v[148:151], v2
	ds_read_b128 v[152:155], v2 offset:1024
	ds_read_b128 v[174:177], v2 offset:2048
	ds_read_b128 v[178:181], v2 offset:3072
	v_lshl_add_u64 v[156:157], s[6:7], 0, v[170:171]
	s_add_i32 m0, s62, 0xc000
	ds_read_b128 v[182:185], v205
	ds_read_b128 v[186:189], v205 offset:1024
	ds_read_b128 v[190:193], v205 offset:2048
	ds_read_b128 v[194:197], v205 offset:3072
	ds_read_b128 v[206:209], v205 offset:4096
	ds_read_b128 v[210:213], v205 offset:5120
	ds_read_b128 v[214:217], v205 offset:6144
	ds_read_b128 v[218:221], v205 offset:7168
	global_load_lds_dwordx4 v[156:157], off
	v_lshl_add_u64 v[156:157], s[6:7], 0, v[172:173]
	s_add_i32 m0, s62, 0xe000
	s_nop 0
	global_load_lds_dwordx4 v[156:157], off
	s_waitcnt vmcnt(8)
	s_waitcnt lgkmcnt(0)
	s_barrier
	s_setprio 1
	s_waitcnt lgkmcnt(0)
	v_mfma_f32_16x16x32_bf16 v[116:119], v[132:135], v[182:185], v[116:119]
	v_mfma_f32_16x16x32_bf16 v[100:103], v[140:143], v[182:185], v[100:103]
	v_mfma_f32_16x16x32_bf16 v[108:111], v[132:135], v[190:193], v[108:111]
	v_mfma_f32_16x16x32_bf16 v[96:99], v[140:143], v[190:193], v[96:99]
	v_mfma_f32_16x16x32_bf16 v[88:91], v[132:135], v[206:209], v[88:91]
	v_mfma_f32_16x16x32_bf16 v[84:87], v[140:143], v[206:209], v[84:87]
	v_mfma_f32_16x16x32_bf16 v[72:75], v[132:135], v[214:217], v[72:75]
	v_mfma_f32_16x16x32_bf16 v[80:83], v[140:143], v[214:217], v[80:83]
	v_mfma_f32_16x16x32_bf16 v[116:119], v[136:139], v[186:189], v[116:119]
	v_mfma_f32_16x16x32_bf16 v[100:103], v[144:147], v[186:189], v[100:103]
	v_mfma_f32_16x16x32_bf16 v[108:111], v[136:139], v[194:197], v[108:111]
	v_mfma_f32_16x16x32_bf16 v[96:99], v[144:147], v[194:197], v[96:99]
	v_mfma_f32_16x16x32_bf16 v[88:91], v[136:139], v[210:213], v[88:91]
	v_mfma_f32_16x16x32_bf16 v[84:87], v[144:147], v[210:213], v[84:87]
	v_mfma_f32_16x16x32_bf16 v[72:75], v[136:139], v[218:221], v[72:75]
	v_mfma_f32_16x16x32_bf16 v[80:83], v[144:147], v[218:221], v[80:83]
	s_setprio 0
	s_setprio 1
	v_mfma_f32_16x16x32_bf16 v[128:131], v[148:151], v[182:185], v[128:131]
	v_mfma_f32_16x16x32_bf16 v[44:47], v[174:177], v[182:185], v[44:47]
	v_mfma_f32_16x16x32_bf16 v[124:127], v[148:151], v[190:193], v[124:127]
	v_mfma_f32_16x16x32_bf16 v[36:39], v[174:177], v[190:193], v[36:39]
	v_mfma_f32_16x16x32_bf16 v[120:123], v[148:151], v[206:209], v[120:123]
	v_mfma_f32_16x16x32_bf16 v[32:35], v[174:177], v[206:209], v[32:35]
	v_mfma_f32_16x16x32_bf16 v[112:115], v[148:151], v[214:217], v[112:115]
	v_mfma_f32_16x16x32_bf16 v[28:31], v[174:177], v[214:217], v[28:31]
	v_mfma_f32_16x16x32_bf16 v[128:131], v[152:155], v[186:189], v[128:131]
	v_mfma_f32_16x16x32_bf16 v[44:47], v[178:181], v[186:189], v[44:47]
	v_mfma_f32_16x16x32_bf16 v[124:127], v[152:155], v[194:197], v[124:127]
	v_mfma_f32_16x16x32_bf16 v[36:39], v[178:181], v[194:197], v[36:39]
	v_mfma_f32_16x16x32_bf16 v[120:123], v[152:155], v[210:213], v[120:123]
	v_mfma_f32_16x16x32_bf16 v[32:35], v[178:181], v[210:213], v[32:35]
	v_mfma_f32_16x16x32_bf16 v[112:115], v[152:155], v[218:221], v[112:115]
	v_mfma_f32_16x16x32_bf16 v[28:31], v[178:181], v[218:221], v[28:31]
	s_setprio 0
	s_barrier
	s_add_i32 s26, s30, s61
	v_lshl_add_u64 v[156:157], s[44:45], 0, v[166:167]
	s_mov_b32 m0, s26
	ds_read_b128 v[182:185], v205 offset:16384
	ds_read_b128 v[186:189], v205 offset:17408
	ds_read_b128 v[190:193], v205 offset:18432
	ds_read_b128 v[194:197], v205 offset:19456
	ds_read_b128 v[206:209], v205 offset:20480
	ds_read_b128 v[210:213], v205 offset:21504
	ds_read_b128 v[214:217], v205 offset:22528
	ds_read_b128 v[218:221], v205 offset:23552
	global_load_lds_dwordx4 v[156:157], off
	s_add_i32 m0, s26, 0x2000
	s_add_u32 s26, s44, 0x80000
	v_lshl_add_u64 v[160:161], s[44:45], 0, v[0:1]
	s_addc_u32 s27, s45, 0
	s_add_i32 s30, s31, s61
	global_load_lds_dwordx4 v[160:161], off
	v_lshl_add_u64 v[162:163], s[26:27], 0, v[166:167]
	s_mov_b32 m0, s30
	v_lshl_add_u64 v[222:223], s[58:59], 0, v[164:165]
	global_load_lds_dwordx4 v[162:163], off
	v_lshl_add_u64 v[162:163], s[26:27], 0, v[0:1]
	s_add_i32 m0, s30, 0x2000
	s_nop 0
	global_load_lds_dwordx4 v[162:163], off
	v_lshl_add_u64 v[162:163], s[58:59], 0, v[168:169]
	s_mov_b32 m0, s62
	s_nop 0
	global_load_lds_dwordx4 v[162:163], off
	s_mov_b32 m0, s63
	s_nop 0
	global_load_lds_dwordx4 v[222:223], off
	s_waitcnt vmcnt(8)
	s_waitcnt lgkmcnt(0)
	s_barrier
; #define PG8_STAGE(bufoff, gbase, voff) do { _Pragma("unroll") for (int _i = 0; _i < 2; ++_i) \
;         __builtin_amdgcn_global_load_lds((const unsigned*)((const char*)(gbase) + (voff)[_i]), (LAS unsigned*)(lds + (bufoff) + ldsw + _i * 8192), 16, 0, 0); } while (0)
; #define PG8_LDA(dst, b, h) do { _Pragma("unroll") for (int m = 0; m < 4; ++m) _Pragma("unroll") for (int k = 0; k < 2; ++k) dst[m][k] = *(const LAS bf16x8*)(lds + PG8_SA(b, h) + aoff + m * 2048 + k * 1024); } while (0)
; #define PG8_LDB(dst, b, h) do { _Pragma("unroll") for (int n = 0; n < 2; ++n) _Pragma("unroll") for (int k = 0; k < 2; ++k) dst[n][k] = *(const LAS bf16x8*)(lds + PG8_SB(b, h) + boff + n * 2048 + k * 1024); } while (0)
; #define PG8_MMA(ai, bj, At, Bt) do { __builtin_amdgcn_s_setprio(1); _Pragma("unroll") for (int m = 0; m < 4; ++m) _Pragma("unroll") for (int n = 0; n < 2; ++n) _Pragma("unroll") for (int k = 0; k < 2; ++k) \
;         acc[ai][bj][m][n] = __builtin_amdgcn_mfma_f32_16x16x32_bf16(Bt[n][k], At[m][k], acc[ai][bj][m][n], 0, 0, 0); __builtin_amdgcn_s_setprio(0); } while (0)
; #define PG8_WAIT_V(n) asm volatile("s_waitcnt vmcnt(" #n ")" ::: "memory")
; #define PG8_WAIT_L(n) asm volatile("s_waitcnt lgkmcnt(" #n ")" ::: "memory")
; #define PG8_BAR __builtin_amdgcn_s_barrier()
; #define PG8_SCHED __builtin_amdgcn_sched_barrier(0)
; template <class Epi, class Sched, bool ALIGN_EPI = true>
; __device__ __forceinline__ void gemm_phase(LAS unsigned char* lds, const Gemm g, const Sched& S, const Epi& E) {
;     ...
;             PG8_LDB(B0, 0, 0); PG8_LDB(B1, 0, 1); PG8_SCHED; PG8_LDA(At, 0, 0); PG8_STAGE(PG8_SA(1, 1), a1 + hA, voffA);
;             PG8_WAIT_V(8); PG8_WAIT_L(0); PG8_BAR; PG8_MMA(0, 0, At, B0); PG8_MMA(0, 1, At, B1); PG8_BAR; PG8_SCHED;
;             PG8_LDA(At, 0, 1); PG8_STAGE(PG8_SB(0, 0), b2, voffB); PG8_STAGE(PG8_SB(0, 1), b2 + hB, voffB); PG8_STAGE(PG8_SA(0, 0), a2, voffA);
;             PG8_WAIT_V(8); PG8_WAIT_L(0); PG8_BAR; PG8_MMA(1, 0, At, B0); PG8_MMA(1, 1, At, B1); PG8_BAR; PG8_SCHED;
;             PG8_LDB(B0, 1, 0); PG8_LDB(B1, 1, 1); PG8_SCHED; PG8_LDA(At, 1, 0); PG8_STAGE(PG8_SA(0, 1), a2 + hA, voffA);
;             PG8_WAIT_V(8); PG8_WAIT_L(0); PG8_BAR; PG8_MMA(0, 0, At, B0); PG8_MMA(0, 1, At, B1); PG8_BAR; PG8_SCHED;
	s_setprio 1
	s_waitcnt lgkmcnt(0)
	v_mfma_f32_16x16x32_bf16 v[60:63], v[132:135], v[182:185], v[60:63]
	v_mfma_f32_16x16x32_bf16 v[68:71], v[140:143], v[182:185], v[68:71]
	v_mfma_f32_16x16x32_bf16 v[40:43], v[132:135], v[190:193], v[40:43]
	v_mfma_f32_16x16x32_bf16 v[64:67], v[140:143], v[190:193], v[64:67]
	v_mfma_f32_16x16x32_bf16 v[24:27], v[132:135], v[206:209], v[24:27]
	v_mfma_f32_16x16x32_bf16 v[56:59], v[140:143], v[206:209], v[56:59]
	v_mfma_f32_16x16x32_bf16 v[12:15], v[132:135], v[214:217], v[12:15]
	v_mfma_f32_16x16x32_bf16 v[48:51], v[140:143], v[214:217], v[48:51]
	v_mfma_f32_16x16x32_bf16 v[60:63], v[136:139], v[186:189], v[60:63]
	v_mfma_f32_16x16x32_bf16 v[68:71], v[144:147], v[186:189], v[68:71]
	v_mfma_f32_16x16x32_bf16 v[40:43], v[136:139], v[194:197], v[40:43]
	v_mfma_f32_16x16x32_bf16 v[64:67], v[144:147], v[194:197], v[64:67]
	v_mfma_f32_16x16x32_bf16 v[24:27], v[136:139], v[210:213], v[24:27]
	v_mfma_f32_16x16x32_bf16 v[56:59], v[144:147], v[210:213], v[56:59]
	v_mfma_f32_16x16x32_bf16 v[12:15], v[136:139], v[218:221], v[12:15]
	v_mfma_f32_16x16x32_bf16 v[48:51], v[144:147], v[218:221], v[48:51]
	s_setprio 0
	s_setprio 1
	v_mfma_f32_16x16x32_bf16 v[104:107], v[148:151], v[182:185], v[104:107]
	v_mfma_f32_16x16x32_bf16 v[20:23], v[174:177], v[182:185], v[20:23]
	v_mfma_f32_16x16x32_bf16 v[92:95], v[148:151], v[190:193], v[92:95]
	v_mfma_f32_16x16x32_bf16 v[16:19], v[174:177], v[190:193], v[16:19]
	v_mfma_f32_16x16x32_bf16 v[76:79], v[148:151], v[206:209], v[76:79]
	v_mfma_f32_16x16x32_bf16 v[8:11], v[174:177], v[206:209], v[8:11]
	v_mfma_f32_16x16x32_bf16 v[52:55], v[148:151], v[214:217], v[52:55]
	v_mfma_f32_16x16x32_bf16 v[4:7], v[174:177], v[214:217], v[4:7]
	v_mfma_f32_16x16x32_bf16 v[104:107], v[152:155], v[186:189], v[104:107]
	v_mfma_f32_16x16x32_bf16 v[20:23], v[178:181], v[186:189], v[20:23]
	v_mfma_f32_16x16x32_bf16 v[92:95], v[152:155], v[194:197], v[92:95]
	v_mfma_f32_16x16x32_bf16 v[16:19], v[178:181], v[194:197], v[16:19]
	v_mfma_f32_16x16x32_bf16 v[76:79], v[152:155], v[210:213], v[76:79]
	v_mfma_f32_16x16x32_bf16 v[8:11], v[178:181], v[210:213], v[8:11]
	v_mfma_f32_16x16x32_bf16 v[52:55], v[152:155], v[218:221], v[52:55]
	v_mfma_f32_16x16x32_bf16 v[4:7], v[178:181], v[218:221], v[4:7]
	s_setprio 0
	s_barrier
	s_add_i32 s30, 0, 0x18000
	v_add_u32_e32 v2, s30, v204
	s_add_i32 s31, 0, 0x1c000
	ds_read_b128 v[132:135], v2
	ds_read_b128 v[136:139], v2 offset:1024
	ds_read_b128 v[140:143], v2 offset:2048
	ds_read_b128 v[144:147], v2 offset:3072
	v_add_u32_e32 v2, s31, v204
	ds_read_b128 v[148:151], v2
	ds_read_b128 v[152:155], v2 offset:1024
	ds_read_b128 v[174:177], v2 offset:2048
	ds_read_b128 v[178:181], v2 offset:3072
	s_add_u32 s26, s58, 0x80000
	s_addc_u32 s27, s59, 0
	s_mov_b32 m0, s64
	v_lshl_add_u64 v[224:225], s[26:27], 0, v[168:169]
	ds_read_b128 v[182:185], v205 offset:32768
	ds_read_b128 v[186:189], v205 offset:33792
	ds_read_b128 v[190:193], v205 offset:34816
	ds_read_b128 v[194:197], v205 offset:35840
	ds_read_b128 v[206:209], v205 offset:36864
	ds_read_b128 v[210:213], v205 offset:37888
	ds_read_b128 v[214:217], v205 offset:38912
	ds_read_b128 v[218:221], v205 offset:39936
	global_load_lds_dwordx4 v[224:225], off
	v_lshl_add_u64 v[224:225], s[26:27], 0, v[164:165]
	s_mov_b32 m0, s65
	s_nop 0
	global_load_lds_dwordx4 v[224:225], off
	s_waitcnt vmcnt(8)
	s_waitcnt lgkmcnt(0)
	s_barrier
	s_setprio 1
	s_waitcnt lgkmcnt(0)
	v_mfma_f32_16x16x32_bf16 v[116:119], v[132:135], v[182:185], v[116:119]
	v_mfma_f32_16x16x32_bf16 v[100:103], v[140:143], v[182:185], v[100:103]
	v_mfma_f32_16x16x32_bf16 v[108:111], v[132:135], v[190:193], v[108:111]
	v_mfma_f32_16x16x32_bf16 v[96:99], v[140:143], v[190:193], v[96:99]
	v_mfma_f32_16x16x32_bf16 v[88:91], v[132:135], v[206:209], v[88:91]
	v_mfma_f32_16x16x32_bf16 v[84:87], v[140:143], v[206:209], v[84:87]
	v_mfma_f32_16x16x32_bf16 v[72:75], v[132:135], v[214:217], v[72:75]
	v_mfma_f32_16x16x32_bf16 v[80:83], v[140:143], v[214:217], v[80:83]
	v_mfma_f32_16x16x32_bf16 v[116:119], v[136:139], v[186:189], v[116:119]
	v_mfma_f32_16x16x32_bf16 v[100:103], v[144:147], v[186:189], v[100:103]
	v_mfma_f32_16x16x32_bf16 v[108:111], v[136:139], v[194:197], v[108:111]
	v_mfma_f32_16x16x32_bf16 v[96:99], v[144:147], v[194:197], v[96:99]
	v_mfma_f32_16x16x32_bf16 v[88:91], v[136:139], v[210:213], v[88:91]
	v_mfma_f32_16x16x32_bf16 v[84:87], v[144:147], v[210:213], v[84:87]
	v_mfma_f32_16x16x32_bf16 v[72:75], v[136:139], v[218:221], v[72:75]
	v_mfma_f32_16x16x32_bf16 v[80:83], v[144:147], v[218:221], v[80:83]
	s_setprio 0
	s_setprio 1
	v_mfma_f32_16x16x32_bf16 v[128:131], v[148:151], v[182:185], v[128:131]
	v_mfma_f32_16x16x32_bf16 v[44:47], v[174:177], v[182:185], v[44:47]
	v_mfma_f32_16x16x32_bf16 v[124:127], v[148:151], v[190:193], v[124:127]
	v_mfma_f32_16x16x32_bf16 v[36:39], v[174:177], v[190:193], v[36:39]
	v_mfma_f32_16x16x32_bf16 v[120:123], v[148:151], v[206:209], v[120:123]
	v_mfma_f32_16x16x32_bf16 v[32:35], v[174:177], v[206:209], v[32:35]
	v_mfma_f32_16x16x32_bf16 v[112:115], v[148:151], v[214:217], v[112:115]
	v_mfma_f32_16x16x32_bf16 v[28:31], v[174:177], v[214:217], v[28:31]
	v_mfma_f32_16x16x32_bf16 v[128:131], v[152:155], v[186:189], v[128:131]
	v_mfma_f32_16x16x32_bf16 v[44:47], v[178:181], v[186:189], v[44:47]
	v_mfma_f32_16x16x32_bf16 v[124:127], v[152:155], v[194:197], v[124:127]
	v_mfma_f32_16x16x32_bf16 v[36:39], v[178:181], v[194:197], v[36:39]
	v_mfma_f32_16x16x32_bf16 v[120:123], v[152:155], v[210:213], v[120:123]
	v_mfma_f32_16x16x32_bf16 v[32:35], v[178:181], v[210:213], v[32:35]
	v_mfma_f32_16x16x32_bf16 v[112:115], v[152:155], v[218:221], v[112:115]
	v_mfma_f32_16x16x32_bf16 v[28:31], v[178:181], v[218:221], v[28:31]
	s_setprio 0
	s_barrier
; #define LAS __attribute__((address_space(3)))
; #define PG8_STAGE(bufoff, gbase, voff) do { _Pragma("unroll") for (int _i = 0; _i < 2; ++_i) \
;         __builtin_amdgcn_global_load_lds((const unsigned*)((const char*)(gbase) + (voff)[_i]), (LAS unsigned*)(lds + (bufoff) + ldsw + _i * 8192), 16, 0, 0); } while (0)
; #define PG8_LDA(dst, b, h) do { _Pragma("unroll") for (int m = 0; m < 4; ++m) _Pragma("unroll") for (int k = 0; k < 2; ++k) dst[m][k] = *(const LAS bf16x8*)(lds + PG8_SA(b, h) + aoff + m * 2048 + k * 1024); } while (0)
; #define PG8_WAIT_V(n) asm volatile("s_waitcnt vmcnt(" #n ")" ::: "memory")
; #define PG8_WAIT_L(n) asm volatile("s_waitcnt lgkmcnt(" #n ")" ::: "memory")
;     __device__ __forceinline__ void operator()(f32x4 (&acc)[2][2][4][2], const Unit& u, int wr, int wc, int fr_, int fq_, int wid, int lane_) const {
;         int lane = lane_; asm volatile("" : "+v"(lane));
;         const int fr = lane & 15, fq = lane >> 4;
;         const int cl = 32 * wc + 8 * fq;
;         LAS float* wl = xbuf + 2048;
;         {
;             const int t = wid * 64 + lane, kind = t >> 6, pr = t & 63, bj = kind >> 2, tap = kind & 3;
;             const float* src = (tap < 3) ? (cw + (size_t)tap * FF2 + bj * FF + u.pn * 128 + 2 * pr) : (cb + bj * FF + u.pn * 128 + 2 * pr);
;             const f32x2 wv = *(const f32x2*)src;
;             if (fr >= 14) {
;                 unsigned xo = (unsigned)(wr * 512 + (fr - 14) * 128 + cl) * 4u; asm volatile("" : "+v"(xo));
;                 LAS unsigned char* xb = (LAS unsigned char*)xbuf + xo;
; #pragma unroll
;                 for (int ai = 0; ai < 2; ++ai)
; #pragma unroll
;                     for (int bj2 = 0; bj2 < 2; ++bj2)
; #pragma unroll
;                         for (int n = 0; n < 2; ++n) *(LAS f32x4*)(xb + (ai * 1024 + bj2 * 256 + 4 * n) * 4) = acc[ai][bj2][3][n];
; template <class Epi, class Sched, bool ALIGN_EPI = true>
; __device__ __forceinline__ void gemm_phase(LAS unsigned char* lds, const Gemm g, const Sched& S, const Epi& E) {
;     ...
;             PG8_LDA(At, 1, 1); PG8_STAGE(PG8_SB(1, 0), b3, voffB); PG8_STAGE(PG8_SB(1, 1), b3 + hB, voffB); PG8_STAGE(PG8_SA(1, 0), a3, voffA);
;             PG8_WAIT_V(8); PG8_WAIT_L(0); PG8_BAR; PG8_MMA(1, 0, At, B0); PG8_MMA(1, 1, At, B1); PG8_BAR; PG8_SCHED;
;         }
;         if constexpr (ALIGN_EPI) { if (wr == 0) PG8_BAR; }
	s_add_i32 s26, s30, s61
	v_lshl_add_u64 v[156:157], v[156:157], 0, s[86:87]
	s_mov_b32 m0, s26
	ds_read_b128 v[182:185], v205 offset:49152
	ds_read_b128 v[186:189], v205 offset:50176
	ds_read_b128 v[190:193], v205 offset:51200
	ds_read_b128 v[194:197], v205 offset:52224
	ds_read_b128 v[206:209], v205 offset:53248
	ds_read_b128 v[210:213], v205 offset:54272
	ds_read_b128 v[214:217], v205 offset:55296
	ds_read_b128 v[218:221], v205 offset:56320
	global_load_lds_dwordx4 v[156:157], off
	s_add_i32 m0, s26, 0x2000
	s_add_u32 s26, s44, 0x80080
	v_lshl_add_u64 v[156:157], v[160:161], 0, s[86:87]
	s_addc_u32 s27, s45, 0
	s_add_i32 s30, s31, s61
	global_load_lds_dwordx4 v[156:157], off
	v_lshl_add_u64 v[156:157], s[26:27], 0, v[166:167]
	s_mov_b32 m0, s30
	s_nop 0
	global_load_lds_dwordx4 v[156:157], off
	v_lshl_add_u64 v[156:157], s[26:27], 0, v[0:1]
	s_add_i32 m0, s30, 0x2000
	s_nop 0
	global_load_lds_dwordx4 v[156:157], off
	v_lshl_add_u64 v[156:157], v[162:163], 0, s[86:87]
	s_mov_b32 m0, s75
	s_nop 0
	global_load_lds_dwordx4 v[156:157], off
	v_lshl_add_u64 v[156:157], v[222:223], 0, s[86:87]
	s_mov_b32 m0, s76
	s_nop 0
	global_load_lds_dwordx4 v[156:157], off
	s_waitcnt vmcnt(8)
	s_waitcnt lgkmcnt(0)
	s_barrier
	s_setprio 1
	s_waitcnt lgkmcnt(0)
	v_mfma_f32_16x16x32_bf16 v[60:63], v[132:135], v[182:185], v[60:63]
	v_mfma_f32_16x16x32_bf16 v[68:71], v[140:143], v[182:185], v[68:71]
	v_mfma_f32_16x16x32_bf16 v[40:43], v[132:135], v[190:193], v[40:43]
	v_mfma_f32_16x16x32_bf16 v[64:67], v[140:143], v[190:193], v[64:67]
	v_mfma_f32_16x16x32_bf16 v[24:27], v[132:135], v[206:209], v[24:27]
	v_mfma_f32_16x16x32_bf16 v[56:59], v[140:143], v[206:209], v[56:59]
	v_mfma_f32_16x16x32_bf16 v[12:15], v[132:135], v[214:217], v[12:15]
	v_mfma_f32_16x16x32_bf16 v[48:51], v[140:143], v[214:217], v[48:51]
	v_mfma_f32_16x16x32_bf16 v[60:63], v[136:139], v[186:189], v[60:63]
	v_mfma_f32_16x16x32_bf16 v[68:71], v[144:147], v[186:189], v[68:71]
	v_mfma_f32_16x16x32_bf16 v[40:43], v[136:139], v[194:197], v[40:43]
	v_mfma_f32_16x16x32_bf16 v[64:67], v[144:147], v[194:197], v[64:67]
	v_mfma_f32_16x16x32_bf16 v[24:27], v[136:139], v[210:213], v[24:27]
	v_mfma_f32_16x16x32_bf16 v[56:59], v[144:147], v[210:213], v[56:59]
	v_mfma_f32_16x16x32_bf16 v[12:15], v[136:139], v[218:221], v[12:15]
	v_mfma_f32_16x16x32_bf16 v[48:51], v[144:147], v[218:221], v[48:51]
	s_setprio 0
	s_setprio 1
	v_mfma_f32_16x16x32_bf16 v[104:107], v[148:151], v[182:185], v[104:107]
	v_mfma_f32_16x16x32_bf16 v[20:23], v[174:177], v[182:185], v[20:23]
	v_mfma_f32_16x16x32_bf16 v[92:95], v[148:151], v[190:193], v[92:95]
	v_mfma_f32_16x16x32_bf16 v[16:19], v[174:177], v[190:193], v[16:19]
	v_mfma_f32_16x16x32_bf16 v[76:79], v[148:151], v[206:209], v[76:79]
	v_mfma_f32_16x16x32_bf16 v[8:11], v[174:177], v[206:209], v[8:11]
	v_mfma_f32_16x16x32_bf16 v[52:55], v[148:151], v[214:217], v[52:55]
	v_mfma_f32_16x16x32_bf16 v[4:7], v[174:177], v[214:217], v[4:7]
	v_mfma_f32_16x16x32_bf16 v[104:107], v[152:155], v[186:189], v[104:107]
	v_mfma_f32_16x16x32_bf16 v[20:23], v[178:181], v[186:189], v[20:23]
	v_mfma_f32_16x16x32_bf16 v[92:95], v[152:155], v[194:197], v[92:95]
	v_mfma_f32_16x16x32_bf16 v[16:19], v[178:181], v[194:197], v[16:19]
	v_mfma_f32_16x16x32_bf16 v[76:79], v[152:155], v[210:213], v[76:79]
	v_mfma_f32_16x16x32_bf16 v[8:11], v[178:181], v[210:213], v[8:11]
	v_mfma_f32_16x16x32_bf16 v[52:55], v[152:155], v[218:221], v[52:55]
	v_mfma_f32_16x16x32_bf16 v[4:7], v[178:181], v[218:221], v[4:7]
	s_setprio 0
	s_barrier
	s_add_i32 s25, s25, 2
	s_add_u32 s6, s6, 0x100
	s_addc_u32 s7, s7, 0
	s_add_u32 s19, s19, 0x100
	s_addc_u32 s24, s24, 0
	s_cmp_gt_u32 s25, 29
	s_cbranch_scc0 .LBB0_828
	s_and_b64 vcc, exec, s[12:13]
	s_cbranch_vccz .LBB0_831
	s_barrier
.LBB0_831:
	v_mov_b32_e32 v134, v158
	s_lshl_b32 s44, s82, 7
	v_add_u32_e32 v2, s77, v134
	v_ashrrev_i32_e32 v135, 6, v2
	v_and_b32_e32 v137, 3, v135
	v_lshrrev_b32_e32 v136, 8, v2
	v_mul_u32_u24_e32 v2, 0x2c00, v137
	v_lshlrev_b32_e32 v2, 2, v2
	v_lshl_add_u64 v[132:133], s[2:3], 0, v[2:3]
	v_mov_b32_e32 v2, s9
	v_cmp_eq_u32_e32 vcc, 3, v137
	v_mul_i32_i24_e32 v136, 0x1600, v136
	v_ashrrev_i32_e32 v137, 31, v136
	v_cndmask_b32_e32 v133, v133, v2, vcc
	v_mov_b32_e32 v2, s8
	v_cndmask_b32_e32 v132, v132, v2, vcc
	v_and_b32_e32 v138, 63, v134
	v_lshl_add_u64 v[132:133], v[136:137], 2, v[132:133]
	s_ashr_i32 s45, s44, 31
	v_lshl_add_u64 v[132:133], s[44:45], 2, v[132:133]
	v_lshlrev_b32_e32 v2, 3, v138
	v_lshl_add_u64 v[132:133], v[132:133], 0, v[2:3]
	v_ashrrev_i32_e32 v136, 1, v134
	v_and_b32_e32 v206, 15, v134
	v_and_b32_e32 v136, -8, v136
	v_add_u32_e32 v174, s67, v136
	v_cmp_lt_u32_e32 vcc, 13, v206
	s_and_saveexec_b64 s[6:7], vcc
	s_cbranch_execz .LBB0_833
	v_lshl_add_u32 v136, v206, 7, s78
	v_add_lshl_u32 v136, v136, v174, 2
	s_nop 0
	v_add_u32_e32 v136, 0, v136
	v_add_u32_e32 v136, 0x20000, v136
	ds_write_b128 v136, v[72:75]
	ds_write_b128 v136, v[80:83] offset:16
	ds_write_b128 v136, v[112:115] offset:1024
	ds_write_b128 v136, v[28:31] offset:1040
	ds_write_b128 v136, v[12:15] offset:4096
	ds_write_b128 v136, v[48:51] offset:4112
	ds_write_b128 v136, v[52:55] offset:5120
	ds_write_b128 v136, v[4:7] offset:5136

; #define LAS __attribute__((address_space(3)))
;     __device__ __forceinline__ void operator()(f32x4 (&acc)[2][2][4][2], const Unit& u, int wr, int wc, int fr_, int fq_, int wid, int lane_) const {
;     ...
;             *(LAS f32x2*)(wl + kind * 128 + 2 * pr) = wv;
;         }
;         asm volatile("s_waitcnt lgkmcnt(0)" ::: "memory"); __builtin_amdgcn_s_barrier(); asm volatile("" ::: "memory");
;         const int row0 = u.pm * BM + wr * 64 + fr;
;         const float k1a = fr >= 1 ? 1.f : 0.f, k1b = 1.f - k1a, k0a = fr >= 2 ? 1.f : 0.f, k0b = 1.f - k0a;
; #pragma unroll
;         for (int n = 0; n < 2; ++n)
; #pragma unroll
;             for (int bj = 0; bj < 2; ++bj) {
;                 const LAS float* wp = wl + bj * 512 + cl + 4 * n;
;                 const f32x4 t0 = *(const LAS f32x4*)wp, t1 = *(const LAS f32x4*)(wp + 128), w2 = *(const LAS f32x4*)(wp + 256), bb = *(const LAS f32x4*)(wp + 384);
.LBB0_837:
	s_or_b64 exec, exec, s[6:7]
	v_lshlrev_b32_e32 v135, 9, v135
	v_add3_u32 v2, s51, v135, v2
	ds_write_b64 v2, v[226:227]
	s_waitcnt lgkmcnt(0)
	s_barrier
	v_lshl_add_u32 v175, v174, 2, s51
	v_lshlrev_b32_e32 v2, 7, v134
	ds_read_b128 v[150:153], v175
	ds_read_b128 v[154:157], v175 offset:512
	ds_read_b128 v[134:137], v175 offset:1024
	ds_read_b128 v[138:141], v175 offset:1536
	v_cndmask_b32_e64 v133, 0, 1, s[10:11]
	v_and_b32_e32 v2, 0x80, v2
	v_mov_b32_e32 v132, 0
	s_mov_b32 s15, 0
	v_cmp_ne_u32_e64 s[6:7], 1, v133
	s_andn2_b64 vcc, exec, s[10:11]
	s_mov_b32 s16, 0
	v_mov_b32_e32 v146, 0
	v_mov_b32_e32 v147, 0
	v_mov_b32_e32 v148, 0
	v_mov_b32_e32 v149, 0
	v_mov_b32_e32 v142, 0
	v_mov_b32_e32 v143, 0
	v_mov_b32_e32 v144, 0
	v_mov_b32_e32 v145, 0
	s_cbranch_vccnz .LBB0_839
	s_add_i32 s16, 0, 0x20000
	v_lshl_add_u32 v133, v174, 2, s16
	v_lshl_add_u32 v142, v2, 2, v133
	ds_read_b128 v[146:149], v133 offset:512
	ds_read_b128 v[142:145], v142
	s_mov_b32 s16, 2

; #define PG8_STAGE(bufoff, gbase, voff) do { _Pragma("unroll") for (int _i = 0; _i < 2; ++_i) \
;         __builtin_amdgcn_global_load_lds((const unsigned*)((const char*)(gbase) + (voff)[_i]), (LAS unsigned*)(lds + (bufoff) + ldsw + _i * 8192), 16, 0, 0); } while (0)
; #define PG8_LDA(dst, b, h) do { _Pragma("unroll") for (int m = 0; m < 4; ++m) _Pragma("unroll") for (int k = 0; k < 2; ++k) dst[m][k] = *(const LAS bf16x8*)(lds + PG8_SA(b, h) + aoff + m * 2048 + k * 1024); } while (0)
; #define PG8_LDB(dst, b, h) do { _Pragma("unroll") for (int n = 0; n < 2; ++n) _Pragma("unroll") for (int k = 0; k < 2; ++k) dst[n][k] = *(const LAS bf16x8*)(lds + PG8_SB(b, h) + boff + n * 2048 + k * 1024); } while (0)
; #define PG8_WAIT_V(n) asm volatile("s_waitcnt vmcnt(" #n ")" ::: "memory")
; #define PG8_BAR __builtin_amdgcn_s_barrier()
; template <class Epi, class Sched, bool ALIGN_EPI = true>
; __device__ __forceinline__ void gemm_phase(LAS unsigned char* lds, const Gemm g, const Sched& S, const Epi& E) {
;     ...
;         for (int t = 0; t < nt; t += 2) {
;             const bool last = (t == nt - 2);
;             const char* a1 = cA + (size_t)(t + 1) * kstep;
;             const char* a2 = last ? nA : cA + (size_t)(t + 2) * kstep; const char* b2 = last ? nB : cB + (size_t)(t + 2) * kstep;
;             const char* a3 = a2 + kstep; const char* b3 = b2 + kstep;
;             PG8_LDB(B0, 0, 0); PG8_LDB(B1, 0, 1); PG8_SCHED; PG8_LDA(At, 0, 0); PG8_STAGE(PG8_SA(1, 1), a1 + hA, voffA);
;             PG8_WAIT_V(8); PG8_WAIT_L(0); PG8_BAR; PG8_MMA(0, 0, At, B0); PG8_MMA(0, 1, At, B1); PG8_BAR; PG8_SCHED;
;             PG8_LDA(At, 0, 1); PG8_STAGE(PG8_SB(0, 0), b2, voffB); PG8_STAGE(PG8_SB(0, 1), b2 + hB, voffB); PG8_STAGE(PG8_SA(0, 0), a2, voffA);
;             PG8_WAIT_V(8); PG8_WAIT_L(0); PG8_BAR; PG8_MMA(1, 0, At, B0); PG8_MMA(1, 1, At, B1); PG8_BAR; PG8_SCHED;
;             PG8_LDB(B0, 1, 0); PG8_LDB(B1, 1, 1); PG8_SCHED; PG8_LDA(At, 1, 0); PG8_STAGE(PG8_SA(0, 1), a2 + hA, voffA);
;             PG8_WAIT_V(8); PG8_WAIT_L(0); PG8_BAR; PG8_MMA(0, 0, At, B0); PG8_MMA(0, 1, At, B1); PG8_BAR; PG8_SCHED;
;             PG8_LDA(At, 1, 1); PG8_STAGE(PG8_SB(1, 0), b3, voffB); PG8_STAGE(PG8_SB(1, 1), b3 + hB, voffB); PG8_STAGE(PG8_SA(1, 0), a3, voffA);
;             PG8_WAIT_V(8); PG8_WAIT_L(0); PG8_BAR; PG8_MMA(1, 0, At, B0); PG8_MMA(1, 1, At, B1); PG8_BAR; PG8_SCHED;
.LBB0_1111:
	s_add_u32 vcc_lo, s10, 0x100
	s_addc_u32 vcc_hi, s11, 0
	s_add_u32 s19, s16, s10
	s_addc_u32 s24, s17, s11
	s_add_i32 s25, 0, 0x10000
	s_cmpk_eq_i32 s18, 0x54
	s_cselect_b32 s65, s61, s24
	s_cselect_b32 s24, 0, vcc_lo
	s_cselect_b32 s64, s60, s19
	s_cselect_b32 s19, 0, vcc_hi
	s_add_u32 s62, s2, s24
	v_add_u32_e32 v160, s25, v188
	s_addc_u32 s63, s3, s19
	s_add_i32 s19, 0, 0x14000
	ds_read_b128 v[136:139], v160
	ds_read_b128 v[140:143], v160 offset:1024
	ds_read_b128 v[144:147], v160 offset:2048
	ds_read_b128 v[172:175], v160 offset:3072
	v_add_u32_e32 v160, s19, v188
	ds_read_b128 v[176:179], v160
	ds_read_b128 v[180:183], v160 offset:1024
	ds_read_b128 v[184:187], v160 offset:2048
	ds_read_b128 v[208:211], v160 offset:3072
	v_lshl_add_u64 v[160:161], v[132:133], 0, s[10:11]
	s_add_i32 m0, s67, 0xc000
	ds_read_b128 v[212:215], v197
	ds_read_b128 v[216:219], v197 offset:1024
	ds_read_b128 v[220:223], v197 offset:2048
	ds_read_b128 v[224:227], v197 offset:3072
	ds_read_b128 v[228:231], v197 offset:4096
	ds_read_b128 v[232:235], v197 offset:5120
	ds_read_b128 v[236:239], v197 offset:6144
	ds_read_b128 v[240:243], v197 offset:7168
	global_load_lds_dwordx4 v[160:161], off
	v_lshl_add_u64 v[160:161], v[134:135], 0, s[10:11]
	s_add_i32 m0, s67, 0xe000
	s_nop 0
	global_load_lds_dwordx4 v[160:161], off
	s_waitcnt vmcnt(8)
	s_waitcnt lgkmcnt(0)
	s_barrier
	s_setprio 1
	s_waitcnt lgkmcnt(0)
	v_mfma_f32_16x16x32_bf16 v[16:19], v[136:139], v[212:215], v[16:19]
	v_mfma_f32_16x16x32_bf16 v[12:15], v[144:147], v[212:215], v[12:15]
	v_mfma_f32_16x16x32_bf16 v[56:59], v[136:139], v[220:223], v[56:59]
	v_mfma_f32_16x16x32_bf16 v[52:55], v[144:147], v[220:223], v[52:55]
	v_mfma_f32_16x16x32_bf16 v[88:91], v[136:139], v[228:231], v[88:91]
	v_mfma_f32_16x16x32_bf16 v[76:79], v[144:147], v[228:231], v[76:79]
	v_mfma_f32_16x16x32_bf16 v[112:115], v[136:139], v[236:239], v[112:115]
	v_mfma_f32_16x16x32_bf16 v[108:111], v[144:147], v[236:239], v[108:111]
	v_mfma_f32_16x16x32_bf16 v[16:19], v[140:143], v[216:219], v[16:19]
	v_mfma_f32_16x16x32_bf16 v[12:15], v[172:175], v[216:219], v[12:15]
	v_mfma_f32_16x16x32_bf16 v[56:59], v[140:143], v[224:227], v[56:59]
	v_mfma_f32_16x16x32_bf16 v[52:55], v[172:175], v[224:227], v[52:55]
	v_mfma_f32_16x16x32_bf16 v[88:91], v[140:143], v[232:235], v[88:91]
	v_mfma_f32_16x16x32_bf16 v[76:79], v[172:175], v[232:235], v[76:79]
	v_mfma_f32_16x16x32_bf16 v[112:115], v[140:143], v[240:243], v[112:115]
	v_mfma_f32_16x16x32_bf16 v[108:111], v[172:175], v[240:243], v[108:111]
	s_setprio 0
	s_setprio 1
	v_mfma_f32_16x16x32_bf16 v[8:11], v[176:179], v[212:215], v[8:11]
	v_mfma_f32_16x16x32_bf16 v[4:7], v[184:187], v[212:215], v[4:7]
	v_mfma_f32_16x16x32_bf16 v[40:43], v[176:179], v[220:223], v[40:43]
	v_mfma_f32_16x16x32_bf16 v[36:39], v[184:187], v[220:223], v[36:39]
	v_mfma_f32_16x16x32_bf16 v[64:67], v[176:179], v[228:231], v[64:67]
	v_mfma_f32_16x16x32_bf16 v[60:63], v[184:187], v[228:231], v[60:63]
	v_mfma_f32_16x16x32_bf16 v[96:99], v[176:179], v[236:239], v[96:99]
	v_mfma_f32_16x16x32_bf16 v[92:95], v[184:187], v[236:239], v[92:95]
	v_mfma_f32_16x16x32_bf16 v[8:11], v[180:183], v[216:219], v[8:11]
	v_mfma_f32_16x16x32_bf16 v[4:7], v[208:211], v[216:219], v[4:7]
	v_mfma_f32_16x16x32_bf16 v[40:43], v[180:183], v[224:227], v[40:43]
	v_mfma_f32_16x16x32_bf16 v[36:39], v[208:211], v[224:227], v[36:39]
	v_mfma_f32_16x16x32_bf16 v[64:67], v[180:183], v[232:235], v[64:67]
	v_mfma_f32_16x16x32_bf16 v[60:63], v[208:211], v[232:235], v[60:63]
	v_mfma_f32_16x16x32_bf16 v[96:99], v[180:183], v[240:243], v[96:99]
	v_mfma_f32_16x16x32_bf16 v[92:95], v[208:211], v[240:243], v[92:95]
	s_setprio 0
	s_barrier
	s_add_i32 s10, s25, s66
	v_lshl_add_u64 v[160:161], s[62:63], 0, v[2:3]
	s_mov_b32 m0, s10
	ds_read_b128 v[212:215], v197 offset:16384
	ds_read_b128 v[216:219], v197 offset:17408
	ds_read_b128 v[220:223], v197 offset:18432
	ds_read_b128 v[224:227], v197 offset:19456
	ds_read_b128 v[228:231], v197 offset:20480
	ds_read_b128 v[232:235], v197 offset:21504
	ds_read_b128 v[236:239], v197 offset:22528
	ds_read_b128 v[240:243], v197 offset:23552
	global_load_lds_dwordx4 v[160:161], off
	s_add_i32 m0, s10, 0x2000
	s_add_u32 s10, s62, 0x160000
	v_lshl_add_u64 v[162:163], s[62:63], 0, v[150:151]
	s_addc_u32 s11, s63, 0
	s_add_i32 s19, s19, s66
	global_load_lds_dwordx4 v[162:163], off
	v_lshl_add_u64 v[244:245], s[10:11], 0, v[2:3]
	s_mov_b32 m0, s19
	v_lshl_add_u64 v[246:247], s[64:65], 0, v[148:149]
	global_load_lds_dwordx4 v[244:245], off
	v_lshl_add_u64 v[244:245], s[10:11], 0, v[150:151]
	s_add_i32 m0, s19, 0x2000
	s_nop 0
	global_load_lds_dwordx4 v[244:245], off
	v_lshl_add_u64 v[244:245], s[64:65], 0, v[0:1]
	s_mov_b32 m0, s67
	s_nop 0
	global_load_lds_dwordx4 v[244:245], off
	s_mov_b32 m0, s75
	s_nop 0
	global_load_lds_dwordx4 v[246:247], off
	s_waitcnt vmcnt(8)
	s_waitcnt lgkmcnt(0)
	s_barrier
; #define PG8_STAGE(bufoff, gbase, voff) do { _Pragma("unroll") for (int _i = 0; _i < 2; ++_i) \
;         __builtin_amdgcn_global_load_lds((const unsigned*)((const char*)(gbase) + (voff)[_i]), (LAS unsigned*)(lds + (bufoff) + ldsw + _i * 8192), 16, 0, 0); } while (0)
; #define PG8_LDA(dst, b, h) do { _Pragma("unroll") for (int m = 0; m < 4; ++m) _Pragma("unroll") for (int k = 0; k < 2; ++k) dst[m][k] = *(const LAS bf16x8*)(lds + PG8_SA(b, h) + aoff + m * 2048 + k * 1024); } while (0)
; #define PG8_LDB(dst, b, h) do { _Pragma("unroll") for (int n = 0; n < 2; ++n) _Pragma("unroll") for (int k = 0; k < 2; ++k) dst[n][k] = *(const LAS bf16x8*)(lds + PG8_SB(b, h) + boff + n * 2048 + k * 1024); } while (0)
; #define PG8_MMA(ai, bj, At, Bt) do { __builtin_amdgcn_s_setprio(1); _Pragma("unroll") for (int m = 0; m < 4; ++m) _Pragma("unroll") for (int n = 0; n < 2; ++n) _Pragma("unroll") for (int k = 0; k < 2; ++k) \
;         acc[ai][bj][m][n] = __builtin_amdgcn_mfma_f32_16x16x32_bf16(Bt[n][k], At[m][k], acc[ai][bj][m][n], 0, 0, 0); __builtin_amdgcn_s_setprio(0); } while (0)
; #define PG8_WAIT_V(n) asm volatile("s_waitcnt vmcnt(" #n ")" ::: "memory")
; #define PG8_WAIT_L(n) asm volatile("s_waitcnt lgkmcnt(" #n ")" ::: "memory")
; #define PG8_BAR __builtin_amdgcn_s_barrier()
; #define PG8_SCHED __builtin_amdgcn_sched_barrier(0)
; template <class Epi, class Sched, bool ALIGN_EPI = true>
; __device__ __forceinline__ void gemm_phase(LAS unsigned char* lds, const Gemm g, const Sched& S, const Epi& E) {
;     ...
;             PG8_LDB(B0, 0, 0); PG8_LDB(B1, 0, 1); PG8_SCHED; PG8_LDA(At, 0, 0); PG8_STAGE(PG8_SA(1, 1), a1 + hA, voffA);
;             PG8_WAIT_V(8); PG8_WAIT_L(0); PG8_BAR; PG8_MMA(0, 0, At, B0); PG8_MMA(0, 1, At, B1); PG8_BAR; PG8_SCHED;
;             PG8_LDA(At, 0, 1); PG8_STAGE(PG8_SB(0, 0), b2, voffB); PG8_STAGE(PG8_SB(0, 1), b2 + hB, voffB); PG8_STAGE(PG8_SA(0, 0), a2, voffA);
;             PG8_WAIT_V(8); PG8_WAIT_L(0); PG8_BAR; PG8_MMA(1, 0, At, B0); PG8_MMA(1, 1, At, B1); PG8_BAR; PG8_SCHED;
;             PG8_LDB(B0, 1, 0); PG8_LDB(B1, 1, 1); PG8_SCHED; PG8_LDA(At, 1, 0); PG8_STAGE(PG8_SA(0, 1), a2 + hA, voffA);
;             PG8_WAIT_V(8); PG8_WAIT_L(0); PG8_BAR; PG8_MMA(0, 0, At, B0); PG8_MMA(0, 1, At, B1); PG8_BAR; PG8_SCHED;
	s_setprio 1
	s_waitcnt lgkmcnt(0)
	v_mfma_f32_16x16x32_bf16 v[128:131], v[136:139], v[212:215], v[128:131]
	v_mfma_f32_16x16x32_bf16 v[124:127], v[144:147], v[212:215], v[124:127]
	v_mfma_f32_16x16x32_bf16 v[104:107], v[136:139], v[220:223], v[104:107]
	v_mfma_f32_16x16x32_bf16 v[100:103], v[144:147], v[220:223], v[100:103]
	v_mfma_f32_16x16x32_bf16 v[72:75], v[136:139], v[228:231], v[72:75]
	v_mfma_f32_16x16x32_bf16 v[68:71], v[144:147], v[228:231], v[68:71]
	v_mfma_f32_16x16x32_bf16 v[32:35], v[136:139], v[236:239], v[32:35]
	v_mfma_f32_16x16x32_bf16 v[28:31], v[144:147], v[236:239], v[28:31]
	v_mfma_f32_16x16x32_bf16 v[128:131], v[140:143], v[216:219], v[128:131]
	v_mfma_f32_16x16x32_bf16 v[124:127], v[172:175], v[216:219], v[124:127]
	v_mfma_f32_16x16x32_bf16 v[104:107], v[140:143], v[224:227], v[104:107]
	v_mfma_f32_16x16x32_bf16 v[100:103], v[172:175], v[224:227], v[100:103]
	v_mfma_f32_16x16x32_bf16 v[72:75], v[140:143], v[232:235], v[72:75]
	v_mfma_f32_16x16x32_bf16 v[68:71], v[172:175], v[232:235], v[68:71]
	v_mfma_f32_16x16x32_bf16 v[32:35], v[140:143], v[240:243], v[32:35]
	v_mfma_f32_16x16x32_bf16 v[28:31], v[172:175], v[240:243], v[28:31]
	s_setprio 0
	s_setprio 1
	v_mfma_f32_16x16x32_bf16 v[120:123], v[176:179], v[212:215], v[120:123]
	v_mfma_f32_16x16x32_bf16 v[116:119], v[184:187], v[212:215], v[116:119]
	v_mfma_f32_16x16x32_bf16 v[84:87], v[176:179], v[220:223], v[84:87]
	v_mfma_f32_16x16x32_bf16 v[80:83], v[184:187], v[220:223], v[80:83]
	v_mfma_f32_16x16x32_bf16 v[48:51], v[176:179], v[228:231], v[48:51]
	v_mfma_f32_16x16x32_bf16 v[44:47], v[184:187], v[228:231], v[44:47]
	v_mfma_f32_16x16x32_bf16 v[24:27], v[176:179], v[236:239], v[24:27]
	v_mfma_f32_16x16x32_bf16 v[20:23], v[184:187], v[236:239], v[20:23]
	v_mfma_f32_16x16x32_bf16 v[120:123], v[180:183], v[216:219], v[120:123]
	v_mfma_f32_16x16x32_bf16 v[116:119], v[208:211], v[216:219], v[116:119]
	v_mfma_f32_16x16x32_bf16 v[84:87], v[180:183], v[224:227], v[84:87]
	v_mfma_f32_16x16x32_bf16 v[80:83], v[208:211], v[224:227], v[80:83]
	v_mfma_f32_16x16x32_bf16 v[48:51], v[180:183], v[232:235], v[48:51]
	v_mfma_f32_16x16x32_bf16 v[44:47], v[208:211], v[232:235], v[44:47]
	v_mfma_f32_16x16x32_bf16 v[24:27], v[180:183], v[240:243], v[24:27]
	v_mfma_f32_16x16x32_bf16 v[20:23], v[208:211], v[240:243], v[20:23]
	s_setprio 0
	s_barrier
	s_add_i32 s19, 0, 0x18000
	s_add_i32 s24, 0, 0x1c000
	v_add_u32_e32 v172, s19, v188
	v_add_u32_e32 v207, s24, v188
	ds_read_b128 v[136:139], v172
	ds_read_b128 v[140:143], v172 offset:1024
	ds_read_b128 v[144:147], v172 offset:2048
	ds_read_b128 v[172:175], v172 offset:3072
	ds_read_b128 v[176:179], v207
	ds_read_b128 v[180:183], v207 offset:1024
	ds_read_b128 v[184:187], v207 offset:2048
	ds_read_b128 v[208:211], v207 offset:3072
	s_add_u32 s10, s64, 0x160000
	s_addc_u32 s11, s65, 0
	s_mov_b32 m0, s76
	v_lshl_add_u64 v[248:249], s[10:11], 0, v[0:1]
	ds_read_b128 v[212:215], v197 offset:32768
	ds_read_b128 v[216:219], v197 offset:33792
	ds_read_b128 v[220:223], v197 offset:34816
	ds_read_b128 v[224:227], v197 offset:35840
	ds_read_b128 v[228:231], v197 offset:36864
	ds_read_b128 v[232:235], v197 offset:37888
	ds_read_b128 v[236:239], v197 offset:38912
	ds_read_b128 v[240:243], v197 offset:39936
	global_load_lds_dwordx4 v[248:249], off
	v_lshl_add_u64 v[248:249], s[10:11], 0, v[148:149]
	s_mov_b32 m0, s77
	s_nop 0
	global_load_lds_dwordx4 v[248:249], off
	s_waitcnt vmcnt(8)
	s_waitcnt lgkmcnt(0)
	s_barrier
	s_setprio 1
	s_waitcnt lgkmcnt(0)
	v_mfma_f32_16x16x32_bf16 v[16:19], v[136:139], v[212:215], v[16:19]
	v_mfma_f32_16x16x32_bf16 v[12:15], v[144:147], v[212:215], v[12:15]
	v_mfma_f32_16x16x32_bf16 v[56:59], v[136:139], v[220:223], v[56:59]
	v_mfma_f32_16x16x32_bf16 v[52:55], v[144:147], v[220:223], v[52:55]
	v_mfma_f32_16x16x32_bf16 v[88:91], v[136:139], v[228:231], v[88:91]
	v_mfma_f32_16x16x32_bf16 v[76:79], v[144:147], v[228:231], v[76:79]
	v_mfma_f32_16x16x32_bf16 v[112:115], v[136:139], v[236:239], v[112:115]
	v_mfma_f32_16x16x32_bf16 v[108:111], v[144:147], v[236:239], v[108:111]
	v_mfma_f32_16x16x32_bf16 v[16:19], v[140:143], v[216:219], v[16:19]
	v_mfma_f32_16x16x32_bf16 v[12:15], v[172:175], v[216:219], v[12:15]
	v_mfma_f32_16x16x32_bf16 v[56:59], v[140:143], v[224:227], v[56:59]
	v_mfma_f32_16x16x32_bf16 v[52:55], v[172:175], v[224:227], v[52:55]
	v_mfma_f32_16x16x32_bf16 v[88:91], v[140:143], v[232:235], v[88:91]
	v_mfma_f32_16x16x32_bf16 v[76:79], v[172:175], v[232:235], v[76:79]
	v_mfma_f32_16x16x32_bf16 v[112:115], v[140:143], v[240:243], v[112:115]
	v_mfma_f32_16x16x32_bf16 v[108:111], v[172:175], v[240:243], v[108:111]
	s_setprio 0
	s_setprio 1
	v_mfma_f32_16x16x32_bf16 v[8:11], v[176:179], v[212:215], v[8:11]
	v_mfma_f32_16x16x32_bf16 v[4:7], v[184:187], v[212:215], v[4:7]
	v_mfma_f32_16x16x32_bf16 v[40:43], v[176:179], v[220:223], v[40:43]
	v_mfma_f32_16x16x32_bf16 v[36:39], v[184:187], v[220:223], v[36:39]
	v_mfma_f32_16x16x32_bf16 v[64:67], v[176:179], v[228:231], v[64:67]
	v_mfma_f32_16x16x32_bf16 v[60:63], v[184:187], v[228:231], v[60:63]
	v_mfma_f32_16x16x32_bf16 v[96:99], v[176:179], v[236:239], v[96:99]
	v_mfma_f32_16x16x32_bf16 v[92:95], v[184:187], v[236:239], v[92:95]
	v_mfma_f32_16x16x32_bf16 v[8:11], v[180:183], v[216:219], v[8:11]
	v_mfma_f32_16x16x32_bf16 v[4:7], v[208:211], v[216:219], v[4:7]
	v_mfma_f32_16x16x32_bf16 v[40:43], v[180:183], v[224:227], v[40:43]
	v_mfma_f32_16x16x32_bf16 v[36:39], v[208:211], v[224:227], v[36:39]
	v_mfma_f32_16x16x32_bf16 v[64:67], v[180:183], v[232:235], v[64:67]
	v_mfma_f32_16x16x32_bf16 v[60:63], v[208:211], v[232:235], v[60:63]
	v_mfma_f32_16x16x32_bf16 v[96:99], v[180:183], v[240:243], v[96:99]
	v_mfma_f32_16x16x32_bf16 v[92:95], v[208:211], v[240:243], v[92:95]
	s_setprio 0
	s_barrier
; __device__ __forceinline__ float bflo(unsigned w) { return __uint_as_float(w << 16); }
; __device__ __forceinline__ float bfhi(unsigned w) { return __uint_as_float(w & 0xffff0000u); }
; #define PG8_STAGE(bufoff, gbase, voff) do { _Pragma("unroll") for (int _i = 0; _i < 2; ++_i) \
;         __builtin_amdgcn_global_load_lds((const unsigned*)((const char*)(gbase) + (voff)[_i]), (LAS unsigned*)(lds + (bufoff) + ldsw + _i * 8192), 16, 0, 0); } while (0)
; #define PG8_LDA(dst, b, h) do { _Pragma("unroll") for (int m = 0; m < 4; ++m) _Pragma("unroll") for (int k = 0; k < 2; ++k) dst[m][k] = *(const LAS bf16x8*)(lds + PG8_SA(b, h) + aoff + m * 2048 + k * 1024); } while (0)
; #define PG8_MMA(ai, bj, At, Bt) do { __builtin_amdgcn_s_setprio(1); _Pragma("unroll") for (int m = 0; m < 4; ++m) _Pragma("unroll") for (int n = 0; n < 2; ++n) _Pragma("unroll") for (int k = 0; k < 2; ++k) \
;         acc[ai][bj][m][n] = __builtin_amdgcn_mfma_f32_16x16x32_bf16(Bt[n][k], At[m][k], acc[ai][bj][m][n], 0, 0, 0); __builtin_amdgcn_s_setprio(0); } while (0)
;     __device__ __forceinline__ void operator()(f32x4 (&acc)[2][2][4][2], const Unit& u, int wr, int wc, int fr, int fq, int wid, int lane) const {
;     ...
;             for (int m = 0; m < 4; ++m) { const size_t off = (size_t)(row0 + ai * HALF + m * 16) * D + col0;
; #pragma unroll
;                 for (int bj = 0; bj < 2; ++bj) { f32x4 x0, x1;
;                     if (X) { x0 = *(const f32x4*)(X + off + bj * HALF); x1 = *(const f32x4*)(X + off + bj * HALF + 4); }
;                     else { const u32x4 xw = *(const u32x4*)(XB + off + bj * HALF); x0 = (f32x4){bflo(xw.x), bfhi(xw.x), bflo(xw.y), bfhi(xw.y)}; x1 = (f32x4){bflo(xw.z), bfhi(xw.z), bflo(xw.w), bfhi(xw.w)}; }
;                     acc[ai][bj][m][0] = x0 * ALPHA + acc[ai][bj][m][0]; acc[ai][bj][m][1] = x1 * ALPHA + acc[ai][bj][m][1]; }
; template <class Epi, class Sched, bool ALIGN_EPI = true>
; __device__ __forceinline__ void gemm_phase(LAS unsigned char* lds, const Gemm g, const Sched& S, const Epi& E) {
;     ...
;             PG8_LDA(At, 1, 1); PG8_STAGE(PG8_SB(1, 0), b3, voffB); PG8_STAGE(PG8_SB(1, 1), b3 + hB, voffB); PG8_STAGE(PG8_SA(1, 0), a3, voffA);
;             PG8_WAIT_V(8); PG8_WAIT_L(0); PG8_BAR; PG8_MMA(1, 0, At, B0); PG8_MMA(1, 1, At, B1); PG8_BAR; PG8_SCHED;
;         }
;         if constexpr (ALIGN_EPI) { if (wr == 0) PG8_BAR; }
	s_add_i32 s10, s19, s66
	v_lshl_add_u64 v[160:161], v[160:161], 0, s[86:87]
	s_mov_b32 m0, s10
	ds_read_b128 v[212:215], v197 offset:49152
	ds_read_b128 v[216:219], v197 offset:50176
	ds_read_b128 v[220:223], v197 offset:51200
	ds_read_b128 v[224:227], v197 offset:52224
	ds_read_b128 v[228:231], v197 offset:53248
	ds_read_b128 v[232:235], v197 offset:54272
	ds_read_b128 v[236:239], v197 offset:55296
	ds_read_b128 v[240:243], v197 offset:56320
	global_load_lds_dwordx4 v[160:161], off
	s_add_i32 m0, s10, 0x2000
	s_add_u32 s10, s62, 0x160080
	v_lshl_add_u64 v[160:161], v[162:163], 0, s[86:87]
	s_addc_u32 s11, s63, 0
	s_add_i32 s19, s24, s66
	global_load_lds_dwordx4 v[160:161], off
	v_lshl_add_u64 v[160:161], s[10:11], 0, v[2:3]
	s_mov_b32 m0, s19
	s_nop 0
	global_load_lds_dwordx4 v[160:161], off
	v_lshl_add_u64 v[160:161], s[10:11], 0, v[150:151]
	s_add_i32 m0, s19, 0x2000
	s_nop 0
	global_load_lds_dwordx4 v[160:161], off
	v_lshl_add_u64 v[160:161], v[244:245], 0, s[86:87]
	s_mov_b32 m0, s80
	s_nop 0
	global_load_lds_dwordx4 v[160:161], off
	v_lshl_add_u64 v[160:161], v[246:247], 0, s[86:87]
	s_mov_b32 m0, s81
	s_nop 0
	global_load_lds_dwordx4 v[160:161], off
	s_waitcnt vmcnt(8)
	s_waitcnt lgkmcnt(0)
	s_barrier
	s_setprio 1
	s_waitcnt lgkmcnt(0)
	v_mfma_f32_16x16x32_bf16 v[128:131], v[136:139], v[212:215], v[128:131]
	v_mfma_f32_16x16x32_bf16 v[124:127], v[144:147], v[212:215], v[124:127]
	v_mfma_f32_16x16x32_bf16 v[104:107], v[136:139], v[220:223], v[104:107]
	v_mfma_f32_16x16x32_bf16 v[100:103], v[144:147], v[220:223], v[100:103]
	v_mfma_f32_16x16x32_bf16 v[72:75], v[136:139], v[228:231], v[72:75]
	v_mfma_f32_16x16x32_bf16 v[68:71], v[144:147], v[228:231], v[68:71]
	v_mfma_f32_16x16x32_bf16 v[32:35], v[136:139], v[236:239], v[32:35]
	v_mfma_f32_16x16x32_bf16 v[28:31], v[144:147], v[236:239], v[28:31]
	v_mfma_f32_16x16x32_bf16 v[128:131], v[140:143], v[216:219], v[128:131]
	v_mfma_f32_16x16x32_bf16 v[124:127], v[172:175], v[216:219], v[124:127]
	v_mfma_f32_16x16x32_bf16 v[104:107], v[140:143], v[224:227], v[104:107]
	v_mfma_f32_16x16x32_bf16 v[100:103], v[172:175], v[224:227], v[100:103]
	v_mfma_f32_16x16x32_bf16 v[72:75], v[140:143], v[232:235], v[72:75]
	v_mfma_f32_16x16x32_bf16 v[68:71], v[172:175], v[232:235], v[68:71]
	v_mfma_f32_16x16x32_bf16 v[32:35], v[140:143], v[240:243], v[32:35]
	v_mfma_f32_16x16x32_bf16 v[28:31], v[172:175], v[240:243], v[28:31]
	s_setprio 0
	s_setprio 1
	v_mfma_f32_16x16x32_bf16 v[120:123], v[176:179], v[212:215], v[120:123]
	v_mfma_f32_16x16x32_bf16 v[116:119], v[184:187], v[212:215], v[116:119]
	v_mfma_f32_16x16x32_bf16 v[84:87], v[176:179], v[220:223], v[84:87]
	v_mfma_f32_16x16x32_bf16 v[80:83], v[184:187], v[220:223], v[80:83]
	v_mfma_f32_16x16x32_bf16 v[48:51], v[176:179], v[228:231], v[48:51]
	v_mfma_f32_16x16x32_bf16 v[44:47], v[184:187], v[228:231], v[44:47]
	v_mfma_f32_16x16x32_bf16 v[24:27], v[176:179], v[236:239], v[24:27]
	v_mfma_f32_16x16x32_bf16 v[20:23], v[184:187], v[236:239], v[20:23]
	v_mfma_f32_16x16x32_bf16 v[120:123], v[180:183], v[216:219], v[120:123]
	v_mfma_f32_16x16x32_bf16 v[116:119], v[208:211], v[216:219], v[116:119]
	v_mfma_f32_16x16x32_bf16 v[84:87], v[180:183], v[224:227], v[84:87]
	v_mfma_f32_16x16x32_bf16 v[80:83], v[208:211], v[224:227], v[80:83]
	v_mfma_f32_16x16x32_bf16 v[48:51], v[180:183], v[232:235], v[48:51]
	v_mfma_f32_16x16x32_bf16 v[44:47], v[208:211], v[232:235], v[44:47]
	v_mfma_f32_16x16x32_bf16 v[24:27], v[180:183], v[240:243], v[24:27]
	v_mfma_f32_16x16x32_bf16 v[20:23], v[208:211], v[240:243], v[20:23]
	s_setprio 0
	s_barrier
	s_add_i32 s18, s18, 2
	s_cmpk_gt_u32 s18, 0x55
	s_mov_b64 s[10:11], vcc
	s_cbranch_scc0 .LBB0_1111
	s_and_b64 vcc, exec, s[42:43]
	s_cbranch_vccz .LBB0_1114
	s_barrier
.LBB0_1114:
	s_lshl_b32 s82, s84, 8
	v_add_u32_e32 v132, s82, v158
	v_ashrrev_i32_e32 v133, 31, v132
	v_lshlrev_b64 v[172:173], 11, v[132:133]
	v_lshl_add_u64 v[176:177], v[172:173], 0, v[152:153]
	v_lshl_add_u64 v[174:175], v[176:177], 1, s[46:47]
	global_load_dwordx4 v[208:211], v[174:175], off
	global_load_dwordx4 v[212:215], v[174:175], off offset:256
	s_mov_b64 s[10:11], 0x10000
	s_nop 0
	v_lshl_add_u64 v[248:249], v[174:175], 0, s[10:11]
	global_load_dwordx4 v[216:219], v[248:249], off
	global_load_dwordx4 v[220:223], v[248:249], off offset:256
	s_mov_b64 s[10:11], 0x20000
	s_nop 0
	v_lshl_add_u64 v[248:249], v[174:175], 0, s[10:11]
	global_load_dwordx4 v[224:227], v[248:249], off
	global_load_dwordx4 v[228:231], v[248:249], off offset:256
	s_mov_b64 s[10:11], 0x30000
	s_nop 0
	v_lshl_add_u64 v[248:249], v[174:175], 0, s[10:11]
	global_load_dwordx4 v[232:235], v[248:249], off
	global_load_dwordx4 v[236:239], v[248:249], off offset:256
	s_mov_b64 s[10:11], 0x80000
	s_nop 0
	v_lshl_add_u64 v[248:249], v[174:175], 0, s[10:11]
	global_load_dwordx4 v[240:243], v[248:249], off
	global_load_dwordx4 v[244:247], v[248:249], off offset:256
	s_waitcnt vmcnt(9)
	v_mov_b32_e32 v134, v208
	v_mov_b32_e32 v135, v209
	v_mov_b32_e32 v136, v210
	v_mov_b32_e32 v137, v211
	v_lshlrev_b32_e32 v138, 16, v134
	v_and_b32_e32 v139, 0xffff0000, v134
	v_lshlrev_b32_e32 v134, 16, v135
	v_and_b32_e32 v135, 0xffff0000, v135
	v_lshlrev_b32_e32 v140, 16, v136
	v_and_b32_e32 v141, 0xffff0000, v136
	v_lshlrev_b32_e32 v136, 16, v137
	v_and_b32_e32 v137, 0xffff0000, v137
	v_pk_fma_f32 v[18:19], v[134:135], s[92:93], v[18:19] op_sel_hi:[1,0,1]
	v_pk_fma_f32 v[14:15], v[136:137], s[92:93], v[14:15] op_sel_hi:[1,0,1]
	v_pk_fma_f32 v[16:17], v[138:139], s[92:93], v[16:17] op_sel_hi:[1,0,1]
	v_pk_fma_f32 v[12:13], v[140:141], s[92:93], v[12:13] op_sel_hi:[1,0,1]
	s_waitcnt vmcnt(8)
; __device__ __forceinline__ float bflo(unsigned w) { return __uint_as_float(w << 16); }
; __device__ __forceinline__ float bfhi(unsigned w) { return __uint_as_float(w & 0xffff0000u); }
;     __device__ __forceinline__ void operator()(f32x4 (&acc)[2][2][4][2], const Unit& u, int wr, int wc, int fr, int fq, int wid, int lane) const {
;     ...
;             for (int m = 0; m < 4; ++m) { const size_t off = (size_t)(row0 + ai * HALF + m * 16) * D + col0;
; #pragma unroll
;                 for (int bj = 0; bj < 2; ++bj) { f32x4 x0, x1;
;                     if (X) { x0 = *(const f32x4*)(X + off + bj * HALF); x1 = *(const f32x4*)(X + off + bj * HALF + 4); }
;                     else { const u32x4 xw = *(const u32x4*)(XB + off + bj * HALF); x0 = (f32x4){bflo(xw.x), bfhi(xw.x), bflo(xw.y), bfhi(xw.y)}; x1 = (f32x4){bflo(xw.z), bfhi(xw.z), bflo(xw.w), bfhi(xw.w)}; }
;                     acc[ai][bj][m][0] = x0 * ALPHA + acc[ai][bj][m][0]; acc[ai][bj][m][1] = x1 * ALPHA + acc[ai][bj][m][1]; }
;                 asm volatile("" : "+v"(acc[ai][0][m][0]), "+v"(acc[ai][0][m][1]), "+v"(acc[ai][1][m][0]), "+v"(acc[ai][1][m][1]));
;                 float s = 0.f;
; #pragma unroll
;                 for (int bj = 0; bj < 2; ++bj)
; #pragma unroll
;                     for (int n = 0; n < 2; ++n) { const f32x4 x = acc[ai][bj][m][n]; s += (x[0] + x[1]) + (x[2] + x[3]); }
;                 s += __shfl_xor(s, 16); s += __shfl_xor(s, 32);
;                 const float mw = s * (1.0f / 64.0f); float q = 0.f;
; #pragma unroll
;                 for (int bj = 0; bj < 2; ++bj)
; #pragma unroll
;                     for (int n = 0; n < 2; ++n) { const f32x4 d = acc[ai][bj][m][n] - mw; q += (d[0] * d[0] + d[1] * d[1]) + (d[2] * d[2] + d[3] * d[3]); }
;                 q += __shfl_xor(q, 16); q += __shfl_xor(q, 32);
;                 if (fq == 0) P[(ai * HALF + wr * 64 + m * 16 + fr) * 4 + wc] = (f32x2){mw, q};
	v_mov_b32_e32 v134, v212
	v_mov_b32_e32 v135, v213
	v_mov_b32_e32 v136, v214
	v_mov_b32_e32 v137, v215
	s_mov_b64 s[10:11], 0x90000
	s_nop 0
	v_lshl_add_u64 v[248:249], v[174:175], 0, s[10:11]
	global_load_dwordx4 v[208:211], v[248:249], off
	global_load_dwordx4 v[212:215], v[248:249], off offset:256
	v_lshlrev_b32_e32 v138, 16, v134
	v_and_b32_e32 v139, 0xffff0000, v134
	v_lshlrev_b32_e32 v134, 16, v135
	v_and_b32_e32 v135, 0xffff0000, v135
	v_lshlrev_b32_e32 v140, 16, v136
	v_and_b32_e32 v141, 0xffff0000, v136
	v_lshlrev_b32_e32 v136, 16, v137
	v_and_b32_e32 v137, 0xffff0000, v137
	v_pk_fma_f32 v[10:11], v[134:135], s[92:93], v[10:11] op_sel_hi:[1,0,1]
	v_pk_fma_f32 v[8:9], v[138:139], s[92:93], v[8:9] op_sel_hi:[1,0,1]
	v_pk_fma_f32 v[6:7], v[136:137], s[92:93], v[6:7] op_sel_hi:[1,0,1]
	v_pk_fma_f32 v[4:5], v[140:141], s[92:93], v[4:5] op_sel_hi:[1,0,1]
	s_nop 0
	s_nop 0
	v_mov_b32_e32 v134, v17
	v_mov_b32_e32 v135, v18
	v_mov_b32_e32 v136, v16
	v_mov_b32_e32 v137, v19
	v_pk_add_f32 v[134:135], v[134:135], v[136:137]
	v_mov_b32_e32 v136, v13
	v_mov_b32_e32 v137, v14
	v_mov_b32_e32 v138, v12
	v_mov_b32_e32 v139, v15
	v_pk_add_f32 v[136:137], v[136:137], v[138:139]
	v_add_f32_e32 v134, v134, v135
	v_pk_add_f32 v[136:137], v[136:137], v[136:137] op_sel_hi:[0,1]
	v_add_f32_e32 v135, 0, v134
	v_add_f32_e32 v139, v8, v9
	v_add_f32_e32 v141, v10, v11
	v_mov_b32_e32 v138, v4
	v_mov_b32_e32 v140, v5
	v_mov_b32_e32 v136, v6
	v_mov_b32_e32 v134, v7
	v_pk_add_f32 v[138:139], v[138:139], v[140:141]
	v_pk_add_f32 v[134:135], v[136:137], v[134:135]
	v_and_b32_e32 v136, 64, v202
	v_pk_add_f32 v[134:135], v[138:139], v[134:135]
	v_add_u32_e32 v137, 64, v136
	v_add_f32_e32 v134, v134, v135
	v_xor_b32_e32 v135, 16, v202
	v_cmp_lt_i32_e32 vcc, v135, v137
	s_nop 1
	v_cndmask_b32_e32 v135, v202, v135, vcc
	v_lshlrev_b32_e32 v136, 2, v135
	ds_bpermute_b32 v135, v136, v134
	s_waitcnt lgkmcnt(0)
	v_add_f32_e32 v134, v134, v135
	v_xor_b32_e32 v135, 32, v202
	v_cmp_lt_i32_e32 vcc, v135, v137
	s_nop 1
	v_cndmask_b32_e32 v135, v202, v135, vcc
	v_lshlrev_b32_e32 v137, 2, v135
	ds_bpermute_b32 v135, v137, v134
	s_waitcnt lgkmcnt(0)
	v_add_f32_e32 v134, v134, v135
	v_fmamk_f32 v138, v134, 0xbc800000, v19
	v_fmamk_f32 v140, v134, 0xbc800000, v17
	v_fmamk_f32 v135, v134, 0xbc800000, v18
	v_fmamk_f32 v139, v134, 0xbc800000, v16
	v_mul_f32_e32 v140, v140, v140
	v_mul_f32_e32 v138, v138, v138
	v_fmac_f32_e32 v140, v139, v139
	v_fmac_f32_e32 v138, v135, v135
	v_fmamk_f32 v139, v134, 0xbc800000, v15
	v_fmamk_f32 v141, v134, 0xbc800000, v13
	v_add_f32_e32 v135, v140, v138
	v_fmamk_f32 v138, v134, 0xbc800000, v14
	v_fmamk_f32 v140, v134, 0xbc800000, v12
	v_mul_f32_e32 v141, v141, v141
	v_mul_f32_e32 v139, v139, v139
	v_fmac_f32_e32 v141, v140, v140
	v_fmac_f32_e32 v139, v138, v138
	v_add_f32_e32 v138, v141, v139
	v_fmamk_f32 v139, v134, 0xbc800000, v11
	v_fmamk_f32 v141, v134, 0xbc800000, v9
	v_add_f32_e32 v135, v135, v138
	v_fmamk_f32 v138, v134, 0xbc800000, v10
	v_fmamk_f32 v140, v134, 0xbc800000, v8
	v_mul_f32_e32 v141, v141, v141
	v_mul_f32_e32 v139, v139, v139
	v_fmac_f32_e32 v141, v140, v140
	v_fmac_f32_e32 v139, v138, v138
	v_add_f32_e32 v138, v141, v139
	v_fmamk_f32 v139, v134, 0xbc800000, v7
	v_fmamk_f32 v141, v134, 0xbc800000, v5
	v_add_f32_e32 v135, v138, v135
	v_fmamk_f32 v138, v134, 0xbc800000, v6
	v_fmamk_f32 v140, v134, 0xbc800000, v4
	v_mul_f32_e32 v141, v141, v141
	v_mul_f32_e32 v139, v139, v139
	v_fmac_f32_e32 v141, v140, v140
	v_fmac_f32_e32 v139, v138, v138
	v_add_f32_e32 v138, v141, v139
	v_add_f32_e32 v135, v138, v135
	ds_bpermute_b32 v138, v136, v135
	s_waitcnt lgkmcnt(0)
	v_add_f32_e32 v135, v135, v138
	ds_bpermute_b32 v138, v137, v135
	s_and_saveexec_b64 s[10:11], s[4:5]
	s_cbranch_execz .LBB0_1116
	v_mul_f32_e32 v134, 0x3c800000, v134
	s_waitcnt lgkmcnt(0)
	v_add_f32_e32 v135, v135, v138
	ds_write_b64 v206, v[134:135]
.LBB0_1116:
	s_or_b64 exec, exec, s[10:11]
	v_or_b32_e32 v134, 16, v132
	v_ashrrev_i32_e32 v135, 31, v134
	v_lshlrev_b64 v[134:135], 12, v[134:135]
	v_lshl_add_u64 v[134:135], v[166:167], 0, v[134:135]
	s_waitcnt lgkmcnt(0)
	s_waitcnt vmcnt(9)
	v_mov_b32_e32 v138, v216
	v_mov_b32_e32 v139, v217
	v_mov_b32_e32 v140, v218
	v_mov_b32_e32 v141, v219
	v_lshlrev_b32_e32 v142, 16, v138
	v_and_b32_e32 v143, 0xffff0000, v138
	v_lshlrev_b32_e32 v138, 16, v139
	v_and_b32_e32 v139, 0xffff0000, v139
	v_lshlrev_b32_e32 v144, 16, v140
	v_and_b32_e32 v145, 0xffff0000, v140
	v_lshlrev_b32_e32 v140, 16, v141
	v_and_b32_e32 v141, 0xffff0000, v141
	v_pk_fma_f32 v[58:59], v[138:139], s[92:93], v[58:59] op_sel_hi:[1,0,1]
	v_pk_fma_f32 v[54:55], v[140:141], s[92:93], v[54:55] op_sel_hi:[1,0,1]
	v_pk_fma_f32 v[56:57], v[142:143], s[92:93], v[56:57] op_sel_hi:[1,0,1]
	v_pk_fma_f32 v[52:53], v[144:145], s[92:93], v[52:53] op_sel_hi:[1,0,1]
	s_waitcnt vmcnt(8)
; __device__ __forceinline__ float bflo(unsigned w) { return __uint_as_float(w << 16); }
; __device__ __forceinline__ float bfhi(unsigned w) { return __uint_as_float(w & 0xffff0000u); }
;     __device__ __forceinline__ void operator()(f32x4 (&acc)[2][2][4][2], const Unit& u, int wr, int wc, int fr, int fq, int wid, int lane) const {
;     ...
;             for (int m = 0; m < 4; ++m) { const size_t off = (size_t)(row0 + ai * HALF + m * 16) * D + col0;
; #pragma unroll
;                 for (int bj = 0; bj < 2; ++bj) { f32x4 x0, x1;
;                     if (X) { x0 = *(const f32x4*)(X + off + bj * HALF); x1 = *(const f32x4*)(X + off + bj * HALF + 4); }
;                     else { const u32x4 xw = *(const u32x4*)(XB + off + bj * HALF); x0 = (f32x4){bflo(xw.x), bfhi(xw.x), bflo(xw.y), bfhi(xw.y)}; x1 = (f32x4){bflo(xw.z), bfhi(xw.z), bflo(xw.w), bfhi(xw.w)}; }
;                     acc[ai][bj][m][0] = x0 * ALPHA + acc[ai][bj][m][0]; acc[ai][bj][m][1] = x1 * ALPHA + acc[ai][bj][m][1]; }
;                 asm volatile("" : "+v"(acc[ai][0][m][0]), "+v"(acc[ai][0][m][1]), "+v"(acc[ai][1][m][0]), "+v"(acc[ai][1][m][1]));
;                 float s = 0.f;
; #pragma unroll
;                 for (int bj = 0; bj < 2; ++bj)
; #pragma unroll
;                     for (int n = 0; n < 2; ++n) { const f32x4 x = acc[ai][bj][m][n]; s += (x[0] + x[1]) + (x[2] + x[3]); }
;                 s += __shfl_xor(s, 16); s += __shfl_xor(s, 32);
;                 const float mw = s * (1.0f / 64.0f); float q = 0.f;
; #pragma unroll
;                 for (int bj = 0; bj < 2; ++bj)
; #pragma unroll
;                     for (int n = 0; n < 2; ++n) { const f32x4 d = acc[ai][bj][m][n] - mw; q += (d[0] * d[0] + d[1] * d[1]) + (d[2] * d[2] + d[3] * d[3]); }
;                 q += __shfl_xor(q, 16); q += __shfl_xor(q, 32);
;                 if (fq == 0) P[(ai * HALF + wr * 64 + m * 16 + fr) * 4 + wc] = (f32x2){mw, q};
	v_mov_b32_e32 v138, v220
	v_mov_b32_e32 v139, v221
	v_mov_b32_e32 v140, v222
	v_mov_b32_e32 v141, v223
	s_mov_b64 s[10:11], 0xa0000
	s_nop 0
	v_lshl_add_u64 v[248:249], v[174:175], 0, s[10:11]
	global_load_dwordx4 v[216:219], v[248:249], off
	global_load_dwordx4 v[220:223], v[248:249], off offset:256
	v_lshlrev_b32_e32 v134, 16, v138
	v_and_b32_e32 v135, 0xffff0000, v138
	v_lshlrev_b32_e32 v138, 16, v139
	v_and_b32_e32 v139, 0xffff0000, v139
	v_lshlrev_b32_e32 v142, 16, v140
	v_and_b32_e32 v143, 0xffff0000, v140
	v_lshlrev_b32_e32 v140, 16, v141
	v_and_b32_e32 v141, 0xffff0000, v141
	v_pk_fma_f32 v[42:43], v[138:139], s[92:93], v[42:43] op_sel_hi:[1,0,1]
	v_pk_fma_f32 v[40:41], v[134:135], s[92:93], v[40:41] op_sel_hi:[1,0,1]
	v_pk_fma_f32 v[38:39], v[140:141], s[92:93], v[38:39] op_sel_hi:[1,0,1]
	v_pk_fma_f32 v[36:37], v[142:143], s[92:93], v[36:37] op_sel_hi:[1,0,1]
	s_nop 0
	s_nop 0
	v_mov_b32_e32 v134, v57
	v_mov_b32_e32 v135, v58
	v_mov_b32_e32 v138, v56
	v_mov_b32_e32 v139, v59
	v_pk_add_f32 v[134:135], v[134:135], v[138:139]
	v_mov_b32_e32 v138, v53
	v_mov_b32_e32 v139, v54
	v_mov_b32_e32 v140, v52
	v_mov_b32_e32 v141, v55
	v_pk_add_f32 v[138:139], v[138:139], v[140:141]
	v_add_f32_e32 v134, v134, v135
	v_pk_add_f32 v[138:139], v[138:139], v[138:139] op_sel_hi:[0,1]
	v_add_f32_e32 v135, 0, v134
	v_add_f32_e32 v141, v40, v41
	v_add_f32_e32 v143, v42, v43
	v_mov_b32_e32 v140, v36
	v_mov_b32_e32 v142, v37
	v_mov_b32_e32 v138, v38
	v_mov_b32_e32 v134, v39
	v_pk_add_f32 v[140:141], v[140:141], v[142:143]
	v_pk_add_f32 v[134:135], v[138:139], v[134:135]
	s_nop 0
	v_pk_add_f32 v[134:135], v[140:141], v[134:135]
	s_nop 0
	v_add_f32_e32 v134, v134, v135
	ds_bpermute_b32 v135, v136, v134
	s_waitcnt lgkmcnt(0)
	v_add_f32_e32 v134, v134, v135
	ds_bpermute_b32 v135, v137, v134
	s_waitcnt lgkmcnt(0)
	v_add_f32_e32 v134, v134, v135
	v_fmamk_f32 v138, v134, 0xbc800000, v59
	v_fmamk_f32 v140, v134, 0xbc800000, v57
	v_fmamk_f32 v135, v134, 0xbc800000, v58
	v_fmamk_f32 v139, v134, 0xbc800000, v56
	v_mul_f32_e32 v140, v140, v140
	v_mul_f32_e32 v138, v138, v138
	v_fmac_f32_e32 v140, v139, v139
	v_fmac_f32_e32 v138, v135, v135
	v_fmamk_f32 v139, v134, 0xbc800000, v55
	v_fmamk_f32 v141, v134, 0xbc800000, v53
	v_add_f32_e32 v135, v140, v138
	v_fmamk_f32 v138, v134, 0xbc800000, v54
	v_fmamk_f32 v140, v134, 0xbc800000, v52
	v_mul_f32_e32 v141, v141, v141
	v_mul_f32_e32 v139, v139, v139
	v_fmac_f32_e32 v141, v140, v140
	v_fmac_f32_e32 v139, v138, v138
	v_add_f32_e32 v138, v141, v139
	v_fmamk_f32 v139, v134, 0xbc800000, v43
	v_fmamk_f32 v141, v134, 0xbc800000, v41
	v_add_f32_e32 v135, v135, v138
	v_fmamk_f32 v138, v134, 0xbc800000, v42
	v_fmamk_f32 v140, v134, 0xbc800000, v40
	v_mul_f32_e32 v141, v141, v141
	v_mul_f32_e32 v139, v139, v139
	v_fmac_f32_e32 v141, v140, v140
	v_fmac_f32_e32 v139, v138, v138
	v_add_f32_e32 v138, v141, v139
	v_fmamk_f32 v139, v134, 0xbc800000, v39
	v_fmamk_f32 v141, v134, 0xbc800000, v37
	v_add_f32_e32 v135, v138, v135
	v_fmamk_f32 v138, v134, 0xbc800000, v38
	v_fmamk_f32 v140, v134, 0xbc800000, v36
	v_mul_f32_e32 v141, v141, v141
	v_mul_f32_e32 v139, v139, v139
	v_fmac_f32_e32 v141, v140, v140
	v_fmac_f32_e32 v139, v138, v138
	v_add_f32_e32 v138, v141, v139
	v_add_f32_e32 v135, v138, v135
	ds_bpermute_b32 v138, v136, v135
	s_waitcnt lgkmcnt(0)
	v_add_f32_e32 v135, v135, v138
	ds_bpermute_b32 v138, v137, v135
	s_and_saveexec_b64 s[10:11], s[4:5]
	s_cbranch_execz .LBB0_1118
	v_mul_f32_e32 v134, 0x3c800000, v134
	s_waitcnt lgkmcnt(0)
	v_add_f32_e32 v135, v135, v138
	ds_write_b64 v206, v[134:135] offset:512
.LBB0_1118:
	s_or_b64 exec, exec, s[10:11]
	v_or_b32_e32 v134, 32, v132
	v_ashrrev_i32_e32 v135, 31, v134
	v_lshlrev_b64 v[134:135], 12, v[134:135]
	v_lshl_add_u64 v[134:135], v[166:167], 0, v[134:135]
	s_waitcnt lgkmcnt(0)
	s_waitcnt vmcnt(9)
	v_mov_b32_e32 v138, v224
	v_mov_b32_e32 v139, v225
	v_mov_b32_e32 v140, v226
	v_mov_b32_e32 v141, v227
	v_lshlrev_b32_e32 v142, 16, v138
	v_and_b32_e32 v143, 0xffff0000, v138
	v_lshlrev_b32_e32 v138, 16, v139
	v_and_b32_e32 v139, 0xffff0000, v139
	v_lshlrev_b32_e32 v144, 16, v140
	v_and_b32_e32 v145, 0xffff0000, v140
	v_lshlrev_b32_e32 v140, 16, v141
	v_and_b32_e32 v141, 0xffff0000, v141
	v_pk_fma_f32 v[90:91], v[138:139], s[92:93], v[90:91] op_sel_hi:[1,0,1]
	v_pk_fma_f32 v[78:79], v[140:141], s[92:93], v[78:79] op_sel_hi:[1,0,1]
	v_pk_fma_f32 v[88:89], v[142:143], s[92:93], v[88:89] op_sel_hi:[1,0,1]
	v_pk_fma_f32 v[76:77], v[144:145], s[92:93], v[76:77] op_sel_hi:[1,0,1]
	s_waitcnt vmcnt(8)
	v_mov_b32_e32 v138, v228
	v_mov_b32_e32 v139, v229
	v_mov_b32_e32 v140, v230
	v_mov_b32_e32 v141, v231
	s_mov_b64 s[10:11], 0xb0000
	s_nop 0
	v_lshl_add_u64 v[248:249], v[174:175], 0, s[10:11]
	global_load_dwordx4 v[224:227], v[248:249], off
	global_load_dwordx4 v[228:231], v[248:249], off offset:256
	v_lshlrev_b32_e32 v134, 16, v138
	v_and_b32_e32 v135, 0xffff0000, v138
	v_lshlrev_b32_e32 v138, 16, v139
	v_and_b32_e32 v139, 0xffff0000, v139
	v_lshlrev_b32_e32 v142, 16, v140
	v_and_b32_e32 v143, 0xffff0000, v140
	v_lshlrev_b32_e32 v140, 16, v141
	v_and_b32_e32 v141, 0xffff0000, v141
	v_pk_fma_f32 v[66:67], v[138:139], s[92:93], v[66:67] op_sel_hi:[1,0,1]
	v_pk_fma_f32 v[64:65], v[134:135], s[92:93], v[64:65] op_sel_hi:[1,0,1]
	v_pk_fma_f32 v[62:63], v[140:141], s[92:93], v[62:63] op_sel_hi:[1,0,1]
	v_pk_fma_f32 v[60:61], v[142:143], s[92:93], v[60:61] op_sel_hi:[1,0,1]
	s_nop 0
	s_nop 0
	v_mov_b32_e32 v134, v89
	v_mov_b32_e32 v135, v90
	v_mov_b32_e32 v138, v88
	v_mov_b32_e32 v139, v91
	v_pk_add_f32 v[134:135], v[134:135], v[138:139]
	v_mov_b32_e32 v138, v77
	v_mov_b32_e32 v139, v78
	v_mov_b32_e32 v140, v76
	v_mov_b32_e32 v141, v79
	v_pk_add_f32 v[138:139], v[138:139], v[140:141]
	v_add_f32_e32 v134, v134, v135
	v_pk_add_f32 v[138:139], v[138:139], v[138:139] op_sel_hi:[0,1]
	v_add_f32_e32 v135, 0, v134
	v_add_f32_e32 v141, v64, v65
	v_add_f32_e32 v143, v66, v67
	v_mov_b32_e32 v140, v60
	v_mov_b32_e32 v142, v61
	v_mov_b32_e32 v138, v62
	v_mov_b32_e32 v134, v63
	v_pk_add_f32 v[140:141], v[140:141], v[142:143]
	v_pk_add_f32 v[134:135], v[138:139], v[134:135]
	s_nop 0
	v_pk_add_f32 v[134:135], v[140:141], v[134:135]
	s_nop 0
	v_add_f32_e32 v134, v134, v135
	ds_bpermute_b32 v135, v136, v134
	s_waitcnt lgkmcnt(0)
; __device__ __forceinline__ float bflo(unsigned w) { return __uint_as_float(w << 16); }
; __device__ __forceinline__ float bfhi(unsigned w) { return __uint_as_float(w & 0xffff0000u); }
;     __device__ __forceinline__ void operator()(f32x4 (&acc)[2][2][4][2], const Unit& u, int wr, int wc, int fr, int fq, int wid, int lane) const {
;     ...
;             for (int m = 0; m < 4; ++m) { const size_t off = (size_t)(row0 + ai * HALF + m * 16) * D + col0;
; #pragma unroll
;                 for (int bj = 0; bj < 2; ++bj) { f32x4 x0, x1;
;                     if (X) { x0 = *(const f32x4*)(X + off + bj * HALF); x1 = *(const f32x4*)(X + off + bj * HALF + 4); }
;                     else { const u32x4 xw = *(const u32x4*)(XB + off + bj * HALF); x0 = (f32x4){bflo(xw.x), bfhi(xw.x), bflo(xw.y), bfhi(xw.y)}; x1 = (f32x4){bflo(xw.z), bfhi(xw.z), bflo(xw.w), bfhi(xw.w)}; }
;                     acc[ai][bj][m][0] = x0 * ALPHA + acc[ai][bj][m][0]; acc[ai][bj][m][1] = x1 * ALPHA + acc[ai][bj][m][1]; }
;                 asm volatile("" : "+v"(acc[ai][0][m][0]), "+v"(acc[ai][0][m][1]), "+v"(acc[ai][1][m][0]), "+v"(acc[ai][1][m][1]));
;                 float s = 0.f;
; #pragma unroll
;                 for (int bj = 0; bj < 2; ++bj)
; #pragma unroll
;                     for (int n = 0; n < 2; ++n) { const f32x4 x = acc[ai][bj][m][n]; s += (x[0] + x[1]) + (x[2] + x[3]); }
;                 s += __shfl_xor(s, 16); s += __shfl_xor(s, 32);
;                 const float mw = s * (1.0f / 64.0f); float q = 0.f;
; #pragma unroll
;                 for (int bj = 0; bj < 2; ++bj)
; #pragma unroll
;                     for (int n = 0; n < 2; ++n) { const f32x4 d = acc[ai][bj][m][n] - mw; q += (d[0] * d[0] + d[1] * d[1]) + (d[2] * d[2] + d[3] * d[3]); }
;                 q += __shfl_xor(q, 16); q += __shfl_xor(q, 32);
;                 if (fq == 0) P[(ai * HALF + wr * 64 + m * 16 + fr) * 4 + wc] = (f32x2){mw, q};
	v_add_f32_e32 v134, v134, v135
	ds_bpermute_b32 v135, v137, v134
	s_waitcnt lgkmcnt(0)
	v_add_f32_e32 v134, v134, v135
	v_fmamk_f32 v138, v134, 0xbc800000, v91
	v_fmamk_f32 v140, v134, 0xbc800000, v89
	v_fmamk_f32 v135, v134, 0xbc800000, v90
	v_fmamk_f32 v139, v134, 0xbc800000, v88
	v_mul_f32_e32 v140, v140, v140
	v_mul_f32_e32 v138, v138, v138
	v_fmac_f32_e32 v140, v139, v139
	v_fmac_f32_e32 v138, v135, v135
	v_fmamk_f32 v139, v134, 0xbc800000, v79
	v_fmamk_f32 v141, v134, 0xbc800000, v77
	v_add_f32_e32 v135, v140, v138
	v_fmamk_f32 v138, v134, 0xbc800000, v78
	v_fmamk_f32 v140, v134, 0xbc800000, v76
	v_mul_f32_e32 v141, v141, v141
	v_mul_f32_e32 v139, v139, v139
	v_fmac_f32_e32 v141, v140, v140
	v_fmac_f32_e32 v139, v138, v138
	v_add_f32_e32 v138, v141, v139
	v_fmamk_f32 v139, v134, 0xbc800000, v67
	v_fmamk_f32 v141, v134, 0xbc800000, v65
	v_add_f32_e32 v135, v135, v138
	v_fmamk_f32 v138, v134, 0xbc800000, v66
	v_fmamk_f32 v140, v134, 0xbc800000, v64
	v_mul_f32_e32 v141, v141, v141
	v_mul_f32_e32 v139, v139, v139
	v_fmac_f32_e32 v141, v140, v140
	v_fmac_f32_e32 v139, v138, v138
	v_add_f32_e32 v138, v141, v139
	v_fmamk_f32 v139, v134, 0xbc800000, v63
	v_fmamk_f32 v141, v134, 0xbc800000, v61
	v_add_f32_e32 v135, v138, v135
	v_fmamk_f32 v138, v134, 0xbc800000, v62
	v_fmamk_f32 v140, v134, 0xbc800000, v60
	v_mul_f32_e32 v141, v141, v141
	v_mul_f32_e32 v139, v139, v139
	v_fmac_f32_e32 v141, v140, v140
	v_fmac_f32_e32 v139, v138, v138
	v_add_f32_e32 v138, v141, v139
	v_add_f32_e32 v135, v138, v135
	ds_bpermute_b32 v138, v136, v135
	s_waitcnt lgkmcnt(0)
	v_add_f32_e32 v135, v135, v138
	ds_bpermute_b32 v138, v137, v135
	s_and_saveexec_b64 s[10:11], s[4:5]
	s_cbranch_execz .LBB0_1120
	v_mul_f32_e32 v134, 0x3c800000, v134
	s_waitcnt lgkmcnt(0)
	v_add_f32_e32 v135, v135, v138
	ds_write_b64 v206, v[134:135] offset:1024
.LBB0_1120:
	s_or_b64 exec, exec, s[10:11]
	v_or_b32_e32 v134, 48, v132
	v_ashrrev_i32_e32 v135, 31, v134
	v_lshlrev_b64 v[134:135], 12, v[134:135]
	v_lshl_add_u64 v[134:135], v[166:167], 0, v[134:135]
	s_waitcnt lgkmcnt(0)
	s_waitcnt vmcnt(9)
	v_mov_b32_e32 v138, v232
	v_mov_b32_e32 v139, v233
	v_mov_b32_e32 v140, v234
	v_mov_b32_e32 v141, v235
	v_lshlrev_b32_e32 v142, 16, v138
	v_and_b32_e32 v143, 0xffff0000, v138
	v_lshlrev_b32_e32 v138, 16, v139
	v_and_b32_e32 v139, 0xffff0000, v139
	v_lshlrev_b32_e32 v144, 16, v140
	v_and_b32_e32 v145, 0xffff0000, v140
	v_lshlrev_b32_e32 v140, 16, v141
	v_and_b32_e32 v141, 0xffff0000, v141
	v_pk_fma_f32 v[114:115], v[138:139], s[92:93], v[114:115] op_sel_hi:[1,0,1]
	v_pk_fma_f32 v[110:111], v[140:141], s[92:93], v[110:111] op_sel_hi:[1,0,1]
	v_pk_fma_f32 v[112:113], v[142:143], s[92:93], v[112:113] op_sel_hi:[1,0,1]
	v_pk_fma_f32 v[108:109], v[144:145], s[92:93], v[108:109] op_sel_hi:[1,0,1]
	s_waitcnt vmcnt(8)
	v_mov_b32_e32 v138, v236
	v_mov_b32_e32 v139, v237
	v_mov_b32_e32 v140, v238
	v_mov_b32_e32 v141, v239
	v_lshlrev_b32_e32 v134, 16, v138
	v_and_b32_e32 v135, 0xffff0000, v138
	v_lshlrev_b32_e32 v138, 16, v139
	v_and_b32_e32 v139, 0xffff0000, v139
	v_lshlrev_b32_e32 v142, 16, v140
	v_and_b32_e32 v143, 0xffff0000, v140
	v_lshlrev_b32_e32 v140, 16, v141
	v_and_b32_e32 v141, 0xffff0000, v141
	v_pk_fma_f32 v[98:99], v[138:139], s[92:93], v[98:99] op_sel_hi:[1,0,1]
	v_pk_fma_f32 v[96:97], v[134:135], s[92:93], v[96:97] op_sel_hi:[1,0,1]
	v_pk_fma_f32 v[94:95], v[140:141], s[92:93], v[94:95] op_sel_hi:[1,0,1]
	v_pk_fma_f32 v[92:93], v[142:143], s[92:93], v[92:93] op_sel_hi:[1,0,1]
	s_nop 0
	s_nop 0
	v_mov_b32_e32 v134, v113
	v_mov_b32_e32 v135, v114
	v_mov_b32_e32 v138, v112
	v_mov_b32_e32 v139, v115
	v_pk_add_f32 v[134:135], v[134:135], v[138:139]
	v_mov_b32_e32 v138, v109
	v_mov_b32_e32 v139, v110
	v_mov_b32_e32 v140, v108
	v_mov_b32_e32 v141, v111
	v_pk_add_f32 v[138:139], v[138:139], v[140:141]
	v_add_f32_e32 v134, v134, v135
	v_pk_add_f32 v[138:139], v[138:139], v[138:139] op_sel_hi:[0,1]
	v_add_f32_e32 v135, 0, v134
	v_add_f32_e32 v141, v96, v97
	v_add_f32_e32 v143, v98, v99
	v_mov_b32_e32 v140, v92
	v_mov_b32_e32 v142, v93
	v_mov_b32_e32 v138, v94
	v_mov_b32_e32 v134, v95
	v_pk_add_f32 v[140:141], v[140:141], v[142:143]
	v_pk_add_f32 v[134:135], v[138:139], v[134:135]
	s_nop 0
	v_pk_add_f32 v[134:135], v[140:141], v[134:135]
	s_nop 0
	v_add_f32_e32 v134, v134, v135
	ds_bpermute_b32 v135, v136, v134
	s_waitcnt lgkmcnt(0)
	v_add_f32_e32 v134, v134, v135
	ds_bpermute_b32 v135, v137, v134
	s_waitcnt lgkmcnt(0)
	v_add_f32_e32 v134, v134, v135
	v_fmamk_f32 v138, v134, 0xbc800000, v115
	v_fmamk_f32 v140, v134, 0xbc800000, v113
	v_fmamk_f32 v135, v134, 0xbc800000, v114
	v_fmamk_f32 v139, v134, 0xbc800000, v112
	v_mul_f32_e32 v140, v140, v140
	v_mul_f32_e32 v138, v138, v138
	v_fmac_f32_e32 v140, v139, v139
	v_fmac_f32_e32 v138, v135, v135
	v_fmamk_f32 v139, v134, 0xbc800000, v111
	v_fmamk_f32 v141, v134, 0xbc800000, v109
	v_add_f32_e32 v135, v140, v138
	v_fmamk_f32 v138, v134, 0xbc800000, v110
	v_fmamk_f32 v140, v134, 0xbc800000, v108
	v_mul_f32_e32 v141, v141, v141
	v_mul_f32_e32 v139, v139, v139
	v_fmac_f32_e32 v141, v140, v140
	v_fmac_f32_e32 v139, v138, v138
	v_add_f32_e32 v138, v141, v139
	v_fmamk_f32 v139, v134, 0xbc800000, v99
	v_fmamk_f32 v141, v134, 0xbc800000, v97
	v_add_f32_e32 v135, v135, v138
	v_fmamk_f32 v138, v134, 0xbc800000, v98
	v_fmamk_f32 v140, v134, 0xbc800000, v96
	v_mul_f32_e32 v141, v141, v141
	v_mul_f32_e32 v139, v139, v139
	v_fmac_f32_e32 v141, v140, v140
	v_fmac_f32_e32 v139, v138, v138
	v_add_f32_e32 v138, v141, v139
	v_fmamk_f32 v139, v134, 0xbc800000, v95
	v_fmamk_f32 v141, v134, 0xbc800000, v93
	v_add_f32_e32 v135, v138, v135
	v_fmamk_f32 v138, v134, 0xbc800000, v94
	v_fmamk_f32 v140, v134, 0xbc800000, v92
	v_mul_f32_e32 v141, v141, v141
	v_mul_f32_e32 v139, v139, v139
	v_fmac_f32_e32 v141, v140, v140
	v_fmac_f32_e32 v139, v138, v138
	v_add_f32_e32 v138, v141, v139
	v_add_f32_e32 v135, v138, v135
	ds_bpermute_b32 v138, v136, v135
	s_waitcnt lgkmcnt(0)
	v_add_f32_e32 v135, v135, v138
	ds_bpermute_b32 v138, v137, v135
	s_and_saveexec_b64 s[10:11], s[4:5]
	s_cbranch_execz .LBB0_1122
	v_mul_f32_e32 v134, 0x3c800000, v134
	s_waitcnt lgkmcnt(0)
	v_add_f32_e32 v135, v135, v138
	ds_write_b64 v206, v[134:135] offset:1536
; __device__ __forceinline__ float bflo(unsigned w) { return __uint_as_float(w << 16); }
; __device__ __forceinline__ float bfhi(unsigned w) { return __uint_as_float(w & 0xffff0000u); }
;     __device__ __forceinline__ void operator()(f32x4 (&acc)[2][2][4][2], const Unit& u, int wr, int wc, int fr, int fq, int wid, int lane) const {
;     ...
;             for (int m = 0; m < 4; ++m) { const size_t off = (size_t)(row0 + ai * HALF + m * 16) * D + col0;
; #pragma unroll
;                 for (int bj = 0; bj < 2; ++bj) { f32x4 x0, x1;
;                     if (X) { x0 = *(const f32x4*)(X + off + bj * HALF); x1 = *(const f32x4*)(X + off + bj * HALF + 4); }
;                     else { const u32x4 xw = *(const u32x4*)(XB + off + bj * HALF); x0 = (f32x4){bflo(xw.x), bfhi(xw.x), bflo(xw.y), bfhi(xw.y)}; x1 = (f32x4){bflo(xw.z), bfhi(xw.z), bflo(xw.w), bfhi(xw.w)}; }
;                     acc[ai][bj][m][0] = x0 * ALPHA + acc[ai][bj][m][0]; acc[ai][bj][m][1] = x1 * ALPHA + acc[ai][bj][m][1]; }
;                 asm volatile("" : "+v"(acc[ai][0][m][0]), "+v"(acc[ai][0][m][1]), "+v"(acc[ai][1][m][0]), "+v"(acc[ai][1][m][1]));
;                 float s = 0.f;
; #pragma unroll
;                 for (int bj = 0; bj < 2; ++bj)
; #pragma unroll
;                     for (int n = 0; n < 2; ++n) { const f32x4 x = acc[ai][bj][m][n]; s += (x[0] + x[1]) + (x[2] + x[3]); }
;                 s += __shfl_xor(s, 16); s += __shfl_xor(s, 32);
;                 const float mw = s * (1.0f / 64.0f); float q = 0.f;
; #pragma unroll
;                 for (int bj = 0; bj < 2; ++bj)
; #pragma unroll
;                     for (int n = 0; n < 2; ++n) { const f32x4 d = acc[ai][bj][m][n] - mw; q += (d[0] * d[0] + d[1] * d[1]) + (d[2] * d[2] + d[3] * d[3]); }
;                 q += __shfl_xor(q, 16); q += __shfl_xor(q, 32);
;                 if (fq == 0) P[(ai * HALF + wr * 64 + m * 16 + fr) * 4 + wc] = (f32x2){mw, q};
.LBB0_1122:
	s_or_b64 exec, exec, s[10:11]
	v_lshlrev_b64 v[134:135], 12, v[132:133]
	v_lshl_add_u64 v[134:135], v[166:167], 0, v[134:135]
	s_waitcnt lgkmcnt(0)
	v_add_co_u32_e32 v138, vcc, 0x80000, v134
	v_lshl_add_u64 v[142:143], v[134:135], 0, s[28:29]
	s_nop 0
	v_addc_co_u32_e32 v139, vcc, 0, v135, vcc
	s_waitcnt vmcnt(7)
	v_mov_b32_e32 v138, v240
	v_mov_b32_e32 v139, v241
	v_mov_b32_e32 v140, v242
	v_mov_b32_e32 v141, v243
	v_lshlrev_b32_e32 v144, 16, v138
	v_and_b32_e32 v145, 0xffff0000, v138
	v_lshlrev_b32_e32 v138, 16, v139
	v_and_b32_e32 v139, 0xffff0000, v139
	v_lshlrev_b32_e32 v146, 16, v140
	v_and_b32_e32 v147, 0xffff0000, v140
	v_lshlrev_b32_e32 v140, 16, v141
	v_and_b32_e32 v141, 0xffff0000, v141
	v_pk_fma_f32 v[130:131], v[138:139], s[92:93], v[130:131] op_sel_hi:[1,0,1]
	v_pk_fma_f32 v[126:127], v[140:141], s[92:93], v[126:127] op_sel_hi:[1,0,1]
	v_pk_fma_f32 v[128:129], v[144:145], s[92:93], v[128:129] op_sel_hi:[1,0,1]
	v_pk_fma_f32 v[124:125], v[146:147], s[92:93], v[124:125] op_sel_hi:[1,0,1]
	s_waitcnt vmcnt(6)
	v_mov_b32_e32 v138, v244
	v_mov_b32_e32 v139, v245
	v_mov_b32_e32 v140, v246
	v_mov_b32_e32 v141, v247
	v_lshlrev_b32_e32 v142, 16, v138
	v_and_b32_e32 v143, 0xffff0000, v138
	v_lshlrev_b32_e32 v138, 16, v139
	v_and_b32_e32 v139, 0xffff0000, v139
	v_lshlrev_b32_e32 v144, 16, v140
	v_and_b32_e32 v145, 0xffff0000, v140
	v_lshlrev_b32_e32 v140, 16, v141
	v_and_b32_e32 v141, 0xffff0000, v141
	v_pk_fma_f32 v[122:123], v[138:139], s[92:93], v[122:123] op_sel_hi:[1,0,1]
	v_pk_fma_f32 v[120:121], v[142:143], s[92:93], v[120:121] op_sel_hi:[1,0,1]
	v_pk_fma_f32 v[118:119], v[140:141], s[92:93], v[118:119] op_sel_hi:[1,0,1]
	v_pk_fma_f32 v[116:117], v[144:145], s[92:93], v[116:117] op_sel_hi:[1,0,1]
	s_nop 0
	s_nop 0
	v_mov_b32_e32 v138, v129
	v_mov_b32_e32 v139, v130
	v_mov_b32_e32 v140, v128
	v_mov_b32_e32 v141, v131
	v_pk_add_f32 v[138:139], v[138:139], v[140:141]
	v_mov_b32_e32 v140, v125
	v_mov_b32_e32 v141, v126
	v_mov_b32_e32 v142, v124
	v_mov_b32_e32 v143, v127
	v_pk_add_f32 v[140:141], v[140:141], v[142:143]
	v_add_f32_e32 v138, v138, v139
	v_pk_add_f32 v[140:141], v[140:141], v[140:141] op_sel_hi:[0,1]
	v_add_f32_e32 v139, 0, v138
	v_add_f32_e32 v143, v120, v121
	v_add_f32_e32 v145, v122, v123
	v_mov_b32_e32 v142, v116
	v_mov_b32_e32 v144, v117
	v_mov_b32_e32 v140, v118
	v_mov_b32_e32 v138, v119
	v_pk_add_f32 v[142:143], v[142:143], v[144:145]
	v_pk_add_f32 v[138:139], v[140:141], v[138:139]
	s_nop 0
	v_pk_add_f32 v[138:139], v[142:143], v[138:139]
	s_nop 0
	v_add_f32_e32 v138, v138, v139
	ds_bpermute_b32 v139, v136, v138
	s_waitcnt lgkmcnt(0)
	v_add_f32_e32 v138, v138, v139
	ds_bpermute_b32 v139, v137, v138
	s_waitcnt lgkmcnt(0)
	v_add_f32_e32 v138, v138, v139
	v_fmamk_f32 v140, v138, 0xbc800000, v131
	v_fmamk_f32 v142, v138, 0xbc800000, v129
	v_fmamk_f32 v139, v138, 0xbc800000, v130
	v_fmamk_f32 v141, v138, 0xbc800000, v128
	v_mul_f32_e32 v142, v142, v142
	v_mul_f32_e32 v140, v140, v140
	v_fmac_f32_e32 v142, v141, v141
	v_fmac_f32_e32 v140, v139, v139
	v_fmamk_f32 v141, v138, 0xbc800000, v127
	v_fmamk_f32 v143, v138, 0xbc800000, v125
	v_add_f32_e32 v139, v142, v140
	v_fmamk_f32 v140, v138, 0xbc800000, v126
	v_fmamk_f32 v142, v138, 0xbc800000, v124
	v_mul_f32_e32 v143, v143, v143
	v_mul_f32_e32 v141, v141, v141
	v_fmac_f32_e32 v143, v142, v142
	v_fmac_f32_e32 v141, v140, v140
	v_add_f32_e32 v140, v143, v141
	v_fmamk_f32 v141, v138, 0xbc800000, v123
	v_fmamk_f32 v143, v138, 0xbc800000, v121
	v_add_f32_e32 v139, v139, v140
	v_fmamk_f32 v140, v138, 0xbc800000, v122
	v_fmamk_f32 v142, v138, 0xbc800000, v120
	v_mul_f32_e32 v143, v143, v143
	v_mul_f32_e32 v141, v141, v141
	v_fmac_f32_e32 v143, v142, v142
	v_fmac_f32_e32 v141, v140, v140
	v_add_f32_e32 v140, v143, v141
	v_fmamk_f32 v141, v138, 0xbc800000, v119
	v_fmamk_f32 v143, v138, 0xbc800000, v117
	v_add_f32_e32 v139, v140, v139
	v_fmamk_f32 v140, v138, 0xbc800000, v118
	v_fmamk_f32 v142, v138, 0xbc800000, v116
	v_mul_f32_e32 v143, v143, v143
	v_mul_f32_e32 v141, v141, v141
	v_fmac_f32_e32 v143, v142, v142
	v_fmac_f32_e32 v141, v140, v140
	v_add_f32_e32 v140, v143, v141
	v_add_f32_e32 v139, v140, v139
	ds_bpermute_b32 v140, v136, v139
	s_waitcnt lgkmcnt(0)
	v_add_f32_e32 v139, v139, v140
	ds_bpermute_b32 v140, v137, v139
	s_and_saveexec_b64 s[10:11], s[4:5]
	s_cbranch_execz .LBB0_1124
	v_mul_f32_e32 v138, 0x3c800000, v138
	s_waitcnt lgkmcnt(0)
	v_add_f32_e32 v139, v139, v140
	ds_write_b64 v204, v[138:139]
; __device__ __forceinline__ float bflo(unsigned w) { return __uint_as_float(w << 16); }
; __device__ __forceinline__ float bfhi(unsigned w) { return __uint_as_float(w & 0xffff0000u); }
;     __device__ __forceinline__ void operator()(f32x4 (&acc)[2][2][4][2], const Unit& u, int wr, int wc, int fr, int fq, int wid, int lane) const {
;     ...
;             for (int m = 0; m < 4; ++m) { const size_t off = (size_t)(row0 + ai * HALF + m * 16) * D + col0;
; #pragma unroll
;                 for (int bj = 0; bj < 2; ++bj) { f32x4 x0, x1;
;                     if (X) { x0 = *(const f32x4*)(X + off + bj * HALF); x1 = *(const f32x4*)(X + off + bj * HALF + 4); }
;                     else { const u32x4 xw = *(const u32x4*)(XB + off + bj * HALF); x0 = (f32x4){bflo(xw.x), bfhi(xw.x), bflo(xw.y), bfhi(xw.y)}; x1 = (f32x4){bflo(xw.z), bfhi(xw.z), bflo(xw.w), bfhi(xw.w)}; }
;                     acc[ai][bj][m][0] = x0 * ALPHA + acc[ai][bj][m][0]; acc[ai][bj][m][1] = x1 * ALPHA + acc[ai][bj][m][1]; }
;                 asm volatile("" : "+v"(acc[ai][0][m][0]), "+v"(acc[ai][0][m][1]), "+v"(acc[ai][1][m][0]), "+v"(acc[ai][1][m][1]));
;                 float s = 0.f;
; #pragma unroll
;                 for (int bj = 0; bj < 2; ++bj)
; #pragma unroll
;                     for (int n = 0; n < 2; ++n) { const f32x4 x = acc[ai][bj][m][n]; s += (x[0] + x[1]) + (x[2] + x[3]); }
;                 s += __shfl_xor(s, 16); s += __shfl_xor(s, 32);
;                 const float mw = s * (1.0f / 64.0f); float q = 0.f;
; #pragma unroll
;                 for (int bj = 0; bj < 2; ++bj)
; #pragma unroll
;                     for (int n = 0; n < 2; ++n) { const f32x4 d = acc[ai][bj][m][n] - mw; q += (d[0] * d[0] + d[1] * d[1]) + (d[2] * d[2] + d[3] * d[3]); }
;                 q += __shfl_xor(q, 16); q += __shfl_xor(q, 32);
;                 if (fq == 0) P[(ai * HALF + wr * 64 + m * 16 + fr) * 4 + wc] = (f32x2){mw, q};
.LBB0_1124:
	s_or_b64 exec, exec, s[10:11]
	v_lshl_add_u64 v[142:143], v[134:135], 0, s[30:31]
	v_add_co_u32_e32 v134, vcc, 0x90000, v134
	s_nop 1
	v_addc_co_u32_e32 v135, vcc, 0, v135, vcc
	s_waitcnt lgkmcnt(0)
	s_waitcnt vmcnt(5)
	v_mov_b32_e32 v138, v208
	v_mov_b32_e32 v139, v209
	v_mov_b32_e32 v140, v210
	v_mov_b32_e32 v141, v211
	v_lshlrev_b32_e32 v134, 16, v138
	v_and_b32_e32 v135, 0xffff0000, v138
	v_lshlrev_b32_e32 v138, 16, v139
	v_and_b32_e32 v139, 0xffff0000, v139
	v_lshlrev_b32_e32 v144, 16, v140
	v_and_b32_e32 v145, 0xffff0000, v140
	v_lshlrev_b32_e32 v140, 16, v141
	v_and_b32_e32 v141, 0xffff0000, v141
	v_pk_fma_f32 v[106:107], v[138:139], s[92:93], v[106:107] op_sel_hi:[1,0,1]
	v_pk_fma_f32 v[102:103], v[140:141], s[92:93], v[102:103] op_sel_hi:[1,0,1]
	v_pk_fma_f32 v[104:105], v[134:135], s[92:93], v[104:105] op_sel_hi:[1,0,1]
	v_pk_fma_f32 v[100:101], v[144:145], s[92:93], v[100:101] op_sel_hi:[1,0,1]
	s_waitcnt vmcnt(4)
	v_mov_b32_e32 v138, v212
	v_mov_b32_e32 v139, v213
	v_mov_b32_e32 v140, v214
	v_mov_b32_e32 v141, v215
	v_lshlrev_b32_e32 v134, 16, v138
	v_and_b32_e32 v135, 0xffff0000, v138
	v_lshlrev_b32_e32 v138, 16, v139
	v_and_b32_e32 v139, 0xffff0000, v139
	v_lshlrev_b32_e32 v142, 16, v140
	v_and_b32_e32 v143, 0xffff0000, v140
	v_lshlrev_b32_e32 v140, 16, v141
	v_and_b32_e32 v141, 0xffff0000, v141
	v_pk_fma_f32 v[86:87], v[138:139], s[92:93], v[86:87] op_sel_hi:[1,0,1]
	v_pk_fma_f32 v[84:85], v[134:135], s[92:93], v[84:85] op_sel_hi:[1,0,1]
	v_pk_fma_f32 v[82:83], v[140:141], s[92:93], v[82:83] op_sel_hi:[1,0,1]
	v_pk_fma_f32 v[80:81], v[142:143], s[92:93], v[80:81] op_sel_hi:[1,0,1]
	s_nop 0
	s_nop 0
	v_mov_b32_e32 v134, v105
	v_mov_b32_e32 v135, v106
	v_mov_b32_e32 v138, v104
	v_mov_b32_e32 v139, v107
	v_pk_add_f32 v[134:135], v[134:135], v[138:139]
	v_mov_b32_e32 v138, v101
	v_mov_b32_e32 v139, v102
	v_mov_b32_e32 v140, v100
	v_mov_b32_e32 v141, v103
	v_pk_add_f32 v[138:139], v[138:139], v[140:141]
	v_add_f32_e32 v134, v134, v135
	v_pk_add_f32 v[138:139], v[138:139], v[138:139] op_sel_hi:[0,1]
	v_add_f32_e32 v135, 0, v134
	v_add_f32_e32 v141, v84, v85
	v_add_f32_e32 v143, v86, v87
	v_mov_b32_e32 v140, v80
	v_mov_b32_e32 v142, v81
	v_mov_b32_e32 v138, v82
	v_mov_b32_e32 v134, v83
	v_pk_add_f32 v[140:141], v[140:141], v[142:143]
	v_pk_add_f32 v[134:135], v[138:139], v[134:135]
	s_nop 0
	v_pk_add_f32 v[134:135], v[140:141], v[134:135]
	s_nop 0
	v_add_f32_e32 v134, v134, v135
	ds_bpermute_b32 v135, v136, v134
	s_waitcnt lgkmcnt(0)
	v_add_f32_e32 v134, v134, v135
	ds_bpermute_b32 v135, v137, v134
	s_waitcnt lgkmcnt(0)
	v_add_f32_e32 v134, v134, v135
	v_fmamk_f32 v138, v134, 0xbc800000, v107
	v_fmamk_f32 v140, v134, 0xbc800000, v105
	v_fmamk_f32 v135, v134, 0xbc800000, v106
	v_fmamk_f32 v139, v134, 0xbc800000, v104
	v_mul_f32_e32 v140, v140, v140
	v_mul_f32_e32 v138, v138, v138
	v_fmac_f32_e32 v140, v139, v139
	v_fmac_f32_e32 v138, v135, v135
	v_fmamk_f32 v139, v134, 0xbc800000, v103
	v_fmamk_f32 v141, v134, 0xbc800000, v101
	v_add_f32_e32 v135, v140, v138
	v_fmamk_f32 v138, v134, 0xbc800000, v102
	v_fmamk_f32 v140, v134, 0xbc800000, v100
	v_mul_f32_e32 v141, v141, v141
	v_mul_f32_e32 v139, v139, v139
	v_fmac_f32_e32 v141, v140, v140
	v_fmac_f32_e32 v139, v138, v138
	v_add_f32_e32 v138, v141, v139
	v_fmamk_f32 v139, v134, 0xbc800000, v87
	v_fmamk_f32 v141, v134, 0xbc800000, v85
	v_add_f32_e32 v135, v135, v138
	v_fmamk_f32 v138, v134, 0xbc800000, v86
	v_fmamk_f32 v140, v134, 0xbc800000, v84
	v_mul_f32_e32 v141, v141, v141
	v_mul_f32_e32 v139, v139, v139
	v_fmac_f32_e32 v141, v140, v140
	v_fmac_f32_e32 v139, v138, v138
	v_add_f32_e32 v138, v141, v139
	v_fmamk_f32 v139, v134, 0xbc800000, v83
	v_fmamk_f32 v141, v134, 0xbc800000, v81
	v_add_f32_e32 v135, v138, v135
	v_fmamk_f32 v138, v134, 0xbc800000, v82
	v_fmamk_f32 v140, v134, 0xbc800000, v80
	v_mul_f32_e32 v141, v141, v141
	v_mul_f32_e32 v139, v139, v139
	v_fmac_f32_e32 v141, v140, v140
	v_fmac_f32_e32 v139, v138, v138
	v_add_f32_e32 v138, v141, v139
	v_add_f32_e32 v135, v138, v135
	ds_bpermute_b32 v138, v136, v135
	s_waitcnt lgkmcnt(0)
	v_add_f32_e32 v135, v135, v138
	ds_bpermute_b32 v138, v137, v135
	s_and_saveexec_b64 s[10:11], s[4:5]
	s_cbranch_execz .LBB0_1126
	v_mul_f32_e32 v134, 0x3c800000, v134
	s_waitcnt lgkmcnt(0)
	v_add_f32_e32 v135, v135, v138
	ds_write_b64 v206, v[134:135] offset:4608
; __device__ __forceinline__ float bflo(unsigned w) { return __uint_as_float(w << 16); }
; __device__ __forceinline__ float bfhi(unsigned w) { return __uint_as_float(w & 0xffff0000u); }
;     __device__ __forceinline__ void operator()(f32x4 (&acc)[2][2][4][2], const Unit& u, int wr, int wc, int fr, int fq, int wid, int lane) const {
;     ...
;             for (int m = 0; m < 4; ++m) { const size_t off = (size_t)(row0 + ai * HALF + m * 16) * D + col0;
; #pragma unroll
;                 for (int bj = 0; bj < 2; ++bj) { f32x4 x0, x1;
;                     if (X) { x0 = *(const f32x4*)(X + off + bj * HALF); x1 = *(const f32x4*)(X + off + bj * HALF + 4); }
;                     else { const u32x4 xw = *(const u32x4*)(XB + off + bj * HALF); x0 = (f32x4){bflo(xw.x), bfhi(xw.x), bflo(xw.y), bfhi(xw.y)}; x1 = (f32x4){bflo(xw.z), bfhi(xw.z), bflo(xw.w), bfhi(xw.w)}; }
;                     acc[ai][bj][m][0] = x0 * ALPHA + acc[ai][bj][m][0]; acc[ai][bj][m][1] = x1 * ALPHA + acc[ai][bj][m][1]; }
;                 asm volatile("" : "+v"(acc[ai][0][m][0]), "+v"(acc[ai][0][m][1]), "+v"(acc[ai][1][m][0]), "+v"(acc[ai][1][m][1]));
;                 float s = 0.f;
; #pragma unroll
;                 for (int bj = 0; bj < 2; ++bj)
; #pragma unroll
;                     for (int n = 0; n < 2; ++n) { const f32x4 x = acc[ai][bj][m][n]; s += (x[0] + x[1]) + (x[2] + x[3]); }
;                 s += __shfl_xor(s, 16); s += __shfl_xor(s, 32);
;                 const float mw = s * (1.0f / 64.0f); float q = 0.f;
; #pragma unroll
;                 for (int bj = 0; bj < 2; ++bj)
; #pragma unroll
;                     for (int n = 0; n < 2; ++n) { const f32x4 d = acc[ai][bj][m][n] - mw; q += (d[0] * d[0] + d[1] * d[1]) + (d[2] * d[2] + d[3] * d[3]); }
;                 q += __shfl_xor(q, 16); q += __shfl_xor(q, 32);
;                 if (fq == 0) P[(ai * HALF + wr * 64 + m * 16 + fr) * 4 + wc] = (f32x2){mw, q};
.LBB0_1126:
	s_or_b64 exec, exec, s[10:11]
	v_lshlrev_b64 v[132:133], 12, v[132:133]
	v_lshl_add_u64 v[132:133], v[166:167], 0, v[132:133]
	s_waitcnt lgkmcnt(0)
	v_add_co_u32_e32 v138, vcc, 0xa0000, v132
	v_lshl_add_u64 v[134:135], v[132:133], 0, s[36:37]
	s_nop 0
	v_addc_co_u32_e32 v139, vcc, 0, v133, vcc
	s_waitcnt vmcnt(3)
	v_mov_b32_e32 v138, v216
	v_mov_b32_e32 v139, v217
	v_mov_b32_e32 v140, v218
	v_mov_b32_e32 v141, v219
	v_lshlrev_b32_e32 v142, 16, v138
	v_and_b32_e32 v143, 0xffff0000, v138
	v_lshlrev_b32_e32 v138, 16, v139
	v_and_b32_e32 v139, 0xffff0000, v139
	v_lshlrev_b32_e32 v144, 16, v140
	v_and_b32_e32 v145, 0xffff0000, v140
	v_lshlrev_b32_e32 v140, 16, v141
	v_and_b32_e32 v141, 0xffff0000, v141
	v_pk_fma_f32 v[74:75], v[138:139], s[92:93], v[74:75] op_sel_hi:[1,0,1]
	v_pk_fma_f32 v[70:71], v[140:141], s[92:93], v[70:71] op_sel_hi:[1,0,1]
	v_pk_fma_f32 v[72:73], v[142:143], s[92:93], v[72:73] op_sel_hi:[1,0,1]
	v_pk_fma_f32 v[68:69], v[144:145], s[92:93], v[68:69] op_sel_hi:[1,0,1]
	s_waitcnt vmcnt(2)
	v_mov_b32_e32 v138, v220
	v_mov_b32_e32 v139, v221
	v_mov_b32_e32 v140, v222
	v_mov_b32_e32 v141, v223
	v_lshlrev_b32_e32 v134, 16, v138
	v_and_b32_e32 v135, 0xffff0000, v138
	v_lshlrev_b32_e32 v138, 16, v139
	v_and_b32_e32 v139, 0xffff0000, v139
	v_lshlrev_b32_e32 v142, 16, v140
	v_and_b32_e32 v143, 0xffff0000, v140
	v_lshlrev_b32_e32 v140, 16, v141
	v_and_b32_e32 v141, 0xffff0000, v141
	v_pk_fma_f32 v[50:51], v[138:139], s[92:93], v[50:51] op_sel_hi:[1,0,1]
	v_pk_fma_f32 v[48:49], v[134:135], s[92:93], v[48:49] op_sel_hi:[1,0,1]
	v_pk_fma_f32 v[46:47], v[140:141], s[92:93], v[46:47] op_sel_hi:[1,0,1]
	v_pk_fma_f32 v[44:45], v[142:143], s[92:93], v[44:45] op_sel_hi:[1,0,1]
	s_nop 0
	s_nop 0
	v_mov_b32_e32 v134, v73
	v_mov_b32_e32 v135, v74
	v_mov_b32_e32 v138, v72
	v_mov_b32_e32 v139, v75
	v_pk_add_f32 v[134:135], v[134:135], v[138:139]
	v_mov_b32_e32 v138, v69
	v_mov_b32_e32 v139, v70
	v_mov_b32_e32 v140, v68
	v_mov_b32_e32 v141, v71
	v_pk_add_f32 v[138:139], v[138:139], v[140:141]
	v_add_f32_e32 v134, v134, v135
	v_pk_add_f32 v[138:139], v[138:139], v[138:139] op_sel_hi:[0,1]
	v_add_f32_e32 v135, 0, v134
	v_add_f32_e32 v141, v48, v49
	v_add_f32_e32 v143, v50, v51
	v_mov_b32_e32 v140, v44
	v_mov_b32_e32 v142, v45
	v_mov_b32_e32 v138, v46
	v_mov_b32_e32 v134, v47
	v_pk_add_f32 v[140:141], v[140:141], v[142:143]
	v_pk_add_f32 v[134:135], v[138:139], v[134:135]
	s_nop 0
	v_pk_add_f32 v[134:135], v[140:141], v[134:135]
	s_nop 0
	v_add_f32_e32 v134, v134, v135
	ds_bpermute_b32 v135, v136, v134
	s_waitcnt lgkmcnt(0)
	v_add_f32_e32 v134, v134, v135
	ds_bpermute_b32 v135, v137, v134
	s_waitcnt lgkmcnt(0)
	v_add_f32_e32 v134, v134, v135
	v_fmamk_f32 v138, v134, 0xbc800000, v75
	v_fmamk_f32 v140, v134, 0xbc800000, v73
	v_fmamk_f32 v135, v134, 0xbc800000, v74
	v_fmamk_f32 v139, v134, 0xbc800000, v72
	v_mul_f32_e32 v140, v140, v140
	v_mul_f32_e32 v138, v138, v138
	v_fmac_f32_e32 v140, v139, v139
	v_fmac_f32_e32 v138, v135, v135
	v_fmamk_f32 v139, v134, 0xbc800000, v71
	v_fmamk_f32 v141, v134, 0xbc800000, v69
	v_add_f32_e32 v135, v140, v138
	v_fmamk_f32 v138, v134, 0xbc800000, v70
	v_fmamk_f32 v140, v134, 0xbc800000, v68
	v_mul_f32_e32 v141, v141, v141
	v_mul_f32_e32 v139, v139, v139
	v_fmac_f32_e32 v141, v140, v140
	v_fmac_f32_e32 v139, v138, v138
	v_add_f32_e32 v138, v141, v139
	v_fmamk_f32 v139, v134, 0xbc800000, v51
	v_fmamk_f32 v141, v134, 0xbc800000, v49
	v_add_f32_e32 v135, v135, v138
	v_fmamk_f32 v138, v134, 0xbc800000, v50
	v_fmamk_f32 v140, v134, 0xbc800000, v48
	v_mul_f32_e32 v141, v141, v141
	v_mul_f32_e32 v139, v139, v139
	v_fmac_f32_e32 v141, v140, v140
	v_fmac_f32_e32 v139, v138, v138
	v_add_f32_e32 v138, v141, v139
	v_fmamk_f32 v139, v134, 0xbc800000, v47
	v_fmamk_f32 v141, v134, 0xbc800000, v45
	v_add_f32_e32 v135, v138, v135
	v_fmamk_f32 v138, v134, 0xbc800000, v46
	v_fmamk_f32 v140, v134, 0xbc800000, v44
	v_mul_f32_e32 v141, v141, v141
	v_mul_f32_e32 v139, v139, v139
	v_fmac_f32_e32 v141, v140, v140
	v_fmac_f32_e32 v139, v138, v138
	v_add_f32_e32 v138, v141, v139
	v_add_f32_e32 v135, v138, v135
	ds_bpermute_b32 v138, v136, v135
	s_waitcnt lgkmcnt(0)
	v_add_f32_e32 v135, v135, v138
	ds_bpermute_b32 v138, v137, v135
	s_and_saveexec_b64 s[10:11], s[4:5]
	s_cbranch_execz .LBB0_1128
	v_mul_f32_e32 v134, 0x3c800000, v134
	s_waitcnt lgkmcnt(0)
	v_add_f32_e32 v135, v135, v138
	ds_write_b64 v206, v[134:135] offset:5120
; __device__ __forceinline__ float bflo(unsigned w) { return __uint_as_float(w << 16); }
; __device__ __forceinline__ float bfhi(unsigned w) { return __uint_as_float(w & 0xffff0000u); }
;     __device__ __forceinline__ void operator()(f32x4 (&acc)[2][2][4][2], const Unit& u, int wr, int wc, int fr, int fq, int wid, int lane) const {
;     ...
;             for (int m = 0; m < 4; ++m) { const size_t off = (size_t)(row0 + ai * HALF + m * 16) * D + col0;
; #pragma unroll
;                 for (int bj = 0; bj < 2; ++bj) { f32x4 x0, x1;
;                     if (X) { x0 = *(const f32x4*)(X + off + bj * HALF); x1 = *(const f32x4*)(X + off + bj * HALF + 4); }
;                     else { const u32x4 xw = *(const u32x4*)(XB + off + bj * HALF); x0 = (f32x4){bflo(xw.x), bfhi(xw.x), bflo(xw.y), bfhi(xw.y)}; x1 = (f32x4){bflo(xw.z), bfhi(xw.z), bflo(xw.w), bfhi(xw.w)}; }
;                     acc[ai][bj][m][0] = x0 * ALPHA + acc[ai][bj][m][0]; acc[ai][bj][m][1] = x1 * ALPHA + acc[ai][bj][m][1]; }
;                 asm volatile("" : "+v"(acc[ai][0][m][0]), "+v"(acc[ai][0][m][1]), "+v"(acc[ai][1][m][0]), "+v"(acc[ai][1][m][1]));
;                 float s = 0.f;
; #pragma unroll
;                 for (int bj = 0; bj < 2; ++bj)
; #pragma unroll
;                     for (int n = 0; n < 2; ++n) { const f32x4 x = acc[ai][bj][m][n]; s += (x[0] + x[1]) + (x[2] + x[3]); }
;                 s += __shfl_xor(s, 16); s += __shfl_xor(s, 32);
;                 const float mw = s * (1.0f / 64.0f); float q = 0.f;
; #pragma unroll
;                 for (int bj = 0; bj < 2; ++bj)
; #pragma unroll
;                     for (int n = 0; n < 2; ++n) { const f32x4 d = acc[ai][bj][m][n] - mw; q += (d[0] * d[0] + d[1] * d[1]) + (d[2] * d[2] + d[3] * d[3]); }
;                 q += __shfl_xor(q, 16); q += __shfl_xor(q, 32);
;                 if (fq == 0) P[(ai * HALF + wr * 64 + m * 16 + fr) * 4 + wc] = (f32x2){mw, q};
.LBB0_1128:
	s_or_b64 exec, exec, s[10:11]
	s_mov_b64 s[10:11], 0xb0000
	s_waitcnt lgkmcnt(0)
	v_lshl_add_u64 v[138:139], v[132:133], 0, s[10:11]
	v_add_co_u32_e32 v132, vcc, 0xb0000, v132
	s_nop 1
	v_addc_co_u32_e32 v133, vcc, 0, v133, vcc
	s_waitcnt vmcnt(1)
	v_mov_b32_e32 v132, v224
	v_mov_b32_e32 v133, v225
	v_mov_b32_e32 v134, v226
	v_mov_b32_e32 v135, v227
	v_lshlrev_b32_e32 v140, 16, v132
	v_and_b32_e32 v141, 0xffff0000, v132
	v_lshlrev_b32_e32 v132, 16, v133
	v_and_b32_e32 v133, 0xffff0000, v133
	v_lshlrev_b32_e32 v142, 16, v134
	v_and_b32_e32 v143, 0xffff0000, v134
	v_lshlrev_b32_e32 v134, 16, v135
	v_and_b32_e32 v135, 0xffff0000, v135
	v_pk_fma_f32 v[34:35], v[132:133], s[92:93], v[34:35] op_sel_hi:[1,0,1]
	v_pk_fma_f32 v[30:31], v[134:135], s[92:93], v[30:31] op_sel_hi:[1,0,1]
	v_pk_fma_f32 v[32:33], v[140:141], s[92:93], v[32:33] op_sel_hi:[1,0,1]
	v_pk_fma_f32 v[28:29], v[142:143], s[92:93], v[28:29] op_sel_hi:[1,0,1]
	s_waitcnt vmcnt(0)
	v_mov_b32_e32 v132, v228
	v_mov_b32_e32 v133, v229
	v_mov_b32_e32 v134, v230
	v_mov_b32_e32 v135, v231
	v_lshlrev_b32_e32 v138, 16, v132
	v_and_b32_e32 v139, 0xffff0000, v132
	v_lshlrev_b32_e32 v132, 16, v133
	v_and_b32_e32 v133, 0xffff0000, v133
	v_lshlrev_b32_e32 v140, 16, v134
	v_and_b32_e32 v141, 0xffff0000, v134
	v_lshlrev_b32_e32 v134, 16, v135
	v_and_b32_e32 v135, 0xffff0000, v135
	v_pk_fma_f32 v[26:27], v[132:133], s[92:93], v[26:27] op_sel_hi:[1,0,1]
	v_pk_fma_f32 v[24:25], v[138:139], s[92:93], v[24:25] op_sel_hi:[1,0,1]
	v_pk_fma_f32 v[22:23], v[134:135], s[92:93], v[22:23] op_sel_hi:[1,0,1]
	v_pk_fma_f32 v[20:21], v[140:141], s[92:93], v[20:21] op_sel_hi:[1,0,1]
	s_nop 0
	s_nop 0
	v_mov_b32_e32 v132, v33
	v_mov_b32_e32 v133, v34
	v_mov_b32_e32 v134, v32
	v_mov_b32_e32 v135, v35
	v_pk_add_f32 v[132:133], v[132:133], v[134:135]
	v_mov_b32_e32 v134, v29
	v_mov_b32_e32 v135, v30
	v_mov_b32_e32 v138, v28
	v_mov_b32_e32 v139, v31
	v_pk_add_f32 v[134:135], v[134:135], v[138:139]
	v_add_f32_e32 v132, v132, v133
	v_pk_add_f32 v[134:135], v[134:135], v[134:135] op_sel_hi:[0,1]
	v_add_f32_e32 v133, 0, v132
	v_add_f32_e32 v139, v24, v25
	v_add_f32_e32 v141, v26, v27
	v_mov_b32_e32 v138, v20
	v_mov_b32_e32 v140, v21
	v_mov_b32_e32 v134, v22
	v_mov_b32_e32 v132, v23
	v_pk_add_f32 v[138:139], v[138:139], v[140:141]
	v_pk_add_f32 v[132:133], v[134:135], v[132:133]
	s_nop 0
	v_pk_add_f32 v[132:133], v[138:139], v[132:133]
	s_nop 0
	v_add_f32_e32 v132, v132, v133
	ds_bpermute_b32 v133, v136, v132
	s_waitcnt lgkmcnt(0)
	v_add_f32_e32 v132, v132, v133
	ds_bpermute_b32 v133, v137, v132
	s_waitcnt lgkmcnt(0)
	v_add_f32_e32 v132, v132, v133
	v_fmamk_f32 v134, v132, 0xbc800000, v35
	v_fmamk_f32 v138, v132, 0xbc800000, v33
	v_fmamk_f32 v133, v132, 0xbc800000, v34
	v_fmamk_f32 v135, v132, 0xbc800000, v32
	v_mul_f32_e32 v138, v138, v138
	v_mul_f32_e32 v134, v134, v134
	v_fmac_f32_e32 v138, v135, v135
	v_fmac_f32_e32 v134, v133, v133
	v_fmamk_f32 v135, v132, 0xbc800000, v31
	v_fmamk_f32 v139, v132, 0xbc800000, v29
	v_add_f32_e32 v133, v138, v134
	v_fmamk_f32 v134, v132, 0xbc800000, v30
	v_fmamk_f32 v138, v132, 0xbc800000, v28
	v_mul_f32_e32 v139, v139, v139
	v_mul_f32_e32 v135, v135, v135
	v_fmac_f32_e32 v139, v138, v138
	v_fmac_f32_e32 v135, v134, v134
	v_add_f32_e32 v134, v139, v135
	v_fmamk_f32 v135, v132, 0xbc800000, v27
	v_fmamk_f32 v139, v132, 0xbc800000, v25
	v_add_f32_e32 v133, v133, v134
	v_fmamk_f32 v134, v132, 0xbc800000, v26
	v_fmamk_f32 v138, v132, 0xbc800000, v24
	v_mul_f32_e32 v139, v139, v139
	v_mul_f32_e32 v135, v135, v135
	v_fmac_f32_e32 v139, v138, v138
	v_fmac_f32_e32 v135, v134, v134
	v_add_f32_e32 v134, v139, v135
	v_fmamk_f32 v135, v132, 0xbc800000, v23
	v_fmamk_f32 v139, v132, 0xbc800000, v21
	v_add_f32_e32 v133, v134, v133
	v_fmamk_f32 v134, v132, 0xbc800000, v22
	v_fmamk_f32 v138, v132, 0xbc800000, v20
	v_mul_f32_e32 v139, v139, v139
	v_mul_f32_e32 v135, v135, v135
	v_fmac_f32_e32 v139, v138, v138
	v_fmac_f32_e32 v135, v134, v134
	v_add_f32_e32 v134, v139, v135
	v_add_f32_e32 v133, v134, v133
	ds_bpermute_b32 v134, v136, v133
	s_waitcnt lgkmcnt(0)
	v_add_f32_e32 v133, v133, v134
	ds_bpermute_b32 v134, v137, v133
	s_and_saveexec_b64 s[10:11], s[4:5]
	s_cbranch_execz .LBB0_1130
	v_mul_f32_e32 v132, 0x3c800000, v132
	s_waitcnt lgkmcnt(0)
	v_add_f32_e32 v133, v133, v134
	ds_write_b64 v206, v[132:133] offset:5632

;     __device__ __forceinline__ void operator()(f32x4 (&acc)[2][2][4][2], const Unit& u, int wr, int wc, int fr, int fq, int wid, int lane) const {
;     ...
;         if (lane < 32) {
;             float mt[8], m2[8]; float ms = 0.f;
; #pragma unroll
;             for (int t = 0; t < 8; ++t) { const unsigned long long w = __hip_atomic_load(slot + t, __ATOMIC_RELAXED, __HIP_MEMORY_SCOPE_AGENT); mt[t] = __uint_as_float((unsigned)w); m2[t] = __uint_as_float((unsigned)(w >> 32)); ms += mt[t]; }
;             const float mean = ms * 0.125f; float q = 0.f;
; #pragma unroll
;             for (int t = 0; t < 8; ++t) { const float dm = mt[t] - mean; q += m2[t] + 256.0f * dm * dm; }
;             S[row] = (f32x2){mean, 1.0f / sqrtf(q * (1.0f / 2048.0f) + LN_EPS)};
.LBB0_1141:
	s_waitcnt vmcnt(0) lgkmcnt(0)
	s_barrier
	s_and_saveexec_b64 s[62:63], s[6:7]
	s_cbranch_execz .LBB0_1143
	s_waitcnt lgkmcnt(0)
	global_load_dwordx2 v[134:135], v[132:133], off sc1
	global_load_dwordx2 v[136:137], v[132:133], off offset:8 sc1
	global_load_dwordx2 v[138:139], v[132:133], off offset:16 sc1
	global_load_dwordx2 v[140:141], v[132:133], off offset:24 sc1
	global_load_dwordx2 v[142:143], v[132:133], off offset:32 sc1
	global_load_dwordx2 v[144:145], v[132:133], off offset:40 sc1
	global_load_dwordx2 v[146:147], v[132:133], off offset:48 sc1
	global_load_dwordx2 v[160:161], v[132:133], off offset:56 sc1
	s_waitcnt vmcnt(7)
	v_add_f32_e32 v162, 0, v134
	s_waitcnt vmcnt(6)
	v_add_f32_e32 v162, v162, v136
	s_waitcnt vmcnt(5)
	v_add_f32_e32 v162, v162, v138
	s_waitcnt vmcnt(4)
	v_add_f32_e32 v162, v162, v140
	s_waitcnt vmcnt(3)
	v_add_f32_e32 v162, v162, v142
	s_waitcnt vmcnt(2)
	v_add_f32_e32 v162, v162, v144
	s_waitcnt vmcnt(1)
	v_add_f32_e32 v162, v162, v146
	s_waitcnt vmcnt(0)
	v_add_f32_e32 v133, v162, v160
	v_fmamk_f32 v134, v133, 0xbe000000, v134
	v_mul_f32_e32 v162, 0x43800000, v134
	v_fmac_f32_e32 v135, v134, v162
	v_add_f32_e32 v134, 0, v135
	v_fmamk_f32 v135, v133, 0xbe000000, v136
	v_mul_f32_e32 v136, 0x43800000, v135
	v_fmac_f32_e32 v137, v135, v136
	v_fmamk_f32 v135, v133, 0xbe000000, v138
	v_mul_f32_e32 v136, 0x43800000, v135
	v_fmac_f32_e32 v139, v135, v136
	v_fmamk_f32 v135, v133, 0xbe000000, v140
	v_mul_f32_e32 v136, 0x43800000, v135
	v_fmac_f32_e32 v141, v135, v136
	v_fmamk_f32 v135, v133, 0xbe000000, v142
	v_mul_f32_e32 v136, 0x43800000, v135
	v_add_f32_e32 v134, v137, v134
	v_fmac_f32_e32 v143, v135, v136
	v_fmamk_f32 v135, v133, 0xbe000000, v144
	v_add_f32_e32 v134, v139, v134
	v_mul_f32_e32 v136, 0x43800000, v135
	v_add_f32_e32 v134, v141, v134
	v_fmac_f32_e32 v145, v135, v136
	v_fmamk_f32 v135, v133, 0xbe000000, v146
	v_mul_f32_e32 v132, 0x3e000000, v133
	v_add_f32_e32 v134, v143, v134
	v_mul_f32_e32 v136, 0x43800000, v135
	v_fmamk_f32 v133, v133, 0xbe000000, v160
	v_add_f32_e32 v134, v145, v134
	v_fmac_f32_e32 v147, v135, v136
	v_mul_f32_e32 v135, 0x43800000, v133
	v_add_f32_e32 v134, v147, v134
	v_fmac_f32_e32 v161, v133, v135
	v_add_f32_e32 v133, v161, v134
	v_fmamk_f32 v133, v133, 0x3a000000, v200
	v_cmp_gt_f32_e32 vcc, s26, v133
	v_mul_f32_e32 v134, 0x4f800000, v133
	s_nop 0
	v_cndmask_b32_e32 v133, v133, v134, vcc
	v_sqrt_f32_e32 v134, v133
	s_nop 0
	v_add_u32_e32 v135, -1, v134
	v_fma_f32 v136, -v135, v134, v133
	v_cmp_ge_f32_e64 s[10:11], 0, v136
	v_add_u32_e32 v136, 1, v134
	s_nop 0
	v_cndmask_b32_e64 v135, v134, v135, s[10:11]
	v_fma_f32 v134, -v136, v134, v133
	v_cmp_lt_f32_e64 s[10:11], 0, v134
	s_nop 1
	v_cndmask_b32_e64 v134, v135, v136, s[10:11]
	v_mul_f32_e32 v135, 0x37800000, v134
	v_cndmask_b32_e32 v134, v134, v135, vcc
	v_cmp_class_f32_e32 vcc, v133, v201
	s_nop 1
	v_cndmask_b32_e32 v133, v134, v133, vcc
	v_div_scale_f32 v134, s[10:11], v133, v133, 1.0
	v_rcp_f32_e32 v135, v134
	s_nop 0
	v_fma_f32 v136, -v134, v135, 1.0
	v_fmac_f32_e32 v135, v136, v135
	v_div_scale_f32 v136, vcc, 1.0, v133, 1.0
	v_mul_f32_e32 v137, v136, v135
	v_fma_f32 v138, -v134, v137, v136
	v_fmac_f32_e32 v137, v138, v135
	v_fma_f32 v134, -v134, v137, v136
	v_div_fmas_f32 v134, v134, v135, v137
	v_div_fixup_f32 v133, v134, v133, 1.0
	v_lshl_add_u32 v134, v190, 3, s51
	ds_write_b64 v134, v[132:133]
